# v34 plus hgrn readout wave-sum via DPP/permlane16 and two-deep S0 gather
# speedup vs baseline: 1.0026x; 1.0026x over previous
; __device__ __forceinline__ float bf2f(unsigned v) { return __uint_as_float(v << 16); }
; __device__ __forceinline__ float sigmoidf_(float x) { return __builtin_amdgcn_rcpf(1.0f + __builtin_amdgcn_exp2f(-1.4426950408889634f * x)); }
; __device__ __forceinline__ float lb_val(const float* logits, int l, int dir, int ch) {
;     float v[4]; float mx = -3.0e38f;
; #pragma unroll
;     for (int j = 0; j < 4; ++j) { v[j] = logits[(j * 2 + dir) * 256 + ch]; mx = fmaxf(mx, v[j]); }
;     float s = 0.f, c = 0.f;
; #pragma unroll
;     for (int j = 0; j < 4; ++j) { v[j] = expf(v[j] - mx); s += v[j]; if (j >= 1 && j <= l) c += v[j]; }
;     return c / s;
; }
; __device__ __forceinline__ void hgrn_out_phase(const Ctx& F, const Args& a, int l) {
;     ...
;             const int c = dir == 0 ? (jc < 256 ? 4 + jc : jc - 256) : (jc < 256 ? 4 + 255 - jc : 3 - (jc - 256));
;             const float lb = lb_val(in_ptr(14), l, dir, head * 64 + lane);
;             const int colf = (dir ? C_BFB : C_BFF) + head * 64 + lane, colq = C_BQ + head * 64 + lane;
;             float fv[64]; float ref = 0.f;
; #pragma unroll
;             for (int t = 0; t < 64; ++t) {
;                 const float pre = bf2f(PB[(size_t)(rb + (dir ? 63 - t : t)) * INW + colf]);
;                 const float f = lb + (1.0f - lb) * sigmoidf_(pre);
;                 fv[t] = f;
;                 if (t < 32) ref += __logf(f);
;             }
.LBB0_313:
	s_ashr_i32 s65, s84, 2
	s_lshl_b32 s45, s84, 4
	s_cmpk_lt_i32 s65, 0x100
	s_movk_i32 s2, 0x70
	s_cselect_b32 s82, 4, 0xffffff00
	s_sub_i32 s44, 0x103, s65
	s_ashr_i32 s5, s2, 31
	v_readlane_b32 s0, v251, 1
	v_readlane_b32 s1, v251, 2
	s_add_u32 s4, s0, s2
	s_addc_u32 s5, s1, s5
	s_load_dwordx2 s[4:5], s[4:5], 0x0
	v_readlane_b32 s2, v253, 35
	s_mov_b32 s8, 0x3e000000
	s_add_i32 s82, s82, s65
	s_waitcnt lgkmcnt(0)
	v_lshl_add_u64 v[2:3], v[100:101], 2, s[4:5]
	global_load_dword v4, v[2:3], off
	global_load_dword v5, v[2:3], off offset:2048
	v_lshl_add_u64 v[2:3], v[102:103], 2, s[4:5]
	global_load_dword v7, v[2:3], off
	v_lshl_add_u64 v[2:3], v[104:105], 2, s[4:5]
	global_load_dword v2, v[2:3], off
	s_waitcnt vmcnt(2)
	v_max3_f32 v6, v4, s93, v5
	s_waitcnt vmcnt(0)
	v_max3_f32 v3, v6, v7, v2
	v_sub_f32_e32 v4, v4, v3
	v_mul_f32_e32 v6, 0x3fb8aa3b, v4
	v_fma_f32 v8, v4, s36, -v6
	v_rndne_f32_e32 v9, v6
	v_fmac_f32_e32 v8, 0x32a5705f, v4
	v_sub_f32_e32 v6, v6, v9
	v_add_f32_e32 v6, v6, v8
	v_exp_f32_e32 v6, v6
	v_cvt_i32_f32_e32 v8, v9
	v_cmp_ngt_f32_e32 vcc, s94, v4
	v_sub_f32_e32 v5, v5, v3
	v_sub_f32_e32 v2, v2, v3
	v_ldexp_f32 v6, v6, v8
	v_cndmask_b32_e32 v6, 0, v6, vcc
	v_cmp_nlt_f32_e32 vcc, s95, v4
	s_nop 1
	v_cndmask_b32_e32 v4, v204, v6, vcc
	v_mul_f32_e32 v6, 0x3fb8aa3b, v5
	v_fma_f32 v8, v5, s36, -v6
	v_rndne_f32_e32 v9, v6
	v_fmac_f32_e32 v8, 0x32a5705f, v5
	v_sub_f32_e32 v6, v6, v9
	v_add_f32_e32 v6, v6, v8
	v_exp_f32_e32 v6, v6
	v_cvt_i32_f32_e32 v8, v9
	v_cmp_ngt_f32_e32 vcc, s94, v5
	v_ldexp_f32 v6, v6, v8
	s_nop 0
	v_cndmask_b32_e32 v6, 0, v6, vcc
	v_cmp_nlt_f32_e32 vcc, s95, v5
	s_nop 1
	v_cndmask_b32_e32 v5, v204, v6, vcc
	v_sub_f32_e32 v6, v7, v3
	v_mul_f32_e32 v7, 0x3fb8aa3b, v6
	v_fma_f32 v8, v6, s36, -v7
	v_rndne_f32_e32 v9, v7
	v_fmac_f32_e32 v8, 0x32a5705f, v6
	v_sub_f32_e32 v7, v7, v9
	v_add_f32_e32 v7, v7, v8
	v_exp_f32_e32 v7, v7
	v_cvt_i32_f32_e32 v8, v9
	v_cmp_ngt_f32_e32 vcc, s94, v6
	v_add_f32_e32 v4, v4, v5
	v_cndmask_b32_e64 v5, 0, v5, s[66:67]
	v_ldexp_f32 v7, v7, v8
	v_cndmask_b32_e32 v7, 0, v7, vcc
	v_cmp_nlt_f32_e32 vcc, s95, v6
	v_mul_f32_e32 v3, 0x3fb8aa3b, v2
	s_or_b32 s66, s45, s2
	v_cndmask_b32_e32 v6, v204, v7, vcc
	v_add_f32_e32 v4, v6, v4
	v_add_f32_e32 v6, v6, v5
	v_cndmask_b32_e64 v5, v6, v5, s[46:47]
	v_fma_f32 v6, v2, s36, -v3
	v_rndne_f32_e32 v7, v3
	v_fmac_f32_e32 v6, 0x32a5705f, v2
	v_sub_f32_e32 v3, v3, v7
	v_add_f32_e32 v3, v3, v6
	v_exp_f32_e32 v3, v3
	v_cvt_i32_f32_e32 v6, v7
	v_cmp_ngt_f32_e32 vcc, s94, v2
	v_readlane_b32 s2, v253, 37
	s_or_b32 s67, s45, s2
	v_ldexp_f32 v3, v3, v6
	v_cndmask_b32_e32 v3, 0, v3, vcc
	v_cmp_nlt_f32_e32 vcc, s95, v2
	v_readlane_b32 s2, v253, 39
	s_or_b32 s68, s45, s2
	v_cndmask_b32_e32 v2, v204, v3, vcc
	v_add_f32_e32 v3, v2, v4
	v_add_f32_e32 v2, v2, v5
	v_cndmask_b32_e64 v2, v2, v5, s[52:53]
	v_div_scale_f32 v4, s[4:5], v3, v3, v2
	v_rcp_f32_e32 v5, v4
	v_readlane_b32 s2, v253, 41
	s_or_b32 s69, s45, s2
	v_readlane_b32 s2, v253, 43
	v_fma_f32 v6, -v4, v5, 1.0
	v_fmac_f32_e32 v5, v6, v5
	v_div_scale_f32 v6, vcc, v2, v3, v2
	v_mul_f32_e32 v7, v6, v5
	v_fma_f32 v8, -v4, v7, v6
	v_fmac_f32_e32 v7, v8, v5
	v_fma_f32 v4, -v4, v7, v6
	v_div_fmas_f32 v4, v4, v5, v7
	v_readlane_b32 s100, v253, 35
	s_or_b32 s100, s45, s100
	s_nop 0
	v_mad_i64_i32 v[248:249], s[4:5], s100, v205, v[106:107]
	global_load_ushort v222, v[248:249], off
	v_readlane_b32 s100, v253, 37
	s_or_b32 s100, s45, s100
	s_nop 0
	v_mad_i64_i32 v[248:249], s[4:5], s100, v205, v[106:107]
	global_load_ushort v223, v[248:249], off
	v_readlane_b32 s100, v253, 39
	s_or_b32 s100, s45, s100
	s_nop 0
	v_mad_i64_i32 v[248:249], s[4:5], s100, v205, v[106:107]
	global_load_ushort v224, v[248:249], off
	v_readlane_b32 s100, v253, 41
	s_or_b32 s100, s45, s100
	s_nop 0
	v_mad_i64_i32 v[248:249], s[4:5], s100, v205, v[106:107]
	global_load_ushort v225, v[248:249], off
	v_readlane_b32 s100, v253, 43
	s_or_b32 s100, s45, s100
	s_nop 0
	v_mad_i64_i32 v[248:249], s[4:5], s100, v205, v[106:107]
	global_load_ushort v226, v[248:249], off
	v_readlane_b32 s100, v253, 45
	s_or_b32 s100, s45, s100
	s_nop 0
	v_mad_i64_i32 v[248:249], s[4:5], s100, v205, v[106:107]
	global_load_ushort v227, v[248:249], off
	v_readlane_b32 s100, v253, 47
	s_or_b32 s100, s45, s100
	s_nop 0
	v_mad_i64_i32 v[248:249], s[4:5], s100, v205, v[106:107]
	global_load_ushort v228, v[248:249], off
	v_readlane_b32 s100, v253, 49
	s_or_b32 s100, s45, s100
	s_nop 0
	v_mad_i64_i32 v[248:249], s[4:5], s100, v205, v[106:107]
	global_load_ushort v229, v[248:249], off
	v_readlane_b32 s100, v253, 51
	s_or_b32 s100, s45, s100
	s_nop 0
	v_mad_i64_i32 v[248:249], s[4:5], s100, v205, v[106:107]
	global_load_ushort v230, v[248:249], off
	v_readlane_b32 s100, v253, 53
	s_or_b32 s100, s45, s100
	s_nop 0
	v_mad_i64_i32 v[248:249], s[4:5], s100, v205, v[106:107]
	global_load_ushort v231, v[248:249], off
	v_readlane_b32 s100, v253, 55
	s_or_b32 s100, s45, s100
	s_nop 0
	v_mad_i64_i32 v[248:249], s[4:5], s100, v205, v[106:107]
	global_load_ushort v232, v[248:249], off
	v_readlane_b32 s100, v253, 33
	s_or_b32 s100, s45, s100
	s_nop 0
	v_mad_i64_i32 v[248:249], s[4:5], s100, v205, v[106:107]
	global_load_ushort v233, v[248:249], off
	v_readlane_b32 s100, v253, 57
	s_or_b32 s100, s45, s100
	s_nop 0
	v_mad_i64_i32 v[248:249], s[4:5], s100, v205, v[106:107]
	global_load_ushort v234, v[248:249], off
	v_readlane_b32 s100, v253, 28
	s_or_b32 s100, s45, s100
	s_nop 0
	v_mad_i64_i32 v[248:249], s[4:5], s100, v205, v[106:107]
	global_load_ushort v235, v[248:249], off
	v_readlane_b32 s100, v253, 31
	s_or_b32 s100, s45, s100
	s_nop 0
	v_mad_i64_i32 v[248:249], s[4:5], s100, v205, v[106:107]
; __device__ __forceinline__ float bf2f(unsigned v) { return __uint_as_float(v << 16); }
; __device__ __forceinline__ float sigmoidf_(float x) { return __builtin_amdgcn_rcpf(1.0f + __builtin_amdgcn_exp2f(-1.4426950408889634f * x)); }
; __device__ __forceinline__ void hgrn_out_phase(const Ctx& F, const Args& a, int l) {
;     ...
;             float fv[64]; float ref = 0.f;
; #pragma unroll
;             for (int t = 0; t < 64; ++t) {
;                 const float pre = bf2f(PB[(size_t)(rb + (dir ? 63 - t : t)) * INW + colf]);
;                 const float f = lb + (1.0f - lb) * sigmoidf_(pre);
;                 fv[t] = f;
;                 if (t < 32) ref += __logf(f);
;             }
	global_load_ushort v236, v[248:249], off
	v_readlane_b32 s100, v253, 59
	s_or_b32 s100, s45, s100
	s_nop 0
	v_mad_i64_i32 v[248:249], s[4:5], s100, v205, v[106:107]
	global_load_ushort v237, v[248:249], off
	v_readlane_b32 s100, v253, 61
	s_or_b32 s100, s45, s100
	s_nop 0
	v_mad_i64_i32 v[248:249], s[4:5], s100, v205, v[106:107]
	global_load_ushort v238, v[248:249], off
	v_readlane_b32 s100, v253, 62
	s_or_b32 s100, s45, s100
	s_nop 0
	v_mad_i64_i32 v[248:249], s[4:5], s100, v205, v[106:107]
	global_load_ushort v239, v[248:249], off
	v_readlane_b32 s100, v253, 63
	s_or_b32 s100, s45, s100
	s_nop 0
	v_mad_i64_i32 v[248:249], s[4:5], s100, v205, v[106:107]
	global_load_ushort v240, v[248:249], off
	v_readlane_b32 s100, v254, 0
	s_or_b32 s100, s45, s100
	s_nop 0
	v_mad_i64_i32 v[248:249], s[4:5], s100, v205, v[106:107]
	global_load_ushort v241, v[248:249], off
	v_readlane_b32 s100, v254, 1
	s_or_b32 s100, s45, s100
	s_nop 0
	v_mad_i64_i32 v[248:249], s[4:5], s100, v205, v[106:107]
	global_load_ushort v242, v[248:249], off
	v_readlane_b32 s100, v254, 2
	s_or_b32 s100, s45, s100
	s_nop 0
	v_mad_i64_i32 v[248:249], s[4:5], s100, v205, v[106:107]
	global_load_ushort v243, v[248:249], off
	v_readlane_b32 s100, v254, 3
	s_or_b32 s100, s45, s100
	s_nop 0
	v_mad_i64_i32 v[248:249], s[4:5], s100, v205, v[106:107]
	global_load_ushort v244, v[248:249], off
	v_readlane_b32 s100, v254, 4
	s_or_b32 s100, s45, s100
	s_nop 0
	v_mad_i64_i32 v[248:249], s[4:5], s100, v205, v[106:107]
	global_load_ushort v245, v[248:249], off
	v_readlane_b32 s100, v254, 5
	s_or_b32 s100, s45, s100
	s_nop 0
	v_mad_i64_i32 v[248:249], s[4:5], s100, v205, v[106:107]
	global_load_ushort v246, v[248:249], off
	v_div_fixup_f32 v4, v4, v3, v2
	v_readlane_b32 s100, v254, 6
	s_or_b32 s100, s45, s100
	s_nop 0
	v_mad_i64_i32 v[248:249], s[4:5], s100, v205, v[106:107]
	global_load_ushort v247, v[248:249], off
	v_sub_f32_e32 v2, 1.0, v4
	s_or_b32 s70, s45, s2
	v_readlane_b32 s2, v253, 45
	s_or_b32 s71, s45, s2
	v_readlane_b32 s2, v253, 47
	s_or_b32 s72, s45, s2
	v_readlane_b32 s2, v253, 49
	s_or_b32 s73, s45, s2
	v_readlane_b32 s2, v253, 51
	s_or_b32 s74, s45, s2
	v_readlane_b32 s2, v253, 53
	s_or_b32 s75, s45, s2
	v_readlane_b32 s2, v253, 55
	s_or_b32 s76, s45, s2
	v_readlane_b32 s2, v253, 33
	s_or_b32 s77, s45, s2
	v_readlane_b32 s2, v253, 57
	s_or_b32 s78, s45, s2
	v_readlane_b32 s2, v253, 28
	s_or_b32 s79, s45, s2
	v_readlane_b32 s2, v253, 31
	s_or_b32 s46, s45, s2
	v_readlane_b32 s2, v253, 59
	s_or_b32 s47, s45, s2
	v_readlane_b32 s2, v253, 61
	s_or_b32 s56, s45, s2
	v_readlane_b32 s2, v253, 62
	s_or_b32 s97, s45, s2
	v_readlane_b32 s2, v253, 63
	s_or_b32 s33, s45, s2
	v_readlane_b32 s2, v254, 0
	s_or_b32 s28, s45, s2
	v_readlane_b32 s2, v254, 1
	s_or_b32 s29, s45, s2
	v_readlane_b32 s2, v254, 2
	s_or_b32 s36, s45, s2
	v_readlane_b32 s2, v254, 3
	s_or_b32 s37, s45, s2
	v_readlane_b32 s2, v254, 4
	s_or_b32 s26, s45, s2
	v_readlane_b32 s2, v254, 5
	s_or_b32 s27, s45, s2
	v_readlane_b32 s2, v254, 6
	s_or_b32 s24, s45, s2
	v_readlane_b32 s2, v254, 7
	s_or_b32 s25, s45, s2
	v_readlane_b32 s2, v254, 8
	s_or_b32 s57, s45, s2
	v_readlane_b32 s2, v254, 9
	s_or_b32 s2, s45, s2
	s_waitcnt vmcnt(25)
	v_lshlrev_b32_e32 v3, 16, v222
	v_mul_f32_e32 v3, 0xbfb8aa3b, v3
	v_exp_f32_e32 v3, v3
	s_nop 0
	v_add_f32_e32 v3, 1.0, v3
	v_rcp_f32_e32 v3, v3
	s_nop 0
	v_fma_f32 v3, v3, v2, v4
	v_cmp_gt_f32_e32 vcc, s35, v3
	s_nop 1
	v_cndmask_b32_e64 v5, 0, 32, vcc
	v_ldexp_f32 v5, v3, v5
	v_log_f32_e32 v5, v5
	s_nop 0
	v_mul_f32_e32 v6, 0x3f317217, v5
	v_fma_f32 v6, v5, s31, -v6
	v_fmac_f32_e32 v6, 0x3377d1cf, v5
	v_fmac_f32_e32 v6, 0x3f317217, v5
	v_cmp_lt_f32_e64 s[4:5], |v5|, s34
	s_nop 1
	v_cndmask_b32_e64 v5, v5, v6, s[4:5]
	v_cndmask_b32_e32 v6, 0, v206, vcc
	v_sub_f32_e32 v5, v5, v6
	v_add_f32_e32 v34, 0, v5
	v_readlane_b32 s100, v254, 7
	s_or_b32 s100, s45, s100
	s_nop 0
	v_mad_i64_i32 v[248:249], s[4:5], s100, v205, v[106:107]
	global_load_ushort v222, v[248:249], off
	s_waitcnt vmcnt(25)
	v_lshlrev_b32_e32 v5, 16, v223
	v_mul_f32_e32 v5, 0xbfb8aa3b, v5
	v_exp_f32_e32 v5, v5
	s_nop 0
	v_add_f32_e32 v5, 1.0, v5
	v_rcp_f32_e32 v5, v5
	s_nop 0
	v_fma_f32 v35, v5, v2, v4
	v_cmp_gt_f32_e32 vcc, s35, v35
	s_nop 1
	v_cndmask_b32_e64 v5, 0, 32, vcc
	v_ldexp_f32 v5, v35, v5
	v_log_f32_e32 v5, v5
	s_nop 0
	v_mul_f32_e32 v6, 0x3f317217, v5
	v_fma_f32 v6, v5, s31, -v6
	v_fmac_f32_e32 v6, 0x3377d1cf, v5
	v_fmac_f32_e32 v6, 0x3f317217, v5
	v_cmp_lt_f32_e64 s[4:5], |v5|, s34
	s_nop 1
	v_cndmask_b32_e64 v5, v5, v6, s[4:5]
	v_cndmask_b32_e32 v6, 0, v206, vcc
	v_sub_f32_e32 v5, v5, v6
	v_add_f32_e32 v36, v5, v34
	v_readlane_b32 s100, v254, 8
	s_or_b32 s100, s45, s100
	s_nop 0
	v_mad_i64_i32 v[248:249], s[4:5], s100, v205, v[106:107]
	global_load_ushort v223, v[248:249], off
	s_waitcnt vmcnt(25)
	v_lshlrev_b32_e32 v5, 16, v224
	v_mul_f32_e32 v5, 0xbfb8aa3b, v5
	v_exp_f32_e32 v5, v5
	s_nop 0
	v_add_f32_e32 v5, 1.0, v5
	v_rcp_f32_e32 v5, v5
	s_nop 0
	v_fma_f32 v37, v2, v5, v4
	v_cmp_gt_f32_e32 vcc, s35, v37
	s_nop 1
	v_cndmask_b32_e64 v5, 0, 32, vcc
	v_ldexp_f32 v5, v37, v5
	v_log_f32_e32 v5, v5
	s_nop 0
	v_mul_f32_e32 v6, 0x3f317217, v5
	v_fma_f32 v6, v5, s31, -v6
	v_fmac_f32_e32 v6, 0x3377d1cf, v5
	v_fmac_f32_e32 v6, 0x3f317217, v5
	v_cmp_lt_f32_e64 s[4:5], |v5|, s34
	s_nop 1
	v_cndmask_b32_e64 v5, v5, v6, s[4:5]
	v_cndmask_b32_e32 v6, 0, v206, vcc
	v_sub_f32_e32 v5, v5, v6
	v_add_f32_e32 v38, v5, v36
	v_readlane_b32 s100, v254, 9
	s_or_b32 s100, s45, s100
	s_nop 0
	v_mad_i64_i32 v[248:249], s[4:5], s100, v205, v[106:107]
	global_load_ushort v224, v[248:249], off
	s_waitcnt vmcnt(25)
; __device__ __forceinline__ float bf2f(unsigned v) { return __uint_as_float(v << 16); }
; __device__ __forceinline__ float sigmoidf_(float x) { return __builtin_amdgcn_rcpf(1.0f + __builtin_amdgcn_exp2f(-1.4426950408889634f * x)); }
; __device__ __forceinline__ void hgrn_out_phase(const Ctx& F, const Args& a, int l) {
;     ...
;             float fv[64]; float ref = 0.f;
; #pragma unroll
;             for (int t = 0; t < 64; ++t) {
;                 const float pre = bf2f(PB[(size_t)(rb + (dir ? 63 - t : t)) * INW + colf]);
;                 const float f = lb + (1.0f - lb) * sigmoidf_(pre);
;                 fv[t] = f;
;                 if (t < 32) ref += __logf(f);
;             }
	v_lshlrev_b32_e32 v5, 16, v225
	v_mul_f32_e32 v5, 0xbfb8aa3b, v5
	v_exp_f32_e32 v5, v5
	s_nop 0
	v_add_f32_e32 v5, 1.0, v5
	v_rcp_f32_e32 v5, v5
	s_nop 0
	v_fma_f32 v39, v2, v5, v4
	v_cmp_gt_f32_e32 vcc, s35, v39
	s_nop 1
	v_cndmask_b32_e64 v5, 0, 32, vcc
	v_ldexp_f32 v5, v39, v5
	v_log_f32_e32 v5, v5
	s_nop 0
	v_mul_f32_e32 v6, 0x3f317217, v5
	v_fma_f32 v6, v5, s31, -v6
	v_fmac_f32_e32 v6, 0x3377d1cf, v5
	v_fmac_f32_e32 v6, 0x3f317217, v5
	v_cmp_lt_f32_e64 s[4:5], |v5|, s34
	s_nop 1
	v_cndmask_b32_e64 v5, v5, v6, s[4:5]
	v_cndmask_b32_e32 v6, 0, v206, vcc
	v_sub_f32_e32 v5, v5, v6
	v_add_f32_e32 v40, v5, v38
	v_readlane_b32 s100, v254, 10
	s_or_b32 s100, s45, s100
	s_nop 0
	v_mad_i64_i32 v[248:249], s[4:5], s100, v205, v[106:107]
	global_load_ushort v225, v[248:249], off
	s_waitcnt vmcnt(25)
	v_lshlrev_b32_e32 v5, 16, v226
	v_mul_f32_e32 v5, 0xbfb8aa3b, v5
	v_exp_f32_e32 v5, v5
	s_nop 0
	v_add_f32_e32 v5, 1.0, v5
	v_rcp_f32_e32 v5, v5
	s_nop 0
	v_fma_f32 v41, v2, v5, v4
	v_cmp_gt_f32_e32 vcc, s35, v41
	s_nop 1
	v_cndmask_b32_e64 v5, 0, 32, vcc
	v_ldexp_f32 v5, v41, v5
	v_log_f32_e32 v5, v5
	s_nop 0
	v_mul_f32_e32 v6, 0x3f317217, v5
	v_fma_f32 v6, v5, s31, -v6
	v_fmac_f32_e32 v6, 0x3377d1cf, v5
	v_fmac_f32_e32 v6, 0x3f317217, v5
	v_cmp_lt_f32_e64 s[4:5], |v5|, s34
	s_nop 1
	v_cndmask_b32_e64 v5, v5, v6, s[4:5]
	v_cndmask_b32_e32 v6, 0, v206, vcc
	v_sub_f32_e32 v5, v5, v6
	v_add_f32_e32 v42, v5, v40
	v_readlane_b32 s100, v254, 11
	s_or_b32 s100, s45, s100
	s_nop 0
	v_mad_i64_i32 v[248:249], s[4:5], s100, v205, v[106:107]
	global_load_ushort v226, v[248:249], off
	s_waitcnt vmcnt(25)
	v_lshlrev_b32_e32 v5, 16, v227
	v_mul_f32_e32 v5, 0xbfb8aa3b, v5
	v_exp_f32_e32 v5, v5
	s_nop 0
	v_add_f32_e32 v5, 1.0, v5
	v_rcp_f32_e32 v5, v5
	s_nop 0
	v_fma_f32 v43, v2, v5, v4
	v_cmp_gt_f32_e32 vcc, s35, v43
	s_nop 1
	v_cndmask_b32_e64 v5, 0, 32, vcc
	v_ldexp_f32 v5, v43, v5
	v_log_f32_e32 v5, v5
	s_nop 0
	v_mul_f32_e32 v6, 0x3f317217, v5
	v_fma_f32 v6, v5, s31, -v6
	v_fmac_f32_e32 v6, 0x3377d1cf, v5
	v_fmac_f32_e32 v6, 0x3f317217, v5
	v_cmp_lt_f32_e64 s[4:5], |v5|, s34
	s_nop 1
	v_cndmask_b32_e64 v5, v5, v6, s[4:5]
	v_cndmask_b32_e32 v6, 0, v206, vcc
	v_sub_f32_e32 v5, v5, v6
	v_add_f32_e32 v44, v5, v42
	v_readlane_b32 s100, v254, 12
	s_or_b32 s100, s45, s100
	s_nop 0
	v_mad_i64_i32 v[248:249], s[4:5], s100, v205, v[106:107]
	global_load_ushort v227, v[248:249], off
	s_waitcnt vmcnt(25)
	v_lshlrev_b32_e32 v5, 16, v228
	v_mul_f32_e32 v5, 0xbfb8aa3b, v5
	v_exp_f32_e32 v5, v5
	s_nop 0
	v_add_f32_e32 v5, 1.0, v5
	v_rcp_f32_e32 v5, v5
	s_nop 0
	v_fma_f32 v45, v2, v5, v4
	v_cmp_gt_f32_e32 vcc, s35, v45
	s_nop 1
	v_cndmask_b32_e64 v5, 0, 32, vcc
	v_ldexp_f32 v5, v45, v5
	v_log_f32_e32 v5, v5
	s_nop 0
	v_mul_f32_e32 v6, 0x3f317217, v5
	v_fma_f32 v6, v5, s31, -v6
	v_fmac_f32_e32 v6, 0x3377d1cf, v5
	v_fmac_f32_e32 v6, 0x3f317217, v5
	v_cmp_lt_f32_e64 s[4:5], |v5|, s34
	s_nop 1
	v_cndmask_b32_e64 v5, v5, v6, s[4:5]
	v_cndmask_b32_e32 v6, 0, v206, vcc
	v_sub_f32_e32 v5, v5, v6
	v_add_f32_e32 v46, v5, v44
	v_readlane_b32 s100, v254, 13
	s_or_b32 s100, s45, s100
	s_nop 0
	v_mad_i64_i32 v[248:249], s[4:5], s100, v205, v[106:107]
	global_load_ushort v228, v[248:249], off
	s_waitcnt vmcnt(25)
	v_lshlrev_b32_e32 v5, 16, v229
	v_mul_f32_e32 v5, 0xbfb8aa3b, v5
	v_exp_f32_e32 v5, v5
	s_nop 0
	v_add_f32_e32 v5, 1.0, v5
	v_rcp_f32_e32 v5, v5
	s_nop 0
	v_fma_f32 v47, v2, v5, v4
	v_cmp_gt_f32_e32 vcc, s35, v47
	s_nop 1
	v_cndmask_b32_e64 v5, 0, 32, vcc
	v_ldexp_f32 v5, v47, v5
	v_log_f32_e32 v5, v5
	s_nop 0
	v_mul_f32_e32 v6, 0x3f317217, v5
	v_fma_f32 v6, v5, s31, -v6
	v_fmac_f32_e32 v6, 0x3377d1cf, v5
	v_fmac_f32_e32 v6, 0x3f317217, v5
	v_cmp_lt_f32_e64 s[4:5], |v5|, s34
	s_nop 1
	v_cndmask_b32_e64 v5, v5, v6, s[4:5]
	v_cndmask_b32_e32 v6, 0, v206, vcc
	v_sub_f32_e32 v5, v5, v6
	v_add_f32_e32 v49, v5, v46
	v_readlane_b32 s100, v254, 14
	s_or_b32 s100, s45, s100
	s_nop 0
	v_mad_i64_i32 v[248:249], s[4:5], s100, v205, v[106:107]
	global_load_ushort v229, v[248:249], off
	s_waitcnt vmcnt(25)
	v_lshlrev_b32_e32 v5, 16, v230
	v_mul_f32_e32 v5, 0xbfb8aa3b, v5
	v_exp_f32_e32 v5, v5
	s_nop 0
	v_add_f32_e32 v5, 1.0, v5
	v_rcp_f32_e32 v5, v5
	s_nop 0
	v_fma_f32 v48, v2, v5, v4
	v_cmp_gt_f32_e32 vcc, s35, v48
	s_nop 1
	v_cndmask_b32_e64 v5, 0, 32, vcc
	v_ldexp_f32 v5, v48, v5
	v_log_f32_e32 v5, v5
	s_nop 0
	v_mul_f32_e32 v6, 0x3f317217, v5
	v_fma_f32 v6, v5, s31, -v6
	v_fmac_f32_e32 v6, 0x3377d1cf, v5
	v_fmac_f32_e32 v6, 0x3f317217, v5
	v_cmp_lt_f32_e64 s[4:5], |v5|, s34
	s_nop 1
	v_cndmask_b32_e64 v5, v5, v6, s[4:5]
	v_cndmask_b32_e32 v6, 0, v206, vcc
	v_sub_f32_e32 v5, v5, v6
	v_add_f32_e32 v53, v5, v49
	v_readlane_b32 s100, v254, 15
	s_or_b32 s100, s45, s100
	s_nop 0
	v_mad_i64_i32 v[248:249], s[4:5], s100, v205, v[106:107]
	global_load_ushort v230, v[248:249], off
	s_waitcnt vmcnt(25)
	v_lshlrev_b32_e32 v5, 16, v231
	v_mul_f32_e32 v5, 0xbfb8aa3b, v5
	v_exp_f32_e32 v5, v5
	s_nop 0
	v_add_f32_e32 v5, 1.0, v5
	v_rcp_f32_e32 v5, v5
	s_nop 0
	v_fma_f32 v54, v2, v5, v4
	v_cmp_gt_f32_e32 vcc, s35, v54
	s_nop 1
	v_cndmask_b32_e64 v5, 0, 32, vcc
	v_ldexp_f32 v5, v54, v5
	v_log_f32_e32 v5, v5
	s_nop 0
	v_mul_f32_e32 v6, 0x3f317217, v5
	v_fma_f32 v6, v5, s31, -v6
	v_fmac_f32_e32 v6, 0x3377d1cf, v5
	v_fmac_f32_e32 v6, 0x3f317217, v5
	v_cmp_lt_f32_e64 s[4:5], |v5|, s34
	s_nop 1
	v_cndmask_b32_e64 v5, v5, v6, s[4:5]
	v_cndmask_b32_e32 v6, 0, v206, vcc
	v_sub_f32_e32 v5, v5, v6
	v_add_f32_e32 v55, v5, v53
	v_readlane_b32 s100, v254, 16
	s_or_b32 s100, s45, s100
	s_nop 0
	v_mad_i64_i32 v[248:249], s[4:5], s100, v205, v[106:107]
	global_load_ushort v231, v[248:249], off
	s_waitcnt vmcnt(25)
; __device__ __forceinline__ float bf2f(unsigned v) { return __uint_as_float(v << 16); }
; __device__ __forceinline__ float sigmoidf_(float x) { return __builtin_amdgcn_rcpf(1.0f + __builtin_amdgcn_exp2f(-1.4426950408889634f * x)); }
; __device__ __forceinline__ void hgrn_out_phase(const Ctx& F, const Args& a, int l) {
;     ...
;             float fv[64]; float ref = 0.f;
; #pragma unroll
;             for (int t = 0; t < 64; ++t) {
;                 const float pre = bf2f(PB[(size_t)(rb + (dir ? 63 - t : t)) * INW + colf]);
;                 const float f = lb + (1.0f - lb) * sigmoidf_(pre);
;                 fv[t] = f;
;                 if (t < 32) ref += __logf(f);
;             }
	v_lshlrev_b32_e32 v5, 16, v232
	v_mul_f32_e32 v5, 0xbfb8aa3b, v5
	v_exp_f32_e32 v5, v5
	s_nop 0
	v_add_f32_e32 v5, 1.0, v5
	v_rcp_f32_e32 v5, v5
	s_nop 0
	v_fma_f32 v56, v2, v5, v4
	v_cmp_gt_f32_e32 vcc, s35, v56
	s_nop 1
	v_cndmask_b32_e64 v5, 0, 32, vcc
	v_ldexp_f32 v5, v56, v5
	v_log_f32_e32 v5, v5
	s_nop 0
	v_mul_f32_e32 v6, 0x3f317217, v5
	v_fma_f32 v6, v5, s31, -v6
	v_fmac_f32_e32 v6, 0x3377d1cf, v5
	v_fmac_f32_e32 v6, 0x3f317217, v5
	v_cmp_lt_f32_e64 s[4:5], |v5|, s34
	s_nop 1
	v_cndmask_b32_e64 v5, v5, v6, s[4:5]
	v_cndmask_b32_e32 v6, 0, v206, vcc
	v_sub_f32_e32 v5, v5, v6
	v_add_f32_e32 v57, v5, v55
	v_readlane_b32 s100, v254, 17
	s_or_b32 s100, s45, s100
	s_nop 0
	v_mad_i64_i32 v[248:249], s[4:5], s100, v205, v[106:107]
	global_load_ushort v232, v[248:249], off
	s_waitcnt vmcnt(25)
	v_lshlrev_b32_e32 v5, 16, v233
	v_mul_f32_e32 v5, 0xbfb8aa3b, v5
	v_exp_f32_e32 v5, v5
	s_nop 0
	v_add_f32_e32 v5, 1.0, v5
	v_rcp_f32_e32 v5, v5
	s_nop 0
	v_fma_f32 v58, v2, v5, v4
	v_cmp_gt_f32_e32 vcc, s35, v58
	s_nop 1
	v_cndmask_b32_e64 v5, 0, 32, vcc
	v_ldexp_f32 v5, v58, v5
	v_log_f32_e32 v5, v5
	s_nop 0
	v_mul_f32_e32 v6, 0x3f317217, v5
	v_fma_f32 v6, v5, s31, -v6
	v_fmac_f32_e32 v6, 0x3377d1cf, v5
	v_fmac_f32_e32 v6, 0x3f317217, v5
	v_cmp_lt_f32_e64 s[4:5], |v5|, s34
	s_nop 1
	v_cndmask_b32_e64 v5, v5, v6, s[4:5]
	v_cndmask_b32_e32 v6, 0, v206, vcc
	v_sub_f32_e32 v5, v5, v6
	v_add_f32_e32 v59, v5, v57
	v_readlane_b32 s100, v254, 18
	s_or_b32 s100, s45, s100
	s_nop 0
	v_mad_i64_i32 v[248:249], s[4:5], s100, v205, v[106:107]
	global_load_ushort v233, v[248:249], off
	s_waitcnt vmcnt(25)
	v_lshlrev_b32_e32 v5, 16, v234
	v_mul_f32_e32 v5, 0xbfb8aa3b, v5
	v_exp_f32_e32 v5, v5
	s_nop 0
	v_add_f32_e32 v5, 1.0, v5
	v_rcp_f32_e32 v5, v5
	s_nop 0
	v_fma_f32 v60, v2, v5, v4
	v_cmp_gt_f32_e32 vcc, s35, v60
	s_nop 1
	v_cndmask_b32_e64 v5, 0, 32, vcc
	v_ldexp_f32 v5, v60, v5
	v_log_f32_e32 v5, v5
	s_nop 0
	v_mul_f32_e32 v6, 0x3f317217, v5
	v_fma_f32 v6, v5, s31, -v6
	v_fmac_f32_e32 v6, 0x3377d1cf, v5
	v_fmac_f32_e32 v6, 0x3f317217, v5
	v_cmp_lt_f32_e64 s[4:5], |v5|, s34
	s_nop 1
	v_cndmask_b32_e64 v5, v5, v6, s[4:5]
	v_cndmask_b32_e32 v6, 0, v206, vcc
	v_sub_f32_e32 v5, v5, v6
	v_add_f32_e32 v61, v5, v59
	v_readlane_b32 s100, v254, 19
	s_or_b32 s100, s45, s100
	s_nop 0
	v_mad_i64_i32 v[248:249], s[4:5], s100, v205, v[106:107]
	global_load_ushort v234, v[248:249], off
	s_waitcnt vmcnt(25)
	v_lshlrev_b32_e32 v5, 16, v235
	v_mul_f32_e32 v5, 0xbfb8aa3b, v5
	v_exp_f32_e32 v5, v5
	s_nop 0
	v_add_f32_e32 v5, 1.0, v5
	v_rcp_f32_e32 v5, v5
	s_nop 0
	v_fma_f32 v62, v2, v5, v4
	v_cmp_gt_f32_e32 vcc, s35, v62
	s_nop 1
	v_cndmask_b32_e64 v5, 0, 32, vcc
	v_ldexp_f32 v5, v62, v5
	v_log_f32_e32 v5, v5
	s_nop 0
	v_mul_f32_e32 v6, 0x3f317217, v5
	v_fma_f32 v6, v5, s31, -v6
	v_fmac_f32_e32 v6, 0x3377d1cf, v5
	v_fmac_f32_e32 v6, 0x3f317217, v5
	v_cmp_lt_f32_e64 s[4:5], |v5|, s34
	s_nop 1
	v_cndmask_b32_e64 v5, v5, v6, s[4:5]
	v_cndmask_b32_e32 v6, 0, v206, vcc
	v_sub_f32_e32 v5, v5, v6
	v_add_f32_e32 v63, v5, v61
	v_readlane_b32 s100, v254, 20
	s_or_b32 s100, s45, s100
	s_nop 0
	v_mad_i64_i32 v[248:249], s[4:5], s100, v205, v[106:107]
	global_load_ushort v235, v[248:249], off
	s_waitcnt vmcnt(25)
	v_lshlrev_b32_e32 v5, 16, v236
	v_mul_f32_e32 v5, 0xbfb8aa3b, v5
	v_exp_f32_e32 v5, v5
	s_nop 0
	v_add_f32_e32 v5, 1.0, v5
	v_rcp_f32_e32 v5, v5
	s_nop 0
	v_fma_f32 v64, v2, v5, v4
	v_cmp_gt_f32_e32 vcc, s35, v64
	s_nop 1
	v_cndmask_b32_e64 v5, 0, 32, vcc
	v_ldexp_f32 v5, v64, v5
	v_log_f32_e32 v5, v5
	s_nop 0
	v_mul_f32_e32 v6, 0x3f317217, v5
	v_fma_f32 v6, v5, s31, -v6
	v_fmac_f32_e32 v6, 0x3377d1cf, v5
	v_fmac_f32_e32 v6, 0x3f317217, v5
	v_cmp_lt_f32_e64 s[4:5], |v5|, s34
	s_nop 1
	v_cndmask_b32_e64 v5, v5, v6, s[4:5]
	v_cndmask_b32_e32 v6, 0, v206, vcc
	v_sub_f32_e32 v5, v5, v6
	v_add_f32_e32 v65, v5, v63
	v_readlane_b32 s100, v254, 21
	s_or_b32 s100, s45, s100
	s_nop 0
	v_mad_i64_i32 v[248:249], s[4:5], s100, v205, v[106:107]
	global_load_ushort v236, v[248:249], off
	s_waitcnt vmcnt(25)
	v_lshlrev_b32_e32 v5, 16, v237
	v_mul_f32_e32 v5, 0xbfb8aa3b, v5
	v_exp_f32_e32 v5, v5
	s_nop 0
	v_add_f32_e32 v5, 1.0, v5
	v_rcp_f32_e32 v5, v5
	s_nop 0
	v_fma_f32 v66, v2, v5, v4
	v_cmp_gt_f32_e32 vcc, s35, v66
	s_nop 1
	v_cndmask_b32_e64 v5, 0, 32, vcc
	v_ldexp_f32 v5, v66, v5
	v_log_f32_e32 v5, v5
	s_nop 0
	v_mul_f32_e32 v6, 0x3f317217, v5
	v_fma_f32 v6, v5, s31, -v6
	v_fmac_f32_e32 v6, 0x3377d1cf, v5
	v_fmac_f32_e32 v6, 0x3f317217, v5
	v_cmp_lt_f32_e64 s[4:5], |v5|, s34
	s_nop 1
	v_cndmask_b32_e64 v5, v5, v6, s[4:5]
	v_cndmask_b32_e32 v6, 0, v206, vcc
	v_sub_f32_e32 v5, v5, v6
	v_add_f32_e32 v68, v5, v65
	v_readlane_b32 s100, v254, 22
	s_or_b32 s100, s45, s100
	s_nop 0
	v_mad_i64_i32 v[248:249], s[4:5], s100, v205, v[106:107]
	global_load_ushort v237, v[248:249], off
	s_waitcnt vmcnt(25)
	v_lshlrev_b32_e32 v5, 16, v238
	v_mul_f32_e32 v5, 0xbfb8aa3b, v5
	v_exp_f32_e32 v5, v5
	s_nop 0
	v_add_f32_e32 v5, 1.0, v5
	v_rcp_f32_e32 v5, v5
	s_nop 0
	v_fma_f32 v67, v2, v5, v4
	v_cmp_gt_f32_e32 vcc, s35, v67
	s_nop 1
	v_cndmask_b32_e64 v5, 0, 32, vcc
	v_ldexp_f32 v5, v67, v5
	v_log_f32_e32 v5, v5
	s_nop 0
	v_mul_f32_e32 v6, 0x3f317217, v5
	v_fma_f32 v6, v5, s31, -v6
	v_fmac_f32_e32 v6, 0x3377d1cf, v5
	v_fmac_f32_e32 v6, 0x3f317217, v5
	v_cmp_lt_f32_e64 s[4:5], |v5|, s34
	s_nop 1
	v_cndmask_b32_e64 v5, v5, v6, s[4:5]
	v_cndmask_b32_e32 v6, 0, v206, vcc
	v_sub_f32_e32 v5, v5, v6
	v_add_f32_e32 v69, v5, v68
	v_readlane_b32 s100, v254, 23
	s_or_b32 s100, s45, s100
	s_nop 0
	v_mad_i64_i32 v[248:249], s[4:5], s100, v205, v[106:107]
	global_load_ushort v238, v[248:249], off
	s_waitcnt vmcnt(25)
; __device__ __forceinline__ float bf2f(unsigned v) { return __uint_as_float(v << 16); }
; __device__ __forceinline__ float sigmoidf_(float x) { return __builtin_amdgcn_rcpf(1.0f + __builtin_amdgcn_exp2f(-1.4426950408889634f * x)); }
; __device__ __forceinline__ void hgrn_out_phase(const Ctx& F, const Args& a, int l) {
;     ...
;             float fv[64]; float ref = 0.f;
; #pragma unroll
;             for (int t = 0; t < 64; ++t) {
;                 const float pre = bf2f(PB[(size_t)(rb + (dir ? 63 - t : t)) * INW + colf]);
;                 const float f = lb + (1.0f - lb) * sigmoidf_(pre);
;                 fv[t] = f;
;                 if (t < 32) ref += __logf(f);
;             }
	v_lshlrev_b32_e32 v5, 16, v239
	v_mul_f32_e32 v5, 0xbfb8aa3b, v5
	v_exp_f32_e32 v5, v5
	s_nop 0
	v_add_f32_e32 v5, 1.0, v5
	v_rcp_f32_e32 v5, v5
	s_nop 0
	v_fma_f32 v70, v2, v5, v4
	v_cmp_gt_f32_e32 vcc, s35, v70
	s_nop 1
	v_cndmask_b32_e64 v5, 0, 32, vcc
	v_ldexp_f32 v5, v70, v5
	v_log_f32_e32 v5, v5
	s_nop 0
	v_mul_f32_e32 v6, 0x3f317217, v5
	v_fma_f32 v6, v5, s31, -v6
	v_fmac_f32_e32 v6, 0x3377d1cf, v5
	v_fmac_f32_e32 v6, 0x3f317217, v5
	v_cmp_lt_f32_e64 s[4:5], |v5|, s34
	s_nop 1
	v_cndmask_b32_e64 v5, v5, v6, s[4:5]
	v_cndmask_b32_e32 v6, 0, v206, vcc
	v_sub_f32_e32 v5, v5, v6
	v_add_f32_e32 v71, v5, v69
	v_readlane_b32 s100, v254, 24
	s_or_b32 s100, s45, s100
	s_nop 0
	v_mad_i64_i32 v[248:249], s[4:5], s100, v205, v[106:107]
	global_load_ushort v239, v[248:249], off
	s_waitcnt vmcnt(25)
	v_lshlrev_b32_e32 v5, 16, v240
	v_mul_f32_e32 v5, 0xbfb8aa3b, v5
	v_exp_f32_e32 v5, v5
	s_nop 0
	v_add_f32_e32 v5, 1.0, v5
	v_rcp_f32_e32 v5, v5
	s_nop 0
	v_fma_f32 v72, v2, v5, v4
	v_cmp_gt_f32_e32 vcc, s35, v72
	s_nop 1
	v_cndmask_b32_e64 v5, 0, 32, vcc
	v_ldexp_f32 v5, v72, v5
	v_log_f32_e32 v5, v5
	s_nop 0
	v_mul_f32_e32 v6, 0x3f317217, v5
	v_fma_f32 v6, v5, s31, -v6
	v_fmac_f32_e32 v6, 0x3377d1cf, v5
	v_fmac_f32_e32 v6, 0x3f317217, v5
	v_cmp_lt_f32_e64 s[4:5], |v5|, s34
	s_nop 1
	v_cndmask_b32_e64 v5, v5, v6, s[4:5]
	v_cndmask_b32_e32 v6, 0, v206, vcc
	v_sub_f32_e32 v5, v5, v6
	v_add_f32_e32 v73, v5, v71
	v_readlane_b32 s100, v254, 25
	s_or_b32 s100, s45, s100
	s_nop 0
	v_mad_i64_i32 v[248:249], s[4:5], s100, v205, v[106:107]
	global_load_ushort v240, v[248:249], off
	s_waitcnt vmcnt(25)
	v_lshlrev_b32_e32 v5, 16, v241
	v_mul_f32_e32 v5, 0xbfb8aa3b, v5
	v_exp_f32_e32 v5, v5
	s_nop 0
	v_add_f32_e32 v5, 1.0, v5
	v_rcp_f32_e32 v5, v5
	s_nop 0
	v_fma_f32 v74, v2, v5, v4
	v_cmp_gt_f32_e32 vcc, s35, v74
	s_nop 1
	v_cndmask_b32_e64 v5, 0, 32, vcc
	v_ldexp_f32 v5, v74, v5
	v_log_f32_e32 v5, v5
	s_nop 0
	v_mul_f32_e32 v6, 0x3f317217, v5
	v_fma_f32 v6, v5, s31, -v6
	v_fmac_f32_e32 v6, 0x3377d1cf, v5
	v_fmac_f32_e32 v6, 0x3f317217, v5
	v_cmp_lt_f32_e64 s[4:5], |v5|, s34
	s_nop 1
	v_cndmask_b32_e64 v5, v5, v6, s[4:5]
	v_cndmask_b32_e32 v6, 0, v206, vcc
	v_sub_f32_e32 v5, v5, v6
	v_add_f32_e32 v75, v5, v73
	v_readlane_b32 s100, v254, 26
	s_or_b32 s100, s45, s100
	s_nop 0
	v_mad_i64_i32 v[248:249], s[4:5], s100, v205, v[106:107]
	global_load_ushort v241, v[248:249], off
	s_waitcnt vmcnt(25)
	v_lshlrev_b32_e32 v5, 16, v242
	v_mul_f32_e32 v5, 0xbfb8aa3b, v5
	v_exp_f32_e32 v5, v5
	s_nop 0
	v_add_f32_e32 v5, 1.0, v5
	v_rcp_f32_e32 v5, v5
	s_nop 0
	v_fma_f32 v76, v2, v5, v4
	v_cmp_gt_f32_e32 vcc, s35, v76
	s_nop 1
	v_cndmask_b32_e64 v5, 0, 32, vcc
	v_ldexp_f32 v5, v76, v5
	v_log_f32_e32 v5, v5
	s_nop 0
	v_mul_f32_e32 v6, 0x3f317217, v5
	v_fma_f32 v6, v5, s31, -v6
	v_fmac_f32_e32 v6, 0x3377d1cf, v5
	v_fmac_f32_e32 v6, 0x3f317217, v5
	v_cmp_lt_f32_e64 s[4:5], |v5|, s34
	s_nop 1
	v_cndmask_b32_e64 v5, v5, v6, s[4:5]
	v_cndmask_b32_e32 v6, 0, v206, vcc
	v_sub_f32_e32 v5, v5, v6
	v_add_f32_e32 v77, v5, v75
	v_readlane_b32 s100, v254, 27
	s_or_b32 s100, s45, s100
	s_nop 0
	v_mad_i64_i32 v[248:249], s[4:5], s100, v205, v[106:107]
	global_load_ushort v242, v[248:249], off
	s_waitcnt vmcnt(25)
	v_lshlrev_b32_e32 v5, 16, v243
	v_mul_f32_e32 v5, 0xbfb8aa3b, v5
	v_exp_f32_e32 v5, v5
	s_nop 0
	v_add_f32_e32 v5, 1.0, v5
	v_rcp_f32_e32 v5, v5
	s_nop 0
	v_fma_f32 v78, v2, v5, v4
	v_cmp_gt_f32_e32 vcc, s35, v78
	s_nop 1
	v_cndmask_b32_e64 v5, 0, 32, vcc
	v_ldexp_f32 v5, v78, v5
	v_log_f32_e32 v5, v5
	s_nop 0
	v_mul_f32_e32 v6, 0x3f317217, v5
	v_fma_f32 v6, v5, s31, -v6
	v_fmac_f32_e32 v6, 0x3377d1cf, v5
	v_fmac_f32_e32 v6, 0x3f317217, v5
	v_cmp_lt_f32_e64 s[4:5], |v5|, s34
	s_nop 1
	v_cndmask_b32_e64 v5, v5, v6, s[4:5]
	v_cndmask_b32_e32 v6, 0, v206, vcc
	v_sub_f32_e32 v5, v5, v6
	v_add_f32_e32 v79, v5, v77
	v_readlane_b32 s100, v254, 28
	s_or_b32 s100, s45, s100
	s_nop 0
	v_mad_i64_i32 v[248:249], s[4:5], s100, v205, v[106:107]
	global_load_ushort v243, v[248:249], off
	s_waitcnt vmcnt(25)
	v_lshlrev_b32_e32 v5, 16, v244
	v_mul_f32_e32 v5, 0xbfb8aa3b, v5
	v_exp_f32_e32 v5, v5
	s_nop 0
	v_add_f32_e32 v5, 1.0, v5
	v_rcp_f32_e32 v5, v5
	s_nop 0
	v_fma_f32 v80, v2, v5, v4
	v_cmp_gt_f32_e32 vcc, s35, v80
	s_nop 1
	v_cndmask_b32_e64 v5, 0, 32, vcc
	v_ldexp_f32 v5, v80, v5
	v_log_f32_e32 v5, v5
	s_nop 0
	v_mul_f32_e32 v6, 0x3f317217, v5
	v_fma_f32 v6, v5, s31, -v6
	v_fmac_f32_e32 v6, 0x3377d1cf, v5
	v_fmac_f32_e32 v6, 0x3f317217, v5
	v_cmp_lt_f32_e64 s[4:5], |v5|, s34
	s_nop 1
	v_cndmask_b32_e64 v5, v5, v6, s[4:5]
	v_cndmask_b32_e32 v6, 0, v206, vcc
	v_sub_f32_e32 v5, v5, v6
	v_add_f32_e32 v81, v5, v79
	v_readlane_b32 s100, v254, 29
	s_or_b32 s100, s45, s100
	s_nop 0
	v_mad_i64_i32 v[248:249], s[4:5], s100, v205, v[106:107]
	global_load_ushort v244, v[248:249], off
	s_waitcnt vmcnt(25)
	v_lshlrev_b32_e32 v5, 16, v245
	v_mul_f32_e32 v5, 0xbfb8aa3b, v5
	v_exp_f32_e32 v5, v5
	s_nop 0
	v_add_f32_e32 v5, 1.0, v5
	v_rcp_f32_e32 v5, v5
	s_nop 0
	v_fma_f32 v82, v2, v5, v4
	v_cmp_gt_f32_e32 vcc, s35, v82
	s_nop 1
	v_cndmask_b32_e64 v5, 0, 32, vcc
	v_ldexp_f32 v5, v82, v5
	v_log_f32_e32 v5, v5
	s_nop 0
	v_mul_f32_e32 v6, 0x3f317217, v5
	v_fma_f32 v6, v5, s31, -v6
	v_fmac_f32_e32 v6, 0x3377d1cf, v5
	v_fmac_f32_e32 v6, 0x3f317217, v5
	v_cmp_lt_f32_e64 s[4:5], |v5|, s34
	s_nop 1
	v_cndmask_b32_e64 v5, v5, v6, s[4:5]
	v_cndmask_b32_e32 v6, 0, v206, vcc
	v_sub_f32_e32 v5, v5, v6
	v_add_f32_e32 v83, v5, v81
	v_readlane_b32 s100, v254, 30
	s_or_b32 s100, s45, s100
	s_nop 0
	v_mad_i64_i32 v[248:249], s[4:5], s100, v205, v[106:107]
	global_load_ushort v245, v[248:249], off
	s_waitcnt vmcnt(25)
; __device__ __forceinline__ float bf2f(unsigned v) { return __uint_as_float(v << 16); }
; __device__ __forceinline__ float sigmoidf_(float x) { return __builtin_amdgcn_rcpf(1.0f + __builtin_amdgcn_exp2f(-1.4426950408889634f * x)); }
; __device__ __forceinline__ void hgrn_out_phase(const Ctx& F, const Args& a, int l) {
;     ...
;             float fv[64]; float ref = 0.f;
; #pragma unroll
;             for (int t = 0; t < 64; ++t) {
;                 const float pre = bf2f(PB[(size_t)(rb + (dir ? 63 - t : t)) * INW + colf]);
;                 const float f = lb + (1.0f - lb) * sigmoidf_(pre);
;                 fv[t] = f;
;                 if (t < 32) ref += __logf(f);
;             }
	v_lshlrev_b32_e32 v5, 16, v246
	v_mul_f32_e32 v5, 0xbfb8aa3b, v5
	v_exp_f32_e32 v5, v5
	s_nop 0
	v_add_f32_e32 v5, 1.0, v5
	v_rcp_f32_e32 v5, v5
	s_nop 0
	v_fma_f32 v84, v2, v5, v4
	v_cmp_gt_f32_e32 vcc, s35, v84
	s_nop 1
	v_cndmask_b32_e64 v5, 0, 32, vcc
	v_ldexp_f32 v5, v84, v5
	v_log_f32_e32 v5, v5
	s_nop 0
	v_mul_f32_e32 v6, 0x3f317217, v5
	v_fma_f32 v6, v5, s31, -v6
	v_fmac_f32_e32 v6, 0x3377d1cf, v5
	v_fmac_f32_e32 v6, 0x3f317217, v5
	v_cmp_lt_f32_e64 s[4:5], |v5|, s34
	s_nop 1
	v_cndmask_b32_e64 v5, v5, v6, s[4:5]
	v_cndmask_b32_e32 v6, 0, v206, vcc
	v_sub_f32_e32 v5, v5, v6
	v_add_f32_e32 v85, v5, v83
	v_readlane_b32 s100, v254, 31
	s_or_b32 s100, s45, s100
	s_nop 0
	v_mad_i64_i32 v[248:249], s[4:5], s100, v205, v[106:107]
	global_load_ushort v246, v[248:249], off
	s_waitcnt vmcnt(25)
	v_lshlrev_b32_e32 v5, 16, v247
	v_mul_f32_e32 v5, 0xbfb8aa3b, v5
	v_exp_f32_e32 v5, v5
	s_nop 0
	v_add_f32_e32 v5, 1.0, v5
	v_rcp_f32_e32 v5, v5
	s_nop 0
	v_fma_f32 v86, v2, v5, v4
	v_cmp_gt_f32_e32 vcc, s35, v86
	s_nop 1
	v_cndmask_b32_e64 v5, 0, 32, vcc
	v_ldexp_f32 v5, v86, v5
	v_log_f32_e32 v5, v5
	s_nop 0
	v_mul_f32_e32 v6, 0x3f317217, v5
	v_fma_f32 v6, v5, s31, -v6
	v_fmac_f32_e32 v6, 0x3377d1cf, v5
	v_fmac_f32_e32 v6, 0x3f317217, v5
	v_cmp_lt_f32_e64 s[4:5], |v5|, s34
	s_nop 1
	v_cndmask_b32_e64 v5, v5, v6, s[4:5]
	v_cndmask_b32_e32 v6, 0, v206, vcc
	v_sub_f32_e32 v5, v5, v6
	v_add_f32_e32 v87, v5, v85
	v_readlane_b32 s100, v254, 32
	s_or_b32 s100, s45, s100
	s_nop 0
	v_mad_i64_i32 v[248:249], s[4:5], s100, v205, v[106:107]
	global_load_ushort v247, v[248:249], off
	s_waitcnt vmcnt(25)
	v_lshlrev_b32_e32 v5, 16, v222
	v_mul_f32_e32 v5, 0xbfb8aa3b, v5
	v_exp_f32_e32 v5, v5
	s_nop 0
	v_add_f32_e32 v5, 1.0, v5
	v_rcp_f32_e32 v5, v5
	s_nop 0
	v_fma_f32 v88, v2, v5, v4
	v_cmp_gt_f32_e32 vcc, s35, v88
	s_nop 1
	v_cndmask_b32_e64 v5, 0, 32, vcc
	v_ldexp_f32 v5, v88, v5
	v_log_f32_e32 v5, v5
	s_nop 0
	v_mul_f32_e32 v6, 0x3f317217, v5
	v_fma_f32 v6, v5, s31, -v6
	v_fmac_f32_e32 v6, 0x3377d1cf, v5
	v_fmac_f32_e32 v6, 0x3f317217, v5
	v_cmp_lt_f32_e64 s[4:5], |v5|, s34
	s_nop 1
	v_cndmask_b32_e64 v5, v5, v6, s[4:5]
	v_cndmask_b32_e32 v6, 0, v206, vcc
	v_sub_f32_e32 v5, v5, v6
	v_add_f32_e32 v89, v5, v87
	v_readlane_b32 s100, v254, 33
	s_or_b32 s100, s45, s100
	s_nop 0
	v_mad_i64_i32 v[248:249], s[4:5], s100, v205, v[106:107]
	global_load_ushort v222, v[248:249], off
	s_waitcnt vmcnt(25)
	v_lshlrev_b32_e32 v5, 16, v223
	v_mul_f32_e32 v5, 0xbfb8aa3b, v5
	v_exp_f32_e32 v5, v5
	s_nop 0
	v_add_f32_e32 v5, 1.0, v5
	v_rcp_f32_e32 v5, v5
	s_nop 0
	v_fma_f32 v90, v2, v5, v4
	v_cmp_gt_f32_e32 vcc, s35, v90
	s_nop 1
	v_cndmask_b32_e64 v5, 0, 32, vcc
	v_ldexp_f32 v5, v90, v5
	v_log_f32_e32 v5, v5
	s_nop 0
	v_mul_f32_e32 v6, 0x3f317217, v5
	v_fma_f32 v6, v5, s31, -v6
	v_fmac_f32_e32 v6, 0x3377d1cf, v5
	v_fmac_f32_e32 v6, 0x3f317217, v5
	v_cmp_lt_f32_e64 s[4:5], |v5|, s34
	s_nop 1
	v_cndmask_b32_e64 v5, v5, v6, s[4:5]
	v_cndmask_b32_e32 v6, 0, v206, vcc
	v_sub_f32_e32 v5, v5, v6
	v_add_f32_e32 v91, v5, v89
	v_readlane_b32 s100, v254, 34
	s_or_b32 s100, s45, s100
	s_nop 0
	v_mad_i64_i32 v[248:249], s[4:5], s100, v205, v[106:107]
	global_load_ushort v223, v[248:249], off
	s_waitcnt vmcnt(25)
	v_lshlrev_b32_e32 v5, 16, v224
	v_mul_f32_e32 v5, 0xbfb8aa3b, v5
	v_exp_f32_e32 v5, v5
	s_nop 0
	v_add_f32_e32 v5, 1.0, v5
	v_rcp_f32_e32 v5, v5
	s_nop 0
	v_fma_f32 v92, v2, v5, v4
	v_cmp_gt_f32_e32 vcc, s35, v92
	s_nop 1
	v_cndmask_b32_e64 v5, 0, 32, vcc
	v_ldexp_f32 v5, v92, v5
	v_log_f32_e32 v5, v5
	s_nop 0
	v_mul_f32_e32 v6, 0x3f317217, v5
	v_fma_f32 v6, v5, s31, -v6
	v_fmac_f32_e32 v6, 0x3377d1cf, v5
	v_fmac_f32_e32 v6, 0x3f317217, v5
	v_cmp_lt_f32_e64 s[4:5], |v5|, s34
	s_nop 1
	v_cndmask_b32_e64 v5, v5, v6, s[4:5]
	v_readlane_b32 s4, v254, 10
	v_cndmask_b32_e32 v6, 0, v206, vcc
	s_or_b32 s96, s45, s4
	v_sub_f32_e32 v5, v5, v6
	v_add_f32_e32 v93, v5, v91
	v_readlane_b32 s100, v254, 35
	s_or_b32 s100, s45, s100
	s_nop 0
	v_mad_i64_i32 v[248:249], s[4:5], s100, v205, v[106:107]
	global_load_ushort v224, v[248:249], off
	s_waitcnt vmcnt(25)
	v_lshlrev_b32_e32 v5, 16, v225
	v_mul_f32_e32 v5, 0xbfb8aa3b, v5
	v_exp_f32_e32 v5, v5
	s_nop 0
	v_add_f32_e32 v5, 1.0, v5
	v_rcp_f32_e32 v5, v5
	s_nop 0
	v_fma_f32 v94, v2, v5, v4
	v_cmp_gt_f32_e32 vcc, s35, v94
	s_nop 1
	v_cndmask_b32_e64 v5, 0, 32, vcc
	v_ldexp_f32 v5, v94, v5
	v_log_f32_e32 v5, v5
	s_nop 0
	v_mul_f32_e32 v6, 0x3f317217, v5
	v_fma_f32 v6, v5, s31, -v6
	v_fmac_f32_e32 v6, 0x3377d1cf, v5
	v_fmac_f32_e32 v6, 0x3f317217, v5
	v_cmp_lt_f32_e64 s[4:5], |v5|, s34
	s_nop 1
	v_cndmask_b32_e64 v5, v5, v6, s[4:5]
	v_readlane_b32 s4, v254, 11
	v_cndmask_b32_e32 v6, 0, v206, vcc
	s_or_b32 s20, s45, s4
	v_sub_f32_e32 v5, v5, v6
	v_add_f32_e32 v95, v5, v93
	v_readlane_b32 s100, v254, 36
	s_or_b32 s100, s45, s100
	s_nop 0
	v_mad_i64_i32 v[248:249], s[4:5], s100, v205, v[106:107]
	global_load_ushort v225, v[248:249], off
	s_waitcnt vmcnt(25)
	v_lshlrev_b32_e32 v5, 16, v226
	v_mul_f32_e32 v5, 0xbfb8aa3b, v5
	v_exp_f32_e32 v5, v5
	s_nop 0
	v_add_f32_e32 v5, 1.0, v5
	v_rcp_f32_e32 v5, v5
	s_nop 0
	v_fma_f32 v96, v2, v5, v4
	v_cmp_gt_f32_e32 vcc, s35, v96
	s_nop 1
	v_cndmask_b32_e64 v5, 0, 32, vcc
	v_ldexp_f32 v5, v96, v5
	v_log_f32_e32 v5, v5
	s_nop 0
	v_mul_f32_e32 v6, 0x3f317217, v5
	v_fma_f32 v6, v5, s31, -v6
	v_fmac_f32_e32 v6, 0x3377d1cf, v5
	v_fmac_f32_e32 v6, 0x3f317217, v5
	v_cmp_lt_f32_e64 s[4:5], |v5|, s34
	s_nop 1
	v_cndmask_b32_e64 v5, v5, v6, s[4:5]
	v_readlane_b32 s4, v254, 12
	v_cndmask_b32_e32 v6, 0, v206, vcc
	s_or_b32 s22, s45, s4
	v_sub_f32_e32 v5, v5, v6
	v_add_f32_e32 v97, v5, v95
	v_readlane_b32 s100, v254, 37
	s_or_b32 s100, s45, s100
	s_nop 0
	v_mad_i64_i32 v[248:249], s[4:5], s100, v205, v[106:107]
	global_load_ushort v226, v[248:249], off
	s_waitcnt vmcnt(25)
; __device__ __forceinline__ float bf2f(unsigned v) { return __uint_as_float(v << 16); }
; __device__ __forceinline__ float sigmoidf_(float x) { return __builtin_amdgcn_rcpf(1.0f + __builtin_amdgcn_exp2f(-1.4426950408889634f * x)); }
; __device__ __forceinline__ void hgrn_out_phase(const Ctx& F, const Args& a, int l) {
;     ...
;             float fv[64]; float ref = 0.f;
; #pragma unroll
;             for (int t = 0; t < 64; ++t) {
;                 const float pre = bf2f(PB[(size_t)(rb + (dir ? 63 - t : t)) * INW + colf]);
;                 const float f = lb + (1.0f - lb) * sigmoidf_(pre);
;                 fv[t] = f;
;                 if (t < 32) ref += __logf(f);
;             }
	v_lshlrev_b32_e32 v5, 16, v227
	v_mul_f32_e32 v5, 0xbfb8aa3b, v5
	v_exp_f32_e32 v5, v5
	s_nop 0
	v_add_f32_e32 v5, 1.0, v5
	v_rcp_f32_e32 v5, v5
	s_nop 0
	v_fma_f32 v99, v2, v5, v4
	v_cmp_gt_f32_e32 vcc, s35, v99
	s_nop 1
	v_cndmask_b32_e64 v5, 0, 32, vcc
	v_ldexp_f32 v5, v99, v5
	v_log_f32_e32 v5, v5
	s_nop 0
	v_mul_f32_e32 v6, 0x3f317217, v5
	v_fma_f32 v6, v5, s31, -v6
	v_fmac_f32_e32 v6, 0x3377d1cf, v5
	v_fmac_f32_e32 v6, 0x3f317217, v5
	v_cmp_lt_f32_e64 s[4:5], |v5|, s34
	s_nop 1
	v_cndmask_b32_e64 v5, v5, v6, s[4:5]
	v_readlane_b32 s4, v254, 13
	v_cndmask_b32_e32 v6, 0, v206, vcc
	s_or_b32 s4, s45, s4
	v_sub_f32_e32 v5, v5, v6
	v_readlane_b32 s100, v254, 38
	s_or_b32 s100, s45, s100
	s_nop 0
	v_mad_i64_i32 v[248:249], s[6:7], s100, v205, v[106:107]
	global_load_ushort v227, v[248:249], off
	v_readlane_b32 s5, v254, 14
	s_or_b32 s64, s45, s5
	v_readlane_b32 s5, v254, 15
	s_or_b32 s63, s45, s5
	v_readlane_b32 s5, v254, 16
	s_or_b32 s62, s45, s5
	v_readlane_b32 s5, v254, 17
	s_or_b32 s43, s45, s5
	v_readlane_b32 s5, v254, 18
	s_or_b32 s42, s45, s5
	v_readlane_b32 s5, v254, 19
	s_or_b32 s59, s45, s5
	v_readlane_b32 s5, v254, 20
	s_or_b32 s58, s45, s5
	v_readlane_b32 s5, v254, 21
	v_add_f32_e32 v5, v5, v97
	s_waitcnt vmcnt(25)
	v_lshlrev_b32_e32 v6, 16, v228
	v_mul_f32_e32 v6, 0xbfb8aa3b, v6
	v_exp_f32_e32 v6, v6
	s_nop 0
	v_add_f32_e32 v6, 1.0, v6
	v_rcp_f32_e32 v6, v6
	s_nop 0
	v_fma_f32 v52, v2, v6, v4
	v_readlane_b32 s100, v254, 39
	s_or_b32 s100, s45, s100
	s_nop 0
	v_mad_i64_i32 v[248:249], s[6:7], s100, v205, v[106:107]
	global_load_ushort v228, v[248:249], off
	s_waitcnt vmcnt(25)
	v_lshlrev_b32_e32 v6, 16, v229
	v_mul_f32_e32 v6, 0xbfb8aa3b, v6
	v_exp_f32_e32 v6, v6
	s_nop 0
	v_add_f32_e32 v6, 1.0, v6
	v_rcp_f32_e32 v6, v6
	s_nop 0
	v_fma_f32 v51, v2, v6, v4
	v_readlane_b32 s100, v254, 40
	s_or_b32 s100, s45, s100
	s_nop 0
	v_mad_i64_i32 v[248:249], s[6:7], s100, v205, v[106:107]
	global_load_ushort v229, v[248:249], off
	s_waitcnt vmcnt(25)
	v_lshlrev_b32_e32 v6, 16, v230
	v_mul_f32_e32 v6, 0xbfb8aa3b, v6
	v_exp_f32_e32 v6, v6
	s_nop 0
	v_add_f32_e32 v6, 1.0, v6
	v_rcp_f32_e32 v6, v6
	s_nop 0
	v_fma_f32 v50, v2, v6, v4
	v_readlane_b32 s100, v254, 41
	s_or_b32 s100, s45, s100
	s_nop 0
	v_mad_i64_i32 v[248:249], s[6:7], s100, v205, v[106:107]
	global_load_ushort v230, v[248:249], off
	s_waitcnt vmcnt(25)
	v_lshlrev_b32_e32 v6, 16, v231
	v_mul_f32_e32 v6, 0xbfb8aa3b, v6
	v_exp_f32_e32 v6, v6
	s_nop 0
	v_add_f32_e32 v6, 1.0, v6
	v_rcp_f32_e32 v6, v6
	s_nop 0
	v_fma_f32 v33, v2, v6, v4
	v_readlane_b32 s100, v254, 42
	s_or_b32 s100, s45, s100
	s_nop 0
	v_mad_i64_i32 v[248:249], s[6:7], s100, v205, v[106:107]
	global_load_ushort v231, v[248:249], off
	s_waitcnt vmcnt(25)
	v_lshlrev_b32_e32 v6, 16, v232
	v_mul_f32_e32 v6, 0xbfb8aa3b, v6
	v_exp_f32_e32 v6, v6
	s_nop 0
	v_add_f32_e32 v6, 1.0, v6
	v_rcp_f32_e32 v6, v6
	s_nop 0
	v_fma_f32 v32, v2, v6, v4
	s_waitcnt vmcnt(24)
	v_lshlrev_b32_e32 v6, 16, v233
	v_mul_f32_e32 v6, 0xbfb8aa3b, v6
	v_exp_f32_e32 v6, v6
	s_nop 0
	v_add_f32_e32 v6, 1.0, v6
	v_rcp_f32_e32 v6, v6
	s_nop 0
	v_fma_f32 v31, v2, v6, v4
	s_waitcnt vmcnt(23)
	v_lshlrev_b32_e32 v6, 16, v234
	v_mul_f32_e32 v6, 0xbfb8aa3b, v6
	v_exp_f32_e32 v6, v6
	s_nop 0
	v_add_f32_e32 v6, 1.0, v6
	v_rcp_f32_e32 v6, v6
	s_nop 0
	v_fma_f32 v30, v2, v6, v4
	s_or_b32 s7, s45, s5
	v_readlane_b32 s5, v254, 22
	s_or_b32 s6, s45, s5
	v_readlane_b32 s5, v254, 23
	s_or_b32 s55, s45, s5
	v_readlane_b32 s5, v254, 24
	s_or_b32 s54, s45, s5
	v_readlane_b32 s5, v254, 25
	s_or_b32 s53, s45, s5
	v_readlane_b32 s5, v254, 26
	s_or_b32 s52, s45, s5
	v_readlane_b32 s5, v254, 27
	s_or_b32 s51, s45, s5
	v_readlane_b32 s5, v254, 28
	s_or_b32 s50, s45, s5
	v_readlane_b32 s5, v254, 29
	s_waitcnt vmcnt(22)
	v_lshlrev_b32_e32 v6, 16, v235
	v_mul_f32_e32 v6, 0xbfb8aa3b, v6
	v_exp_f32_e32 v6, v6
	s_nop 0
	v_add_f32_e32 v6, 1.0, v6
	v_rcp_f32_e32 v6, v6
	s_nop 0
	v_fma_f32 v29, v2, v6, v4
	s_waitcnt vmcnt(21)
	v_lshlrev_b32_e32 v6, 16, v236
	v_mul_f32_e32 v6, 0xbfb8aa3b, v6
	v_exp_f32_e32 v6, v6
	s_nop 0
	v_add_f32_e32 v6, 1.0, v6
	v_rcp_f32_e32 v6, v6
	s_nop 0
	v_fma_f32 v28, v2, v6, v4
	s_waitcnt vmcnt(20)
	v_lshlrev_b32_e32 v6, 16, v237
	v_mul_f32_e32 v6, 0xbfb8aa3b, v6
	v_exp_f32_e32 v6, v6
	s_nop 0
	v_add_f32_e32 v6, 1.0, v6
	v_rcp_f32_e32 v6, v6
	s_nop 0
	v_fma_f32 v27, v2, v6, v4
	s_waitcnt vmcnt(19)
	v_lshlrev_b32_e32 v6, 16, v238
	v_mul_f32_e32 v6, 0xbfb8aa3b, v6
	v_exp_f32_e32 v6, v6
	s_nop 0
	v_add_f32_e32 v6, 1.0, v6
	v_rcp_f32_e32 v6, v6
	s_nop 0
	v_fma_f32 v26, v2, v6, v4
	s_waitcnt vmcnt(18)
	v_lshlrev_b32_e32 v6, 16, v239
	v_mul_f32_e32 v6, 0xbfb8aa3b, v6
	v_exp_f32_e32 v6, v6
	s_nop 0
	v_add_f32_e32 v6, 1.0, v6
	v_rcp_f32_e32 v6, v6
	s_nop 0
	v_fma_f32 v25, v2, v6, v4
	s_waitcnt vmcnt(17)
	v_lshlrev_b32_e32 v6, 16, v240
	v_mul_f32_e32 v6, 0xbfb8aa3b, v6
	v_exp_f32_e32 v6, v6
	s_nop 0
	v_add_f32_e32 v6, 1.0, v6
	v_rcp_f32_e32 v6, v6
	s_nop 0
	v_fma_f32 v24, v2, v6, v4
	s_waitcnt vmcnt(16)
	v_lshlrev_b32_e32 v6, 16, v241
	v_mul_f32_e32 v6, 0xbfb8aa3b, v6
	v_exp_f32_e32 v6, v6
	s_nop 0
	v_add_f32_e32 v6, 1.0, v6
	v_rcp_f32_e32 v6, v6
	s_nop 0
	v_fma_f32 v23, v2, v6, v4
	s_waitcnt vmcnt(15)
	v_lshlrev_b32_e32 v6, 16, v242
	v_mul_f32_e32 v6, 0xbfb8aa3b, v6
	v_exp_f32_e32 v6, v6
	s_nop 0
	v_add_f32_e32 v6, 1.0, v6
	v_rcp_f32_e32 v6, v6
	s_nop 0
	v_fma_f32 v22, v2, v6, v4
	s_or_b32 s49, s45, s5
	v_readlane_b32 s5, v254, 30
	s_or_b32 s48, s45, s5
	v_readlane_b32 s5, v254, 31
	s_or_b32 s38, s45, s5
	v_readlane_b32 s5, v254, 32
	s_waitcnt vmcnt(14)
	v_lshlrev_b32_e32 v6, 16, v243
	v_mul_f32_e32 v6, 0xbfb8aa3b, v6
	v_exp_f32_e32 v6, v6
	s_nop 0
	v_add_f32_e32 v6, 1.0, v6
	v_rcp_f32_e32 v6, v6
	s_nop 0
	v_fma_f32 v21, v2, v6, v4
	s_waitcnt vmcnt(13)
; #define LAS __attribute__((address_space(3)))
; __device__ __forceinline__ float bf2f(unsigned v) { return __uint_as_float(v << 16); }
; __device__ __forceinline__ unsigned pk2(float lo, float hi) { const f32x2_t v = {lo, hi}; const bf16x2_t b = __builtin_convertvector(v, bf16x2_t); return __builtin_bit_cast(unsigned, b); }
; __device__ __forceinline__ unsigned f2bf(float f) { return pk2(f, 0.f) & 0xffffu; }
; __device__ __forceinline__ float sigmoidf_(float x) { return __builtin_amdgcn_rcpf(1.0f + __builtin_amdgcn_exp2f(-1.4426950408889634f * x)); }
; __device__ __forceinline__ void hgrn_out_phase(const Ctx& F, const Args& a, int l) {
;     ...
;             float fv[64]; float ref = 0.f;
; #pragma unroll
;             for (int t = 0; t < 64; ++t) {
;                 const float pre = bf2f(PB[(size_t)(rb + (dir ? 63 - t : t)) * INW + colf]);
;                 const float f = lb + (1.0f - lb) * sigmoidf_(pre);
;                 fv[t] = f;
;                 if (t < 32) ref += __logf(f);
;             }
;             unsigned qh[32]; float cum = 0.f, qh_prev = 0.f;
; #pragma unroll
;             for (int t = 0; t < 64; ++t) {
;                 const float qv = bf2f(PB[(size_t)(rb + (dir ? 63 - t : t)) * INW + colq]) * 0.125f;
;                 cum += __logf(fv[t]);
;                 const float qt = qv * __expf(fminf(cum - ref, 80.f));
;                 const float kt = (1.0f - fv[t]) * __expf(fminf(ref - cum, 80.f));
;                 const float qhv = qv * __expf(cum);
;                 *(LAS bf16_t*)(TQ + t * TP + 2 * lane) = (bf16_t)f2bf(qt);
;                 *(LAS bf16_t*)(TK + t * TP + 2 * lane) = (bf16_t)f2bf(kt);
;                 if (t & 1) qh[t >> 1] = pk2(qh_prev, qhv); else qh_prev = qhv;
	v_lshlrev_b32_e32 v6, 16, v244
	v_mul_f32_e32 v6, 0xbfb8aa3b, v6
	v_exp_f32_e32 v6, v6
	s_nop 0
	v_add_f32_e32 v6, 1.0, v6
	v_rcp_f32_e32 v6, v6
	s_nop 0
	v_fma_f32 v20, v2, v6, v4
	s_waitcnt vmcnt(12)
	v_lshlrev_b32_e32 v6, 16, v245
	v_mul_f32_e32 v6, 0xbfb8aa3b, v6
	v_exp_f32_e32 v6, v6
	s_nop 0
	v_add_f32_e32 v6, 1.0, v6
	v_rcp_f32_e32 v6, v6
	s_nop 0
	v_fma_f32 v19, v2, v6, v4
	s_or_b32 s81, s45, s5
	v_readlane_b32 s5, v254, 33
	s_or_b32 s80, s45, s5
	v_readlane_b32 s5, v254, 34
	s_or_b32 s95, s45, s5
	v_readlane_b32 s5, v254, 35
	s_or_b32 s94, s45, s5
	v_readlane_b32 s5, v254, 36
	s_or_b32 s93, s45, s5
	v_readlane_b32 s5, v254, 37
	s_or_b32 s92, s45, s5
	v_readlane_b32 s5, v254, 38
	s_or_b32 s91, s45, s5
	v_readlane_b32 s5, v254, 39
	s_or_b32 s90, s45, s5
	v_readlane_b32 s5, v254, 40
	s_or_b32 s89, s45, s5
	v_readlane_b32 s5, v254, 41
	s_or_b32 s88, s45, s5
	v_readlane_b32 s5, v254, 42
	s_waitcnt vmcnt(11)
	v_lshlrev_b32_e32 v6, 16, v246
	v_mul_f32_e32 v6, 0xbfb8aa3b, v6
	v_exp_f32_e32 v6, v6
	s_nop 0
	v_add_f32_e32 v6, 1.0, v6
	v_rcp_f32_e32 v6, v6
	s_nop 0
	v_fma_f32 v18, v2, v6, v4
	s_waitcnt vmcnt(10)
	v_lshlrev_b32_e32 v6, 16, v247
	v_mul_f32_e32 v6, 0xbfb8aa3b, v6
	v_exp_f32_e32 v6, v6
	s_nop 0
	v_add_f32_e32 v6, 1.0, v6
	v_rcp_f32_e32 v6, v6
	s_nop 0
	v_fma_f32 v17, v2, v6, v4
	s_waitcnt vmcnt(9)
	v_lshlrev_b32_e32 v6, 16, v222
	v_mul_f32_e32 v6, 0xbfb8aa3b, v6
	v_exp_f32_e32 v6, v6
	s_nop 0
	v_add_f32_e32 v6, 1.0, v6
	v_rcp_f32_e32 v6, v6
	s_nop 0
	v_fma_f32 v16, v2, v6, v4
	s_waitcnt vmcnt(8)
	v_lshlrev_b32_e32 v6, 16, v223
	v_mul_f32_e32 v6, 0xbfb8aa3b, v6
	v_exp_f32_e32 v6, v6
	s_nop 0
	v_add_f32_e32 v6, 1.0, v6
	v_rcp_f32_e32 v6, v6
	s_nop 0
	v_fma_f32 v15, v2, v6, v4
	s_waitcnt vmcnt(7)
	v_lshlrev_b32_e32 v6, 16, v224
	v_mul_f32_e32 v6, 0xbfb8aa3b, v6
	v_exp_f32_e32 v6, v6
	s_nop 0
	v_add_f32_e32 v6, 1.0, v6
	v_rcp_f32_e32 v6, v6
	s_nop 0
	v_fma_f32 v14, v2, v6, v4
	s_waitcnt vmcnt(6)
	v_lshlrev_b32_e32 v6, 16, v225
	v_mul_f32_e32 v6, 0xbfb8aa3b, v6
	v_exp_f32_e32 v6, v6
	s_nop 0
	v_add_f32_e32 v6, 1.0, v6
	v_rcp_f32_e32 v6, v6
	s_nop 0
	v_fma_f32 v13, v2, v6, v4
	s_waitcnt vmcnt(5)
	v_lshlrev_b32_e32 v6, 16, v226
	v_mul_f32_e32 v6, 0xbfb8aa3b, v6
	v_exp_f32_e32 v6, v6
	s_nop 0
	v_add_f32_e32 v6, 1.0, v6
	v_rcp_f32_e32 v6, v6
	s_nop 0
	v_fma_f32 v12, v2, v6, v4
	s_waitcnt vmcnt(4)
	v_lshlrev_b32_e32 v6, 16, v227
	v_mul_f32_e32 v6, 0xbfb8aa3b, v6
	v_exp_f32_e32 v6, v6
	s_nop 0
	v_add_f32_e32 v6, 1.0, v6
	v_rcp_f32_e32 v6, v6
	s_nop 0
	v_fma_f32 v11, v2, v6, v4
	s_waitcnt vmcnt(3)
	v_lshlrev_b32_e32 v6, 16, v228
	v_mul_f32_e32 v6, 0xbfb8aa3b, v6
	v_exp_f32_e32 v6, v6
	s_nop 0
	v_add_f32_e32 v6, 1.0, v6
	v_rcp_f32_e32 v6, v6
	s_nop 0
	v_fma_f32 v10, v2, v6, v4
	s_waitcnt vmcnt(2)
	v_lshlrev_b32_e32 v6, 16, v229
	v_mul_f32_e32 v6, 0xbfb8aa3b, v6
	v_exp_f32_e32 v6, v6
	s_nop 0
	v_add_f32_e32 v6, 1.0, v6
	v_rcp_f32_e32 v6, v6
	s_nop 0
	v_fma_f32 v9, v2, v6, v4
	s_or_b32 s87, s45, s5
	v_readlane_b32 s5, v254, 43
	s_or_b32 s86, s45, s5
	v_readlane_b32 s5, v254, 44
	v_mad_i64_i32 v[118:119], vcc, s86, v205, v[106:107]
	s_or_b32 s83, s45, s5
	s_waitcnt vmcnt(1)
	v_lshlrev_b32_e32 v6, 16, v230
	v_mul_f32_e32 v6, 0xbfb8aa3b, v6
	v_exp_f32_e32 v6, v6
	s_nop 0
	v_add_f32_e32 v6, 1.0, v6
	v_rcp_f32_e32 v6, v6
	s_nop 0
	v_fma_f32 v8, v2, v6, v4
	s_waitcnt vmcnt(0)
	v_lshlrev_b32_e32 v6, 16, v231
	v_mul_f32_e32 v6, 0xbfb8aa3b, v6
	v_exp_f32_e32 v6, v6
	s_nop 0
	v_add_f32_e32 v6, 1.0, v6
	v_rcp_f32_e32 v6, v6
	s_nop 0
	v_fma_f32 v7, v2, v6, v4
	global_load_ushort v6, v[118:119], off
	v_mad_i64_i32 v[118:119], vcc, s83, v205, v[106:107]
	global_load_ushort v118, v[118:119], off
	s_waitcnt vmcnt(1)
	v_lshlrev_b32_e32 v6, 16, v6
	v_mul_f32_e32 v6, 0xbfb8aa3b, v6
	v_exp_f32_e32 v6, v6
	s_waitcnt vmcnt(0)
	v_lshlrev_b32_e32 v118, 16, v118
	v_mul_f32_e32 v118, 0xbfb8aa3b, v118
	v_exp_f32_e32 v118, v118
	v_add_f32_e32 v6, 1.0, v6
	v_rcp_f32_e32 v6, v6
	v_add_f32_e32 v118, 1.0, v118
	v_rcp_f32_e32 v118, v118
	v_fma_f32 v6, v2, v6, v4
	v_fmac_f32_e32 v4, v2, v118
	v_sub_f32_e32 v2, v34, v5
	v_min_f32_e32 v2, 0x42a00000, v2
	v_mul_f32_e32 v2, 0x3fb8aa3b, v2
	v_exp_f32_e32 v120, v2
	v_sub_f32_e32 v2, 1.0, v3
	v_sub_f32_e32 v3, v5, v34
	v_min_f32_e32 v3, 0x42a00000, v3
	v_mul_f32_e32 v3, 0x3fb8aa3b, v3
	v_exp_f32_e32 v3, v3
	v_mad_i64_i32 v[118:119], vcc, s66, v205, v[108:109]
	v_cmp_gt_f32_e32 vcc, s35, v52
	v_mul_f32_e32 v3, v2, v3
	v_cvt_pk_bf16_f32 v3, v3, s0
	ds_write_b16 v126, v3 offset:9216
	v_sub_f32_e32 v3, v36, v5
	v_min_f32_e32 v3, 0x42a00000, v3
	v_mul_f32_e32 v3, 0x3fb8aa3b, v3
	v_exp_f32_e32 v121, v3
	v_sub_f32_e32 v3, 1.0, v35
	v_sub_f32_e32 v35, v5, v36
	v_min_f32_e32 v35, 0x42a00000, v35
	v_mul_f32_e32 v35, 0x3fb8aa3b, v35
	v_exp_f32_e32 v35, v35
	v_mul_f32_e32 v2, 0x3fb8aa3b, v34
	global_load_ushort v34, v[118:119], off offset:1024
	v_mad_i64_i32 v[118:119], s[66:67], s67, v205, v[108:109]
	v_mul_f32_e32 v3, v3, v35
	global_load_ushort v35, v[118:119], off offset:1024
	v_cvt_pk_bf16_f32 v3, v3, s0
	ds_write_b16 v126, v3 offset:9360
	v_mul_f32_e32 v3, 0x3fb8aa3b, v36
	v_exp_f32_e32 v2, v2
	v_exp_f32_e32 v3, v3
	v_mad_i64_i32 v[118:119], s[66:67], s69, v205, v[108:109]
	s_waitcnt vmcnt(1)
	v_lshlrev_b32_e32 v34, 16, v34
	s_waitcnt vmcnt(0)
; #define LAS __attribute__((address_space(3)))
; __device__ __forceinline__ float bf2f(unsigned v) { return __uint_as_float(v << 16); }
; __device__ __forceinline__ unsigned pk2(float lo, float hi) { const f32x2_t v = {lo, hi}; const bf16x2_t b = __builtin_convertvector(v, bf16x2_t); return __builtin_bit_cast(unsigned, b); }
; __device__ __forceinline__ unsigned f2bf(float f) { return pk2(f, 0.f) & 0xffffu; }
; __device__ __forceinline__ void hgrn_out_phase(const Ctx& F, const Args& a, int l) {
;     ...
; #pragma unroll
;             for (int t = 0; t < 64; ++t) {
;                 const float qv = bf2f(PB[(size_t)(rb + (dir ? 63 - t : t)) * INW + colq]) * 0.125f;
;                 cum += __logf(fv[t]);
;                 const float qt = qv * __expf(fminf(cum - ref, 80.f));
;                 const float kt = (1.0f - fv[t]) * __expf(fminf(ref - cum, 80.f));
;                 const float qhv = qv * __expf(cum);
;                 *(LAS bf16_t*)(TQ + t * TP + 2 * lane) = (bf16_t)f2bf(qt);
;                 *(LAS bf16_t*)(TK + t * TP + 2 * lane) = (bf16_t)f2bf(kt);
;                 if (t & 1) qh[t >> 1] = pk2(qh_prev, qhv); else qh_prev = qhv;
;             }
	v_lshlrev_b32_e32 v35, 16, v35
	v_pk_mul_f32 v[34:35], v[34:35], s[8:9] op_sel_hi:[1,0]
	s_nop 0
	v_mul_f32_e32 v36, v120, v34
	v_cvt_pk_bf16_f32 v36, v36, s0
	ds_write_b16 v126, v36
	v_mul_f32_e32 v36, v121, v35
	v_cvt_pk_bf16_f32 v36, v36, s0
	ds_write_b16 v126, v36 offset:144
	v_sub_f32_e32 v36, 1.0, v37
	v_sub_f32_e32 v37, v5, v38
	v_min_f32_e32 v37, 0x42a00000, v37
	v_mul_f32_e32 v37, 0x3fb8aa3b, v37
	v_exp_f32_e32 v37, v37
	v_pk_mul_f32 v[2:3], v[2:3], v[34:35]
	v_sub_f32_e32 v35, v38, v5
	v_cvt_pk_bf16_f32 v34, v2, v3
	v_mul_f32_e32 v37, v36, v37
	v_cvt_pk_bf16_f32 v37, v37, s0
	ds_write_b16 v126, v37 offset:9504
	v_sub_f32_e32 v37, v40, v5
	v_min_f32_e32 v37, 0x42a00000, v37
	v_mul_f32_e32 v37, 0x3fb8aa3b, v37
	v_mul_f32_e32 v36, 0x3fb8aa3b, v38
	v_exp_f32_e32 v38, v37
	v_sub_f32_e32 v37, 1.0, v39
	v_sub_f32_e32 v39, v5, v40
	v_min_f32_e32 v39, 0x42a00000, v39
	v_mul_f32_e32 v39, 0x3fb8aa3b, v39
	v_exp_f32_e32 v39, v39
	v_mad_i64_i32 v[2:3], s[66:67], s68, v205, v[108:109]
	v_min_f32_e32 v35, 0x42a00000, v35
	v_mul_f32_e32 v37, v37, v39
	v_cvt_pk_bf16_f32 v37, v37, s0
	ds_write_b16 v126, v37 offset:9648
	global_load_ushort v2, v[2:3], off offset:1024
	s_nop 0
	global_load_ushort v3, v[118:119], off offset:1024
	v_mul_f32_e32 v35, 0x3fb8aa3b, v35
	v_exp_f32_e32 v35, v35
	v_mul_f32_e32 v37, 0x3fb8aa3b, v40
	v_exp_f32_e32 v36, v36
	v_exp_f32_e32 v37, v37
	s_waitcnt vmcnt(1)
	v_lshlrev_b32_e32 v2, 16, v2
	s_waitcnt vmcnt(0)
	v_lshlrev_b32_e32 v3, 16, v3
	v_pk_mul_f32 v[2:3], v[2:3], s[8:9] op_sel_hi:[1,0]
	s_nop 0
	v_mul_f32_e32 v35, v35, v2
	v_cvt_pk_bf16_f32 v35, v35, s0
	ds_write_b16 v126, v35 offset:288
	v_mul_f32_e32 v35, v38, v3
	v_pk_mul_f32 v[2:3], v[36:37], v[2:3]
	v_sub_f32_e32 v37, v5, v42
	v_min_f32_e32 v37, 0x42a00000, v37
	v_mul_f32_e32 v37, 0x3fb8aa3b, v37
	v_sub_f32_e32 v36, v42, v5
	v_exp_f32_e32 v37, v37
	v_min_f32_e32 v36, 0x42a00000, v36
	v_mul_f32_e32 v36, 0x3fb8aa3b, v36
	v_exp_f32_e32 v40, v36
	v_sub_f32_e32 v36, 1.0, v41
	v_mul_f32_e32 v37, v36, v37
	v_mul_f32_e32 v36, 0x3fb8aa3b, v42
	v_sub_f32_e32 v42, v5, v44
	v_min_f32_e32 v42, 0x42a00000, v42
	v_cvt_pk_bf16_f32 v37, v37, s0
	v_mul_f32_e32 v42, 0x3fb8aa3b, v42
	ds_write_b16 v126, v37 offset:9792
	v_sub_f32_e32 v37, v44, v5
	v_exp_f32_e32 v42, v42
	v_min_f32_e32 v37, 0x42a00000, v37
	v_mul_f32_e32 v37, 0x3fb8aa3b, v37
	v_exp_f32_e32 v41, v37
	v_sub_f32_e32 v37, 1.0, v43
	v_mul_f32_e32 v37, v37, v42
	v_cvt_pk_bf16_f32 v35, v35, s0
	v_cvt_pk_bf16_f32 v37, v37, s0
	ds_write_b16 v126, v35 offset:432
	v_cvt_pk_bf16_f32 v35, v2, v3
	v_mad_i64_i32 v[2:3], s[66:67], s70, v205, v[108:109]
	ds_write_b16 v126, v37 offset:9936
	v_mad_i64_i32 v[38:39], s[66:67], s71, v205, v[108:109]
	global_load_ushort v2, v[2:3], off offset:1024
	s_nop 0
	global_load_ushort v3, v[38:39], off offset:1024
	v_sub_f32_e32 v39, v5, v46
	v_min_f32_e32 v39, 0x42a00000, v39
	v_mul_f32_e32 v39, 0x3fb8aa3b, v39
	v_exp_f32_e32 v39, v39
	v_sub_f32_e32 v43, v5, v49
	v_min_f32_e32 v43, 0x42a00000, v43
	v_mul_f32_e32 v43, 0x3fb8aa3b, v43
	v_mul_f32_e32 v37, 0x3fb8aa3b, v44
	v_exp_f32_e32 v43, v43
	v_exp_f32_e32 v36, v36
	v_exp_f32_e32 v37, v37
	v_sub_f32_e32 v44, v5, v55
	v_min_f32_e32 v44, 0x42a00000, v44
	v_mul_f32_e32 v44, 0x3fb8aa3b, v44
	v_exp_f32_e32 v44, v44
	s_waitcnt vmcnt(1)
	v_lshlrev_b32_e32 v2, 16, v2
	s_waitcnt vmcnt(0)
	v_lshlrev_b32_e32 v3, 16, v3
	v_pk_mul_f32 v[2:3], v[2:3], s[8:9] op_sel_hi:[1,0]
	s_nop 0
	v_mul_f32_e32 v38, v40, v2
	v_cvt_pk_bf16_f32 v38, v38, s0
	ds_write_b16 v126, v38 offset:576
	v_mul_f32_e32 v38, v41, v3
	v_cvt_pk_bf16_f32 v38, v38, s0
	ds_write_b16 v126, v38 offset:720
	v_sub_f32_e32 v38, 1.0, v45
	v_mul_f32_e32 v39, v38, v39
	v_cvt_pk_bf16_f32 v39, v39, s0
	ds_write_b16 v126, v39 offset:10080
	v_sub_f32_e32 v39, v49, v5
	v_min_f32_e32 v39, 0x42a00000, v39
	v_mul_f32_e32 v39, 0x3fb8aa3b, v39
	v_exp_f32_e32 v42, v39
	v_sub_f32_e32 v39, 1.0, v47
	v_mul_f32_e32 v39, v39, v43
	v_pk_mul_f32 v[2:3], v[36:37], v[2:3]
	v_cvt_pk_bf16_f32 v39, v39, s0
	v_cvt_pk_bf16_f32 v36, v2, v3
	v_mad_i64_i32 v[2:3], s[66:67], s72, v205, v[108:109]
	ds_write_b16 v126, v39 offset:10224
	v_mad_i64_i32 v[40:41], s[66:67], s73, v205, v[108:109]
	global_load_ushort v2, v[2:3], off offset:1024
	s_nop 0
	global_load_ushort v3, v[40:41], off offset:1024
	v_sub_f32_e32 v37, v46, v5
	v_min_f32_e32 v37, 0x42a00000, v37
	v_mul_f32_e32 v37, 0x3fb8aa3b, v37
	v_exp_f32_e32 v37, v37
	v_mul_f32_e32 v38, 0x3fb8aa3b, v46
	v_mul_f32_e32 v39, 0x3fb8aa3b, v49
	v_exp_f32_e32 v38, v38
	v_exp_f32_e32 v39, v39
	v_mad_i64_i32 v[40:41], s[66:67], s75, v205, v[108:109]
	v_sub_f32_e32 v45, v5, v59
	v_min_f32_e32 v45, 0x42a00000, v45
	v_mul_f32_e32 v45, 0x3fb8aa3b, v45
	v_exp_f32_e32 v45, v45
	v_sub_f32_e32 v46, v5, v63
	v_min_f32_e32 v46, 0x42a00000, v46
	v_mul_f32_e32 v46, 0x3fb8aa3b, v46
	v_exp_f32_e32 v46, v46
	v_sub_f32_e32 v47, v5, v68
	v_min_f32_e32 v47, 0x42a00000, v47
	v_mul_f32_e32 v47, 0x3fb8aa3b, v47
	v_exp_f32_e32 v47, v47
	v_sub_f32_e32 v49, v5, v79
	v_min_f32_e32 v49, 0x42a00000, v49
	v_mul_f32_e32 v49, 0x3fb8aa3b, v49
	v_exp_f32_e32 v49, v49
	s_waitcnt vmcnt(1)
	v_lshlrev_b32_e32 v2, 16, v2
	s_waitcnt vmcnt(0)
; #define LAS __attribute__((address_space(3)))
; __device__ __forceinline__ float bf2f(unsigned v) { return __uint_as_float(v << 16); }
; __device__ __forceinline__ unsigned pk2(float lo, float hi) { const f32x2_t v = {lo, hi}; const bf16x2_t b = __builtin_convertvector(v, bf16x2_t); return __builtin_bit_cast(unsigned, b); }
; __device__ __forceinline__ unsigned f2bf(float f) { return pk2(f, 0.f) & 0xffffu; }
; __device__ __forceinline__ void hgrn_out_phase(const Ctx& F, const Args& a, int l) {
;     ...
; #pragma unroll
;             for (int t = 0; t < 64; ++t) {
;                 const float qv = bf2f(PB[(size_t)(rb + (dir ? 63 - t : t)) * INW + colq]) * 0.125f;
;                 cum += __logf(fv[t]);
;                 const float qt = qv * __expf(fminf(cum - ref, 80.f));
;                 const float kt = (1.0f - fv[t]) * __expf(fminf(ref - cum, 80.f));
;                 const float qhv = qv * __expf(cum);
;                 *(LAS bf16_t*)(TQ + t * TP + 2 * lane) = (bf16_t)f2bf(qt);
;                 *(LAS bf16_t*)(TK + t * TP + 2 * lane) = (bf16_t)f2bf(kt);
;                 if (t & 1) qh[t >> 1] = pk2(qh_prev, qhv); else qh_prev = qhv;
;             }
	v_lshlrev_b32_e32 v3, 16, v3
	v_pk_mul_f32 v[2:3], v[2:3], s[8:9] op_sel_hi:[1,0]
	s_nop 0
	v_mul_f32_e32 v37, v37, v2
	v_cvt_pk_bf16_f32 v37, v37, s0
	ds_write_b16 v126, v37 offset:864
	v_mul_f32_e32 v37, v42, v3
	v_pk_mul_f32 v[2:3], v[38:39], v[2:3]
	v_sub_f32_e32 v39, v5, v53
	v_min_f32_e32 v39, 0x42a00000, v39
	v_mul_f32_e32 v39, 0x3fb8aa3b, v39
	v_sub_f32_e32 v38, v53, v5
	v_exp_f32_e32 v39, v39
	v_min_f32_e32 v38, 0x42a00000, v38
	v_mul_f32_e32 v38, 0x3fb8aa3b, v38
	v_exp_f32_e32 v42, v38
	v_sub_f32_e32 v38, 1.0, v48
	v_mul_f32_e32 v39, v38, v39
	v_cvt_pk_bf16_f32 v39, v39, s0
	ds_write_b16 v126, v39 offset:10368
	v_sub_f32_e32 v39, v55, v5
	v_min_f32_e32 v39, 0x42a00000, v39
	v_mul_f32_e32 v39, 0x3fb8aa3b, v39
	v_exp_f32_e32 v43, v39
	v_sub_f32_e32 v39, 1.0, v54
	v_mul_f32_e32 v39, v39, v44
	v_cvt_pk_bf16_f32 v37, v37, s0
	v_cvt_pk_bf16_f32 v39, v39, s0
	ds_write_b16 v126, v37 offset:1008
	v_cvt_pk_bf16_f32 v37, v2, v3
	v_mad_i64_i32 v[2:3], s[66:67], s74, v205, v[108:109]
	ds_write_b16 v126, v39 offset:10512
	global_load_ushort v2, v[2:3], off offset:1024
	s_nop 0
	global_load_ushort v3, v[40:41], off offset:1024
	v_sub_f32_e32 v41, v5, v57
	v_min_f32_e32 v41, 0x42a00000, v41
	v_mul_f32_e32 v41, 0x3fb8aa3b, v41
	v_exp_f32_e32 v41, v41
	v_mul_f32_e32 v38, 0x3fb8aa3b, v53
	v_mul_f32_e32 v39, 0x3fb8aa3b, v55
	v_exp_f32_e32 v38, v38
	v_exp_f32_e32 v39, v39
	v_sub_f32_e32 v48, v5, v71
	v_min_f32_e32 v48, 0x42a00000, v48
	v_mul_f32_e32 v48, 0x3fb8aa3b, v48
	v_exp_f32_e32 v48, v48
	v_sub_f32_e32 v53, v5, v83
	v_min_f32_e32 v53, 0x42a00000, v53
	v_mul_f32_e32 v53, 0x3fb8aa3b, v53
	v_exp_f32_e32 v53, v53
	v_sub_f32_e32 v54, v5, v87
	v_min_f32_e32 v54, 0x42a00000, v54
	v_mul_f32_e32 v54, 0x3fb8aa3b, v54
	v_exp_f32_e32 v54, v54
	v_sub_f32_e32 v55, v5, v91
	v_min_f32_e32 v55, 0x42a00000, v55
	v_mul_f32_e32 v55, 0x3fb8aa3b, v55
	v_exp_f32_e32 v55, v55
	s_waitcnt vmcnt(1)
	v_lshlrev_b32_e32 v2, 16, v2
	s_waitcnt vmcnt(0)
	v_lshlrev_b32_e32 v3, 16, v3
	v_pk_mul_f32 v[2:3], v[2:3], s[8:9] op_sel_hi:[1,0]
	s_nop 0
	v_mul_f32_e32 v40, v42, v2
	v_cvt_pk_bf16_f32 v40, v40, s0
	ds_write_b16 v126, v40 offset:1152
	v_mul_f32_e32 v40, v43, v3
	v_cvt_pk_bf16_f32 v40, v40, s0
	ds_write_b16 v126, v40 offset:1296
	v_sub_f32_e32 v40, 1.0, v56
	v_mul_f32_e32 v41, v40, v41
	v_cvt_pk_bf16_f32 v41, v41, s0
	ds_write_b16 v126, v41 offset:10656
	v_sub_f32_e32 v41, v59, v5
	v_min_f32_e32 v41, 0x42a00000, v41
	v_mul_f32_e32 v41, 0x3fb8aa3b, v41
	v_exp_f32_e32 v44, v41
	v_sub_f32_e32 v41, 1.0, v58
	v_mul_f32_e32 v41, v41, v45
	v_pk_mul_f32 v[2:3], v[38:39], v[2:3]
	v_cvt_pk_bf16_f32 v41, v41, s0
	v_cvt_pk_bf16_f32 v38, v2, v3
	v_mad_i64_i32 v[2:3], s[66:67], s76, v205, v[108:109]
	ds_write_b16 v126, v41 offset:10800
	v_mad_i64_i32 v[42:43], s[66:67], s77, v205, v[108:109]
	global_load_ushort v2, v[2:3], off offset:1024
	s_nop 0
	global_load_ushort v3, v[42:43], off offset:1024
	v_sub_f32_e32 v39, v57, v5
	v_min_f32_e32 v39, 0x42a00000, v39
	v_mul_f32_e32 v39, 0x3fb8aa3b, v39
	v_exp_f32_e32 v39, v39
	v_mul_f32_e32 v40, 0x3fb8aa3b, v57
	v_mul_f32_e32 v41, 0x3fb8aa3b, v59
	v_exp_f32_e32 v40, v40
	v_exp_f32_e32 v41, v41
	v_mad_i64_i32 v[42:43], s[66:67], s79, v205, v[108:109]
	v_sub_f32_e32 v56, v5, v95
	v_min_f32_e32 v56, 0x42a00000, v56
	v_mul_f32_e32 v56, 0x3fb8aa3b, v56
	v_exp_f32_e32 v56, v56
	s_waitcnt vmcnt(1)
	v_lshlrev_b32_e32 v2, 16, v2
	s_waitcnt vmcnt(0)
	v_lshlrev_b32_e32 v3, 16, v3
	v_pk_mul_f32 v[2:3], v[2:3], s[8:9] op_sel_hi:[1,0]
	s_nop 0
	v_mul_f32_e32 v39, v39, v2
	v_cvt_pk_bf16_f32 v39, v39, s0
	ds_write_b16 v126, v39 offset:1440
	v_mul_f32_e32 v39, v44, v3
	v_pk_mul_f32 v[2:3], v[40:41], v[2:3]
	v_sub_f32_e32 v41, v5, v61
	v_min_f32_e32 v41, 0x42a00000, v41
	v_mul_f32_e32 v41, 0x3fb8aa3b, v41
	v_sub_f32_e32 v40, v61, v5
	v_exp_f32_e32 v41, v41
	v_min_f32_e32 v40, 0x42a00000, v40
	v_mul_f32_e32 v40, 0x3fb8aa3b, v40
	v_exp_f32_e32 v44, v40
	v_sub_f32_e32 v40, 1.0, v60
	v_mul_f32_e32 v41, v40, v41
	v_cvt_pk_bf16_f32 v41, v41, s0
	ds_write_b16 v126, v41 offset:10944
	v_sub_f32_e32 v41, v63, v5
	v_min_f32_e32 v41, 0x42a00000, v41
	v_mul_f32_e32 v41, 0x3fb8aa3b, v41
	v_exp_f32_e32 v45, v41
	v_sub_f32_e32 v41, 1.0, v62
	v_mul_f32_e32 v41, v41, v46
	v_cvt_pk_bf16_f32 v39, v39, s0
	v_cvt_pk_bf16_f32 v41, v41, s0
	ds_write_b16 v126, v39 offset:1584
	v_cvt_pk_bf16_f32 v39, v2, v3
	v_mad_i64_i32 v[2:3], s[66:67], s78, v205, v[108:109]
	ds_write_b16 v126, v41 offset:11088
	global_load_ushort v2, v[2:3], off offset:1024
	s_nop 0
	global_load_ushort v3, v[42:43], off offset:1024
	v_sub_f32_e32 v43, v5, v65
	v_min_f32_e32 v43, 0x42a00000, v43
	v_mul_f32_e32 v43, 0x3fb8aa3b, v43
	v_exp_f32_e32 v43, v43
	v_mul_f32_e32 v40, 0x3fb8aa3b, v61
	v_mul_f32_e32 v41, 0x3fb8aa3b, v63
	v_exp_f32_e32 v40, v40
	v_exp_f32_e32 v41, v41
	s_waitcnt vmcnt(1)
	v_lshlrev_b32_e32 v2, 16, v2
	s_waitcnt vmcnt(0)
	v_lshlrev_b32_e32 v3, 16, v3
	v_pk_mul_f32 v[2:3], v[2:3], s[8:9] op_sel_hi:[1,0]
	s_nop 0
	v_mul_f32_e32 v42, v44, v2
	v_cvt_pk_bf16_f32 v42, v42, s0
	ds_write_b16 v126, v42 offset:1728
	v_mul_f32_e32 v42, v45, v3
	v_cvt_pk_bf16_f32 v42, v42, s0
	ds_write_b16 v126, v42 offset:1872
	v_sub_f32_e32 v42, 1.0, v64
	v_mul_f32_e32 v43, v42, v43
	v_cvt_pk_bf16_f32 v43, v43, s0
	ds_write_b16 v126, v43 offset:11232
	v_sub_f32_e32 v43, v68, v5
	v_min_f32_e32 v43, 0x42a00000, v43
	v_mul_f32_e32 v43, 0x3fb8aa3b, v43
	v_exp_f32_e32 v46, v43
	v_sub_f32_e32 v43, 1.0, v66
	v_mul_f32_e32 v43, v43, v47
	v_pk_mul_f32 v[2:3], v[40:41], v[2:3]
	v_cvt_pk_bf16_f32 v43, v43, s0
	v_cvt_pk_bf16_f32 v40, v2, v3
	v_mad_i64_i32 v[2:3], s[66:67], s46, v205, v[108:109]
	ds_write_b16 v126, v43 offset:11376
	v_mad_i64_i32 v[44:45], s[46:47], s47, v205, v[108:109]
	global_load_ushort v2, v[2:3], off offset:1024
	s_nop 0
	global_load_ushort v3, v[44:45], off offset:1024
	v_sub_f32_e32 v41, v65, v5
	v_min_f32_e32 v41, 0x42a00000, v41
	v_mul_f32_e32 v41, 0x3fb8aa3b, v41
	v_exp_f32_e32 v41, v41
	v_mul_f32_e32 v42, 0x3fb8aa3b, v65
	v_mul_f32_e32 v43, 0x3fb8aa3b, v68
	v_exp_f32_e32 v42, v42
	v_exp_f32_e32 v43, v43
	v_mad_i64_i32 v[44:45], s[46:47], s97, v205, v[108:109]
	s_waitcnt vmcnt(1)
; #define LAS __attribute__((address_space(3)))
; __device__ __forceinline__ float bf2f(unsigned v) { return __uint_as_float(v << 16); }
; __device__ __forceinline__ unsigned pk2(float lo, float hi) { const f32x2_t v = {lo, hi}; const bf16x2_t b = __builtin_convertvector(v, bf16x2_t); return __builtin_bit_cast(unsigned, b); }
; __device__ __forceinline__ unsigned f2bf(float f) { return pk2(f, 0.f) & 0xffffu; }
; __device__ __forceinline__ void hgrn_out_phase(const Ctx& F, const Args& a, int l) {
;     ...
; #pragma unroll
;             for (int t = 0; t < 64; ++t) {
;                 const float qv = bf2f(PB[(size_t)(rb + (dir ? 63 - t : t)) * INW + colq]) * 0.125f;
;                 cum += __logf(fv[t]);
;                 const float qt = qv * __expf(fminf(cum - ref, 80.f));
;                 const float kt = (1.0f - fv[t]) * __expf(fminf(ref - cum, 80.f));
;                 const float qhv = qv * __expf(cum);
;                 *(LAS bf16_t*)(TQ + t * TP + 2 * lane) = (bf16_t)f2bf(qt);
;                 *(LAS bf16_t*)(TK + t * TP + 2 * lane) = (bf16_t)f2bf(kt);
;                 if (t & 1) qh[t >> 1] = pk2(qh_prev, qhv); else qh_prev = qhv;
;             }
	v_lshlrev_b32_e32 v2, 16, v2
	s_waitcnt vmcnt(0)
	v_lshlrev_b32_e32 v3, 16, v3
	v_pk_mul_f32 v[2:3], v[2:3], s[8:9] op_sel_hi:[1,0]
	s_nop 0
	v_mul_f32_e32 v41, v41, v2
	v_cvt_pk_bf16_f32 v41, v41, s0
	ds_write_b16 v126, v41 offset:2016
	v_mul_f32_e32 v41, v46, v3
	v_pk_mul_f32 v[2:3], v[42:43], v[2:3]
	v_sub_f32_e32 v43, v5, v69
	v_min_f32_e32 v43, 0x42a00000, v43
	v_mul_f32_e32 v43, 0x3fb8aa3b, v43
	v_sub_f32_e32 v42, v69, v5
	v_exp_f32_e32 v43, v43
	v_min_f32_e32 v42, 0x42a00000, v42
	v_mul_f32_e32 v42, 0x3fb8aa3b, v42
	v_exp_f32_e32 v46, v42
	v_sub_f32_e32 v42, 1.0, v67
	v_mul_f32_e32 v43, v42, v43
	v_cvt_pk_bf16_f32 v43, v43, s0
	ds_write_b16 v126, v43 offset:11520
	v_sub_f32_e32 v43, v71, v5
	v_min_f32_e32 v43, 0x42a00000, v43
	v_mul_f32_e32 v43, 0x3fb8aa3b, v43
	v_exp_f32_e32 v47, v43
	v_sub_f32_e32 v43, 1.0, v70
	v_mul_f32_e32 v43, v43, v48
	v_cvt_pk_bf16_f32 v41, v41, s0
	v_cvt_pk_bf16_f32 v43, v43, s0
	ds_write_b16 v126, v41 offset:2160
	v_cvt_pk_bf16_f32 v41, v2, v3
	v_mad_i64_i32 v[2:3], s[46:47], s56, v205, v[108:109]
	ds_write_b16 v126, v43 offset:11664
	global_load_ushort v2, v[2:3], off offset:1024
	s_nop 0
	global_load_ushort v3, v[44:45], off offset:1024
	v_mul_f32_e32 v42, 0x3fb8aa3b, v69
	v_mul_f32_e32 v43, 0x3fb8aa3b, v71
	v_exp_f32_e32 v42, v42
	v_exp_f32_e32 v43, v43
	v_sub_f32_e32 v45, v5, v73
	v_min_f32_e32 v45, 0x42a00000, v45
	v_mul_f32_e32 v45, 0x3fb8aa3b, v45
	v_exp_f32_e32 v45, v45
	v_sub_f32_e32 v48, v5, v75
	v_min_f32_e32 v48, 0x42a00000, v48
	v_mul_f32_e32 v48, 0x3fb8aa3b, v48
	v_exp_f32_e32 v48, v48
	s_waitcnt vmcnt(1)
	v_lshlrev_b32_e32 v2, 16, v2
	s_waitcnt vmcnt(0)
	v_lshlrev_b32_e32 v3, 16, v3
	v_pk_mul_f32 v[2:3], v[2:3], s[8:9] op_sel_hi:[1,0]
	s_nop 0
	v_mul_f32_e32 v44, v46, v2
	v_cvt_pk_bf16_f32 v44, v44, s0
	ds_write_b16 v126, v44 offset:2304
	v_mul_f32_e32 v44, v47, v3
	v_pk_mul_f32 v[2:3], v[42:43], v[2:3]
	v_cvt_pk_bf16_f32 v44, v44, s0
	v_cvt_pk_bf16_f32 v42, v2, v3
	v_mad_i64_i32 v[2:3], s[46:47], s33, v205, v[108:109]
	global_load_ushort v46, v[2:3], off offset:1024
	v_mad_i64_i32 v[2:3], s[46:47], s28, v205, v[108:109]
	global_load_ushort v3, v[2:3], off offset:1024
	ds_write_b16 v126, v44 offset:2448
	v_sub_f32_e32 v44, 1.0, v72
	v_mul_f32_e32 v45, v44, v45
	v_cvt_pk_bf16_f32 v45, v45, s0
	ds_write_b16 v126, v45 offset:11808
	v_sub_f32_e32 v45, v75, v5
	v_sub_f32_e32 v43, v73, v5
	v_min_f32_e32 v45, 0x42a00000, v45
	v_min_f32_e32 v43, 0x42a00000, v43
	v_mul_f32_e32 v45, 0x3fb8aa3b, v45
	v_mul_f32_e32 v43, 0x3fb8aa3b, v43
	v_exp_f32_e32 v47, v45
	v_sub_f32_e32 v45, 1.0, v74
	v_exp_f32_e32 v43, v43
	v_mul_f32_e32 v45, v45, v48
	v_cvt_pk_bf16_f32 v45, v45, s0
	v_mul_f32_e32 v2, 0x3fb8aa3b, v75
	v_mul_f32_e32 v44, 0x3fb8aa3b, v73
	ds_write_b16 v126, v45 offset:11952
	v_exp_f32_e32 v45, v2
	v_exp_f32_e32 v44, v44
	s_waitcnt vmcnt(1)
	v_lshlrev_b32_e32 v2, 16, v46
	s_waitcnt vmcnt(0)
	v_lshlrev_b32_e32 v3, 16, v3
	v_pk_mul_f32 v[2:3], v[2:3], s[8:9] op_sel_hi:[1,0]
	s_nop 0
	v_mul_f32_e32 v43, v43, v2
	v_cvt_pk_bf16_f32 v43, v43, s0
	ds_write_b16 v126, v43 offset:2592
	v_mul_f32_e32 v43, v47, v3
	v_cvt_pk_bf16_f32 v43, v43, s0
	v_pk_mul_f32 v[2:3], v[44:45], v[2:3]
	ds_write_b16 v126, v43 offset:2736
	v_cvt_pk_bf16_f32 v43, v2, v3
	v_mad_i64_i32 v[2:3], s[28:29], s29, v205, v[108:109]
	global_load_ushort v47, v[2:3], off offset:1024
	v_mad_i64_i32 v[2:3], s[28:29], s36, v205, v[108:109]
	global_load_ushort v3, v[2:3], off offset:1024
	v_sub_f32_e32 v45, v5, v77
	v_min_f32_e32 v45, 0x42a00000, v45
	v_mul_f32_e32 v45, 0x3fb8aa3b, v45
	v_sub_f32_e32 v44, v77, v5
	v_exp_f32_e32 v45, v45
	v_min_f32_e32 v44, 0x42a00000, v44
	v_mul_f32_e32 v44, 0x3fb8aa3b, v44
	v_exp_f32_e32 v46, v44
	v_sub_f32_e32 v44, 1.0, v76
	v_mul_f32_e32 v45, v44, v45
	v_cvt_pk_bf16_f32 v45, v45, s0
	ds_write_b16 v126, v45 offset:12096
	v_sub_f32_e32 v45, v79, v5
	v_min_f32_e32 v45, 0x42a00000, v45
	v_mul_f32_e32 v45, 0x3fb8aa3b, v45
	v_exp_f32_e32 v48, v45
	v_sub_f32_e32 v45, 1.0, v78
	v_mul_f32_e32 v45, v45, v49
	v_mul_f32_e32 v44, 0x3fb8aa3b, v77
	v_cvt_pk_bf16_f32 v45, v45, s0
	v_mul_f32_e32 v2, 0x3fb8aa3b, v79
	v_exp_f32_e32 v44, v44
	ds_write_b16 v126, v45 offset:12240
	v_exp_f32_e32 v45, v2
	s_waitcnt vmcnt(1)
	v_lshlrev_b32_e32 v2, 16, v47
	v_sub_f32_e32 v47, v5, v81
	v_min_f32_e32 v47, 0x42a00000, v47
	s_waitcnt vmcnt(0)
	v_lshlrev_b32_e32 v3, 16, v3
	v_pk_mul_f32 v[2:3], v[2:3], s[8:9] op_sel_hi:[1,0]
	v_mul_f32_e32 v47, 0x3fb8aa3b, v47
	v_mul_f32_e32 v46, v46, v2
	v_cvt_pk_bf16_f32 v46, v46, s0
	ds_write_b16 v126, v46 offset:2880
	v_mul_f32_e32 v46, v48, v3
	v_pk_mul_f32 v[2:3], v[44:45], v[2:3]
	v_exp_f32_e32 v47, v47
	v_cvt_pk_bf16_f32 v44, v2, v3
	v_mad_i64_i32 v[2:3], s[28:29], s37, v205, v[108:109]
	global_load_ushort v48, v[2:3], off offset:1024
	v_mad_i64_i32 v[2:3], s[28:29], s26, v205, v[108:109]
	global_load_ushort v3, v[2:3], off offset:1024
	v_cvt_pk_bf16_f32 v46, v46, s0
	ds_write_b16 v126, v46 offset:3024
	v_sub_f32_e32 v46, 1.0, v80
	v_mul_f32_e32 v47, v46, v47
	v_cvt_pk_bf16_f32 v47, v47, s0
	ds_write_b16 v126, v47 offset:12384
	v_sub_f32_e32 v47, v83, v5
	v_sub_f32_e32 v45, v81, v5
	v_min_f32_e32 v47, 0x42a00000, v47
	v_min_f32_e32 v45, 0x42a00000, v45
	v_mul_f32_e32 v47, 0x3fb8aa3b, v47
	v_mul_f32_e32 v45, 0x3fb8aa3b, v45
	v_exp_f32_e32 v49, v47
	v_sub_f32_e32 v47, 1.0, v82
	v_exp_f32_e32 v45, v45
	v_mul_f32_e32 v47, v47, v53
	v_cvt_pk_bf16_f32 v47, v47, s0
	v_mul_f32_e32 v2, 0x3fb8aa3b, v83
	v_mul_f32_e32 v46, 0x3fb8aa3b, v81
	ds_write_b16 v126, v47 offset:12528
	v_exp_f32_e32 v47, v2
	v_exp_f32_e32 v46, v46
	s_waitcnt vmcnt(1)
	v_lshlrev_b32_e32 v2, 16, v48
	s_waitcnt vmcnt(0)
; #define LAS __attribute__((address_space(3)))
; __device__ __forceinline__ float bf2f(unsigned v) { return __uint_as_float(v << 16); }
; __device__ __forceinline__ unsigned pk2(float lo, float hi) { const f32x2_t v = {lo, hi}; const bf16x2_t b = __builtin_convertvector(v, bf16x2_t); return __builtin_bit_cast(unsigned, b); }
; __device__ __forceinline__ unsigned f2bf(float f) { return pk2(f, 0.f) & 0xffffu; }
; __device__ __forceinline__ void hgrn_out_phase(const Ctx& F, const Args& a, int l) {
;     ...
; #pragma unroll
;             for (int t = 0; t < 64; ++t) {
;                 const float qv = bf2f(PB[(size_t)(rb + (dir ? 63 - t : t)) * INW + colq]) * 0.125f;
;                 cum += __logf(fv[t]);
;                 const float qt = qv * __expf(fminf(cum - ref, 80.f));
;                 const float kt = (1.0f - fv[t]) * __expf(fminf(ref - cum, 80.f));
;                 const float qhv = qv * __expf(cum);
;                 *(LAS bf16_t*)(TQ + t * TP + 2 * lane) = (bf16_t)f2bf(qt);
;                 *(LAS bf16_t*)(TK + t * TP + 2 * lane) = (bf16_t)f2bf(kt);
;                 if (t & 1) qh[t >> 1] = pk2(qh_prev, qhv); else qh_prev = qhv;
;             }
	v_lshlrev_b32_e32 v3, 16, v3
	v_pk_mul_f32 v[2:3], v[2:3], s[8:9] op_sel_hi:[1,0]
	s_nop 0
	v_mul_f32_e32 v45, v45, v2
	v_cvt_pk_bf16_f32 v45, v45, s0
	ds_write_b16 v126, v45 offset:3168
	v_mul_f32_e32 v45, v49, v3
	v_cvt_pk_bf16_f32 v45, v45, s0
	v_pk_mul_f32 v[2:3], v[46:47], v[2:3]
	ds_write_b16 v126, v45 offset:3312
	v_cvt_pk_bf16_f32 v45, v2, v3
	v_mad_i64_i32 v[2:3], s[26:27], s27, v205, v[108:109]
	global_load_ushort v49, v[2:3], off offset:1024
	v_mad_i64_i32 v[2:3], s[26:27], s24, v205, v[108:109]
	global_load_ushort v3, v[2:3], off offset:1024
	v_sub_f32_e32 v47, v5, v85
	v_min_f32_e32 v47, 0x42a00000, v47
	v_mul_f32_e32 v47, 0x3fb8aa3b, v47
	v_sub_f32_e32 v46, v85, v5
	v_exp_f32_e32 v47, v47
	v_min_f32_e32 v46, 0x42a00000, v46
	v_mul_f32_e32 v46, 0x3fb8aa3b, v46
	v_exp_f32_e32 v48, v46
	v_sub_f32_e32 v46, 1.0, v84
	v_mul_f32_e32 v47, v46, v47
	v_cvt_pk_bf16_f32 v47, v47, s0
	ds_write_b16 v126, v47 offset:12672
	v_sub_f32_e32 v47, v87, v5
	v_min_f32_e32 v47, 0x42a00000, v47
	v_mul_f32_e32 v47, 0x3fb8aa3b, v47
	v_exp_f32_e32 v53, v47
	v_sub_f32_e32 v47, 1.0, v86
	v_mul_f32_e32 v47, v47, v54
	v_mul_f32_e32 v46, 0x3fb8aa3b, v85
	v_cvt_pk_bf16_f32 v47, v47, s0
	v_mul_f32_e32 v2, 0x3fb8aa3b, v87
	v_exp_f32_e32 v46, v46
	ds_write_b16 v126, v47 offset:12816
	v_exp_f32_e32 v47, v2
	s_waitcnt vmcnt(1)
	v_lshlrev_b32_e32 v2, 16, v49
	v_sub_f32_e32 v49, v5, v89
	v_min_f32_e32 v49, 0x42a00000, v49
	s_waitcnt vmcnt(0)
	v_lshlrev_b32_e32 v3, 16, v3
	v_pk_mul_f32 v[2:3], v[2:3], s[8:9] op_sel_hi:[1,0]
	v_mul_f32_e32 v49, 0x3fb8aa3b, v49
	v_mul_f32_e32 v48, v48, v2
	v_cvt_pk_bf16_f32 v48, v48, s0
	ds_write_b16 v126, v48 offset:3456
	v_mul_f32_e32 v48, v53, v3
	v_pk_mul_f32 v[2:3], v[46:47], v[2:3]
	v_exp_f32_e32 v49, v49
	v_cvt_pk_bf16_f32 v46, v2, v3
	v_mad_i64_i32 v[2:3], s[24:25], s25, v205, v[108:109]
	global_load_ushort v53, v[2:3], off offset:1024
	v_mad_i64_i32 v[2:3], s[24:25], s57, v205, v[108:109]
	global_load_ushort v3, v[2:3], off offset:1024
	v_cvt_pk_bf16_f32 v48, v48, s0
	ds_write_b16 v126, v48 offset:3600
	v_sub_f32_e32 v48, 1.0, v88
	v_mul_f32_e32 v49, v48, v49
	v_cvt_pk_bf16_f32 v49, v49, s0
	ds_write_b16 v126, v49 offset:12960
	v_sub_f32_e32 v49, v91, v5
	v_sub_f32_e32 v47, v89, v5
	v_min_f32_e32 v49, 0x42a00000, v49
	v_min_f32_e32 v47, 0x42a00000, v47
	v_mul_f32_e32 v49, 0x3fb8aa3b, v49
	v_mul_f32_e32 v47, 0x3fb8aa3b, v47
	v_exp_f32_e32 v54, v49
	v_sub_f32_e32 v49, 1.0, v90
	v_exp_f32_e32 v47, v47
	v_mul_f32_e32 v49, v49, v55
	v_cvt_pk_bf16_f32 v49, v49, s0
	v_mul_f32_e32 v2, 0x3fb8aa3b, v91
	v_mul_f32_e32 v48, 0x3fb8aa3b, v89
	ds_write_b16 v126, v49 offset:13104
	v_exp_f32_e32 v49, v2
	v_exp_f32_e32 v48, v48
	s_waitcnt vmcnt(1)
	v_lshlrev_b32_e32 v2, 16, v53
	s_waitcnt vmcnt(0)
	v_lshlrev_b32_e32 v3, 16, v3
	v_pk_mul_f32 v[2:3], v[2:3], s[8:9] op_sel_hi:[1,0]
	s_nop 0
	v_mul_f32_e32 v47, v47, v2
	v_cvt_pk_bf16_f32 v47, v47, s0
	ds_write_b16 v126, v47 offset:3744
	v_mul_f32_e32 v47, v54, v3
	v_cvt_pk_bf16_f32 v47, v47, s0
	v_pk_mul_f32 v[2:3], v[48:49], v[2:3]
	ds_write_b16 v126, v47 offset:3888
	v_cvt_pk_bf16_f32 v47, v2, v3
	v_mad_i64_i32 v[2:3], s[24:25], s2, v205, v[108:109]
	global_load_ushort v54, v[2:3], off offset:1024
	v_mad_i64_i32 v[2:3], s[24:25], s96, v205, v[108:109]
	global_load_ushort v3, v[2:3], off offset:1024
	v_sub_f32_e32 v49, v5, v93
	v_min_f32_e32 v49, 0x42a00000, v49
	v_mul_f32_e32 v49, 0x3fb8aa3b, v49
	v_sub_f32_e32 v48, v93, v5
	v_exp_f32_e32 v49, v49
	v_min_f32_e32 v48, 0x42a00000, v48
	v_mul_f32_e32 v48, 0x3fb8aa3b, v48
	v_exp_f32_e32 v53, v48
	v_sub_f32_e32 v48, 1.0, v92
	v_mul_f32_e32 v49, v48, v49
	v_cvt_pk_bf16_f32 v49, v49, s0
	ds_write_b16 v126, v49 offset:13248
	v_sub_f32_e32 v49, v95, v5
	v_min_f32_e32 v49, 0x42a00000, v49
	v_mul_f32_e32 v49, 0x3fb8aa3b, v49
	v_exp_f32_e32 v55, v49
	v_sub_f32_e32 v49, 1.0, v94
	v_mul_f32_e32 v49, v49, v56
	v_mul_f32_e32 v48, 0x3fb8aa3b, v93
	v_cvt_pk_bf16_f32 v49, v49, s0
	v_mul_f32_e32 v2, 0x3fb8aa3b, v95
	v_exp_f32_e32 v48, v48
	ds_write_b16 v126, v49 offset:13392
	v_exp_f32_e32 v49, v2
	s_waitcnt vmcnt(1)
	v_lshlrev_b32_e32 v2, 16, v54
	v_sub_f32_e32 v54, v5, v97
	v_min_f32_e32 v54, 0x42a00000, v54
	s_waitcnt vmcnt(0)
	v_lshlrev_b32_e32 v3, 16, v3
	v_pk_mul_f32 v[2:3], v[2:3], s[8:9] op_sel_hi:[1,0]
	v_mul_f32_e32 v54, 0x3fb8aa3b, v54
	v_mul_f32_e32 v53, v53, v2
	v_cvt_pk_bf16_f32 v53, v53, s0
	ds_write_b16 v126, v53 offset:4032
	v_mul_f32_e32 v53, v55, v3
	v_pk_mul_f32 v[2:3], v[48:49], v[2:3]
	v_exp_f32_e32 v54, v54
	v_cvt_pk_bf16_f32 v48, v2, v3
	v_mad_i64_i32 v[2:3], s[24:25], s20, v205, v[108:109]
	global_load_ushort v56, v[2:3], off offset:1024
	v_mad_i64_i32 v[2:3], s[22:23], s22, v205, v[108:109]
	global_load_ushort v3, v[2:3], off offset:1024
	v_cvt_pk_bf16_f32 v53, v53, s0
	ds_write_b16 v126, v53 offset:4176
	v_sub_f32_e32 v53, 1.0, v96
	v_mul_f32_e32 v53, v53, v54
	v_cvt_pk_bf16_f32 v53, v53, s0
	ds_write_b16 v126, v53 offset:13536
	v_sub_f32_e32 v53, v5, v5
	v_min_f32_e32 v53, 0x42a00000, v53
	v_mul_f32_e32 v53, 0x3fb8aa3b, v53
	v_exp_f32_e32 v53, v53
	v_sub_f32_e32 v49, v97, v5
	v_min_f32_e32 v49, 0x42a00000, v49
	v_mul_f32_e32 v49, 0x3fb8aa3b, v49
	v_sub_f32_e32 v55, 1.0, v99
	v_exp_f32_e32 v49, v49
	v_mul_f32_e32 v55, v55, v53
	v_cvt_pk_bf16_f32 v55, v55, s0
	v_mul_f32_e32 v2, 0x3fb8aa3b, v5
	ds_write_b16 v126, v55 offset:13680
	v_exp_f32_e32 v55, v2
	v_mul_f32_e32 v54, 0x3fb8aa3b, v97
	v_exp_f32_e32 v54, v54
	s_waitcnt vmcnt(1)
	v_lshlrev_b32_e32 v2, 16, v56
	s_waitcnt vmcnt(0)
; #define LAS __attribute__((address_space(3)))
; __device__ __forceinline__ float bf2f(unsigned v) { return __uint_as_float(v << 16); }
; __device__ __forceinline__ unsigned pk2(float lo, float hi) { const f32x2_t v = {lo, hi}; const bf16x2_t b = __builtin_convertvector(v, bf16x2_t); return __builtin_bit_cast(unsigned, b); }
; __device__ __forceinline__ unsigned f2bf(float f) { return pk2(f, 0.f) & 0xffffu; }
; __device__ __forceinline__ void hgrn_out_phase(const Ctx& F, const Args& a, int l) {
;     ...
;             unsigned qh[32]; float cum = 0.f, qh_prev = 0.f;
; #pragma unroll
;             for (int t = 0; t < 64; ++t) {
;                 const float qv = bf2f(PB[(size_t)(rb + (dir ? 63 - t : t)) * INW + colq]) * 0.125f;
;                 cum += __logf(fv[t]);
;                 const float qt = qv * __expf(fminf(cum - ref, 80.f));
;                 const float kt = (1.0f - fv[t]) * __expf(fminf(ref - cum, 80.f));
;                 const float qhv = qv * __expf(cum);
;                 *(LAS bf16_t*)(TQ + t * TP + 2 * lane) = (bf16_t)f2bf(qt);
;                 *(LAS bf16_t*)(TK + t * TP + 2 * lane) = (bf16_t)f2bf(kt);
;                 if (t & 1) qh[t >> 1] = pk2(qh_prev, qhv); else qh_prev = qhv;
;             }
	v_lshlrev_b32_e32 v3, 16, v3
	v_pk_mul_f32 v[2:3], v[2:3], s[8:9] op_sel_hi:[1,0]
	s_nop 0
	v_mul_f32_e32 v49, v49, v2
	v_cvt_pk_bf16_f32 v49, v49, s0
	ds_write_b16 v126, v49 offset:4320
	v_mul_f32_e32 v49, v53, v3
	v_cndmask_b32_e64 v53, 0, 32, vcc
	v_ldexp_f32 v53, v52, v53
	v_log_f32_e32 v53, v53
	v_pk_mul_f32 v[2:3], v[54:55], v[2:3]
	v_cvt_pk_bf16_f32 v49, v49, s0
	ds_write_b16 v126, v49 offset:4464
	v_mul_f32_e32 v54, 0x3f317217, v53
	v_fma_f32 v54, v53, s31, -v54
	v_cvt_pk_bf16_f32 v49, v2, v3
	v_mad_i64_i32 v[2:3], s[4:5], s4, v205, v[108:109]
	v_fmac_f32_e32 v54, 0x3377d1cf, v53
	v_fmac_f32_e32 v54, 0x3f317217, v53
	v_cmp_lt_f32_e64 s[4:5], |v53|, s34
	global_load_ushort v56, v[2:3], off offset:1024
	v_sub_f32_e32 v52, 1.0, v52
	v_cndmask_b32_e64 v53, v53, v54, s[4:5]
	v_mad_i64_i32 v[2:3], s[4:5], s64, v205, v[108:109]
	global_load_ushort v3, v[2:3], off offset:1024
	v_cndmask_b32_e32 v54, 0, v206, vcc
	v_sub_f32_e32 v53, v53, v54
	v_add_f32_e32 v53, v53, v5
	v_sub_f32_e32 v55, v5, v53
	v_min_f32_e32 v55, 0x42a00000, v55
	v_mul_f32_e32 v55, 0x3fb8aa3b, v55
	v_exp_f32_e32 v55, v55
	v_cmp_gt_f32_e32 vcc, s35, v51
	v_sub_f32_e32 v54, v53, v5
	v_min_f32_e32 v54, 0x42a00000, v54
	v_mul_f32_e32 v55, v52, v55
	v_cvt_pk_bf16_f32 v55, v55, s0
	ds_write_b16 v126, v55 offset:13824
	v_cndmask_b32_e64 v55, 0, 32, vcc
	v_ldexp_f32 v55, v51, v55
	v_log_f32_e32 v55, v55
	v_mul_f32_e32 v52, 0x3fb8aa3b, v53
	v_mul_f32_e32 v54, 0x3fb8aa3b, v54
	v_exp_f32_e32 v54, v54
	v_mul_f32_e32 v57, 0x3f317217, v55
	v_fma_f32 v57, v55, s31, -v57
	v_fmac_f32_e32 v57, 0x3377d1cf, v55
	v_fmac_f32_e32 v57, 0x3f317217, v55
	v_cmp_lt_f32_e64 s[4:5], |v55|, s34
	v_sub_f32_e32 v51, 1.0, v51
	v_exp_f32_e32 v52, v52
	v_cndmask_b32_e64 v55, v55, v57, s[4:5]
	v_cndmask_b32_e32 v57, 0, v206, vcc
	v_sub_f32_e32 v55, v55, v57
	v_add_f32_e32 v55, v55, v53
	v_sub_f32_e32 v53, v55, v5
	v_min_f32_e32 v53, 0x42a00000, v53
	v_mul_f32_e32 v53, 0x3fb8aa3b, v53
	v_exp_f32_e32 v57, v53
	v_sub_f32_e32 v53, v5, v55
	v_min_f32_e32 v53, 0x42a00000, v53
	v_mul_f32_e32 v53, 0x3fb8aa3b, v53
	v_exp_f32_e32 v53, v53
	v_mul_f32_e32 v2, 0x3fb8aa3b, v55
	v_cmp_gt_f32_e32 vcc, s35, v50
	v_mul_f32_e32 v51, v51, v53
	v_exp_f32_e32 v53, v2
	v_cvt_pk_bf16_f32 v51, v51, s0
	ds_write_b16 v126, v51 offset:13968
	s_waitcnt vmcnt(1)
	v_lshlrev_b32_e32 v2, 16, v56
	s_waitcnt vmcnt(0)
	v_lshlrev_b32_e32 v3, 16, v3
	v_pk_mul_f32 v[2:3], v[2:3], s[8:9] op_sel_hi:[1,0]
	s_nop 0
	v_mul_f32_e32 v51, v54, v2
	v_cvt_pk_bf16_f32 v51, v51, s0
	ds_write_b16 v126, v51 offset:4608
	v_mul_f32_e32 v51, v57, v3
	v_pk_mul_f32 v[2:3], v[52:53], v[2:3]
	v_cndmask_b32_e64 v52, 0, 32, vcc
	v_ldexp_f32 v52, v50, v52
	v_log_f32_e32 v52, v52
	v_cvt_pk_bf16_f32 v51, v51, s0
	ds_write_b16 v126, v51 offset:4752
	v_cvt_pk_bf16_f32 v51, v2, v3
	v_mul_f32_e32 v53, 0x3f317217, v52
	v_fma_f32 v53, v52, s31, -v53
	v_mad_i64_i32 v[2:3], s[4:5], s63, v205, v[108:109]
	v_fmac_f32_e32 v53, 0x3377d1cf, v52
	v_fmac_f32_e32 v53, 0x3f317217, v52
	v_cmp_lt_f32_e64 s[4:5], |v52|, s34
	v_sub_f32_e32 v50, 1.0, v50
	s_nop 0
	v_cndmask_b32_e64 v52, v52, v53, s[4:5]
	v_cndmask_b32_e32 v53, 0, v206, vcc
	v_sub_f32_e32 v52, v52, v53
	v_add_f32_e32 v53, v52, v55
	global_load_ushort v55, v[2:3], off offset:1024
	v_mad_i64_i32 v[2:3], s[4:5], s62, v205, v[108:109]
	global_load_ushort v3, v[2:3], off offset:1024
	v_sub_f32_e32 v52, v53, v5
	v_min_f32_e32 v52, 0x42a00000, v52
	v_mul_f32_e32 v52, 0x3fb8aa3b, v52
	v_exp_f32_e32 v54, v52
	v_sub_f32_e32 v52, v5, v53
	v_min_f32_e32 v52, 0x42a00000, v52
	v_mul_f32_e32 v52, 0x3fb8aa3b, v52
	v_exp_f32_e32 v52, v52
	v_cmp_gt_f32_e32 vcc, s35, v33
	v_mul_f32_e32 v50, v50, v52
	v_cvt_pk_bf16_f32 v50, v50, s0
	ds_write_b16 v126, v50 offset:14112
	v_cndmask_b32_e64 v50, 0, 32, vcc
	v_ldexp_f32 v50, v33, v50
	v_log_f32_e32 v50, v50
	v_mul_f32_e32 v52, 0x3fb8aa3b, v53
	v_sub_f32_e32 v33, 1.0, v33
	v_exp_f32_e32 v52, v52
	v_mul_f32_e32 v56, 0x3f317217, v50
	v_fma_f32 v56, v50, s31, -v56
	v_fmac_f32_e32 v56, 0x3377d1cf, v50
	v_fmac_f32_e32 v56, 0x3f317217, v50
	v_cmp_lt_f32_e64 s[4:5], |v50|, s34
	s_waitcnt vmcnt(0)
	v_lshlrev_b32_e32 v3, 16, v3
	v_cndmask_b32_e64 v50, v50, v56, s[4:5]
	v_cndmask_b32_e32 v56, 0, v206, vcc
	v_sub_f32_e32 v50, v50, v56
	v_add_f32_e32 v56, v50, v53
	v_sub_f32_e32 v53, v5, v56
	v_min_f32_e32 v53, 0x42a00000, v53
	v_mul_f32_e32 v53, 0x3fb8aa3b, v53
	v_exp_f32_e32 v53, v53
	v_sub_f32_e32 v50, v56, v5
	v_min_f32_e32 v50, 0x42a00000, v50
	v_mul_f32_e32 v50, 0x3fb8aa3b, v50
	v_mul_f32_e32 v2, 0x3fb8aa3b, v56
	v_exp_f32_e32 v50, v50
	v_mul_f32_e32 v33, v33, v53
	v_exp_f32_e32 v53, v2
	v_lshlrev_b32_e32 v2, 16, v55
	v_cvt_pk_bf16_f32 v33, v33, s0
	v_pk_mul_f32 v[2:3], v[2:3], s[8:9] op_sel_hi:[1,0]
	ds_write_b16 v126, v33 offset:14256
	v_mul_f32_e32 v33, v54, v2
	v_cvt_pk_bf16_f32 v33, v33, s0
	ds_write_b16 v126, v33 offset:4896
	v_mul_f32_e32 v33, v50, v3
	v_cvt_pk_bf16_f32 v33, v33, s0
	v_cmp_gt_f32_e32 vcc, s35, v32
	ds_write_b16 v126, v33 offset:5040
	v_pk_mul_f32 v[2:3], v[52:53], v[2:3]
	v_cndmask_b32_e64 v33, 0, 32, vcc
	v_ldexp_f32 v33, v32, v33
	v_log_f32_e32 v33, v33
	v_cvt_pk_bf16_f32 v50, v2, v3
	v_mad_i64_i32 v[2:3], s[4:5], s43, v205, v[108:109]
	v_mul_f32_e32 v52, 0x3f317217, v33
	v_fma_f32 v52, v33, s31, -v52
	v_fmac_f32_e32 v52, 0x3377d1cf, v33
	v_fmac_f32_e32 v52, 0x3f317217, v33
	v_cmp_lt_f32_e64 s[4:5], |v33|, s34
	global_load_ushort v54, v[2:3], off offset:1024
	v_sub_f32_e32 v32, 1.0, v32
	v_cndmask_b32_e64 v33, v33, v52, s[4:5]
	v_mad_i64_i32 v[2:3], s[4:5], s42, v205, v[108:109]
	global_load_ushort v3, v[2:3], off offset:1024
	v_cndmask_b32_e32 v52, 0, v206, vcc
	v_sub_f32_e32 v33, v33, v52
	v_add_f32_e32 v33, v33, v56
	v_sub_f32_e32 v53, v5, v33
	v_min_f32_e32 v53, 0x42a00000, v53
	v_mul_f32_e32 v53, 0x3fb8aa3b, v53
	v_exp_f32_e32 v53, v53
	v_cmp_gt_f32_e32 vcc, s35, v31
	v_sub_f32_e32 v52, v33, v5
	v_min_f32_e32 v52, 0x42a00000, v52
	v_mul_f32_e32 v53, v32, v53
	v_cvt_pk_bf16_f32 v53, v53, s0
	ds_write_b16 v126, v53 offset:14400
	v_cndmask_b32_e64 v53, 0, 32, vcc
	v_ldexp_f32 v53, v31, v53
	v_log_f32_e32 v53, v53
	v_mul_f32_e32 v32, 0x3fb8aa3b, v33
	v_mul_f32_e32 v52, 0x3fb8aa3b, v52
	v_exp_f32_e32 v52, v52
	v_mul_f32_e32 v55, 0x3f317217, v53
	v_fma_f32 v55, v53, s31, -v55
	v_fmac_f32_e32 v55, 0x3377d1cf, v53
	v_fmac_f32_e32 v55, 0x3f317217, v53
	v_cmp_lt_f32_e64 s[4:5], |v53|, s34
	v_sub_f32_e32 v31, 1.0, v31
	v_exp_f32_e32 v32, v32
	v_cndmask_b32_e64 v53, v53, v55, s[4:5]
	v_cndmask_b32_e32 v55, 0, v206, vcc
	v_sub_f32_e32 v53, v53, v55
	v_add_f32_e32 v53, v53, v33
	v_sub_f32_e32 v33, v53, v5
	v_min_f32_e32 v33, 0x42a00000, v33
	v_mul_f32_e32 v33, 0x3fb8aa3b, v33
	v_exp_f32_e32 v55, v33
	v_sub_f32_e32 v33, v5, v53
	v_min_f32_e32 v33, 0x42a00000, v33
	v_mul_f32_e32 v33, 0x3fb8aa3b, v33
	v_exp_f32_e32 v33, v33
	v_mul_f32_e32 v2, 0x3fb8aa3b, v53
	v_cmp_gt_f32_e32 vcc, s35, v30
	v_mul_f32_e32 v31, v31, v33
	v_exp_f32_e32 v33, v2
	v_cvt_pk_bf16_f32 v31, v31, s0
	ds_write_b16 v126, v31 offset:14544
	s_waitcnt vmcnt(1)
; #define LAS __attribute__((address_space(3)))
; __device__ __forceinline__ float bf2f(unsigned v) { return __uint_as_float(v << 16); }
; __device__ __forceinline__ unsigned pk2(float lo, float hi) { const f32x2_t v = {lo, hi}; const bf16x2_t b = __builtin_convertvector(v, bf16x2_t); return __builtin_bit_cast(unsigned, b); }
; __device__ __forceinline__ unsigned f2bf(float f) { return pk2(f, 0.f) & 0xffffu; }
; __device__ __forceinline__ void hgrn_out_phase(const Ctx& F, const Args& a, int l) {
;     ...
;             unsigned qh[32]; float cum = 0.f, qh_prev = 0.f;
; #pragma unroll
;             for (int t = 0; t < 64; ++t) {
;                 const float qv = bf2f(PB[(size_t)(rb + (dir ? 63 - t : t)) * INW + colq]) * 0.125f;
;                 cum += __logf(fv[t]);
;                 const float qt = qv * __expf(fminf(cum - ref, 80.f));
;                 const float kt = (1.0f - fv[t]) * __expf(fminf(ref - cum, 80.f));
;                 const float qhv = qv * __expf(cum);
;                 *(LAS bf16_t*)(TQ + t * TP + 2 * lane) = (bf16_t)f2bf(qt);
;                 *(LAS bf16_t*)(TK + t * TP + 2 * lane) = (bf16_t)f2bf(kt);
;                 if (t & 1) qh[t >> 1] = pk2(qh_prev, qhv); else qh_prev = qhv;
;             }
	v_lshlrev_b32_e32 v2, 16, v54
	s_waitcnt vmcnt(0)
	v_lshlrev_b32_e32 v3, 16, v3
	v_pk_mul_f32 v[2:3], v[2:3], s[8:9] op_sel_hi:[1,0]
	s_nop 0
	v_mul_f32_e32 v31, v52, v2
	v_cvt_pk_bf16_f32 v31, v31, s0
	ds_write_b16 v126, v31 offset:5184
	v_mul_f32_e32 v31, v55, v3
	v_cvt_pk_bf16_f32 v31, v31, s0
	ds_write_b16 v126, v31 offset:5328
	v_cndmask_b32_e64 v31, 0, 32, vcc
	v_ldexp_f32 v31, v30, v31
	v_log_f32_e32 v31, v31
	v_pk_mul_f32 v[2:3], v[32:33], v[2:3]
	v_sub_f32_e32 v30, 1.0, v30
	v_cvt_pk_bf16_f32 v52, v2, v3
	v_mul_f32_e32 v32, 0x3f317217, v31
	v_fma_f32 v32, v31, s31, -v32
	v_mad_i64_i32 v[2:3], s[4:5], s59, v205, v[108:109]
	v_fmac_f32_e32 v32, 0x3377d1cf, v31
	v_fmac_f32_e32 v32, 0x3f317217, v31
	v_cmp_lt_f32_e64 s[4:5], |v31|, s34
	s_nop 1
	v_cndmask_b32_e64 v31, v31, v32, s[4:5]
	v_cndmask_b32_e32 v32, 0, v206, vcc
	v_sub_f32_e32 v31, v31, v32
	v_add_f32_e32 v31, v31, v53
	global_load_ushort v53, v[2:3], off offset:1024
	v_mad_i64_i32 v[2:3], s[4:5], s58, v205, v[108:109]
	global_load_ushort v3, v[2:3], off offset:1024
	v_sub_f32_e32 v33, v5, v31
	v_min_f32_e32 v33, 0x42a00000, v33
	v_mul_f32_e32 v33, 0x3fb8aa3b, v33
	v_exp_f32_e32 v33, v33
	v_cmp_gt_f32_e32 vcc, s35, v29
	v_sub_f32_e32 v32, v31, v5
	v_min_f32_e32 v32, 0x42a00000, v32
	v_mul_f32_e32 v33, v30, v33
	v_cvt_pk_bf16_f32 v33, v33, s0
	ds_write_b16 v126, v33 offset:14688
	v_cndmask_b32_e64 v33, 0, 32, vcc
	v_ldexp_f32 v33, v29, v33
	v_log_f32_e32 v33, v33
	v_mul_f32_e32 v30, 0x3fb8aa3b, v31
	v_mul_f32_e32 v32, 0x3fb8aa3b, v32
	v_exp_f32_e32 v32, v32
	v_mul_f32_e32 v54, 0x3f317217, v33
	v_fma_f32 v54, v33, s31, -v54
	v_fmac_f32_e32 v54, 0x3377d1cf, v33
	v_fmac_f32_e32 v54, 0x3f317217, v33
	v_cmp_lt_f32_e64 s[4:5], |v33|, s34
	v_sub_f32_e32 v29, 1.0, v29
	v_exp_f32_e32 v30, v30
	v_cndmask_b32_e64 v33, v33, v54, s[4:5]
	v_cndmask_b32_e32 v54, 0, v206, vcc
	v_sub_f32_e32 v33, v33, v54
	v_add_f32_e32 v33, v33, v31
	v_sub_f32_e32 v31, v33, v5
	v_min_f32_e32 v31, 0x42a00000, v31
	v_mul_f32_e32 v31, 0x3fb8aa3b, v31
	v_exp_f32_e32 v54, v31
	v_sub_f32_e32 v31, v5, v33
	v_min_f32_e32 v31, 0x42a00000, v31
	v_mul_f32_e32 v31, 0x3fb8aa3b, v31
	v_exp_f32_e32 v31, v31
	v_mul_f32_e32 v2, 0x3fb8aa3b, v33
	v_cmp_gt_f32_e32 vcc, s35, v28
	v_mul_f32_e32 v29, v29, v31
	v_exp_f32_e32 v31, v2
	v_cvt_pk_bf16_f32 v29, v29, s0
	ds_write_b16 v126, v29 offset:14832
	s_waitcnt vmcnt(1)
	v_lshlrev_b32_e32 v2, 16, v53
	s_waitcnt vmcnt(0)
	v_lshlrev_b32_e32 v3, 16, v3
	v_pk_mul_f32 v[2:3], v[2:3], s[8:9] op_sel_hi:[1,0]
	s_nop 0
	v_mul_f32_e32 v29, v32, v2
	v_cvt_pk_bf16_f32 v29, v29, s0
	ds_write_b16 v126, v29 offset:5472
	v_mul_f32_e32 v29, v54, v3
	v_cvt_pk_bf16_f32 v29, v29, s0
	ds_write_b16 v126, v29 offset:5616
	v_cndmask_b32_e64 v29, 0, 32, vcc
	v_ldexp_f32 v29, v28, v29
	v_log_f32_e32 v29, v29
	v_pk_mul_f32 v[2:3], v[30:31], v[2:3]
	v_sub_f32_e32 v28, 1.0, v28
	v_cvt_pk_bf16_f32 v53, v2, v3
	v_mul_f32_e32 v30, 0x3f317217, v29
	v_fma_f32 v30, v29, s31, -v30
	v_mad_i64_i32 v[2:3], s[4:5], s7, v205, v[108:109]
	v_fmac_f32_e32 v30, 0x3377d1cf, v29
	v_fmac_f32_e32 v30, 0x3f317217, v29
	v_cmp_lt_f32_e64 s[4:5], |v29|, s34
	global_load_ushort v32, v[2:3], off offset:1024
	s_nop 0
	v_cndmask_b32_e64 v29, v29, v30, s[4:5]
	v_mad_i64_i32 v[2:3], s[4:5], s6, v205, v[108:109]
	global_load_ushort v3, v[2:3], off offset:1024
	v_cndmask_b32_e32 v30, 0, v206, vcc
	v_sub_f32_e32 v29, v29, v30
	v_add_f32_e32 v29, v29, v33
	v_sub_f32_e32 v31, v5, v29
	v_min_f32_e32 v31, 0x42a00000, v31
	v_mul_f32_e32 v31, 0x3fb8aa3b, v31
	v_exp_f32_e32 v31, v31
	v_cmp_gt_f32_e32 vcc, s35, v27
	v_sub_f32_e32 v30, v29, v5
	v_min_f32_e32 v30, 0x42a00000, v30
	v_mul_f32_e32 v31, v28, v31
	v_cvt_pk_bf16_f32 v31, v31, s0
	ds_write_b16 v126, v31 offset:14976
	v_cndmask_b32_e64 v31, 0, 32, vcc
	v_ldexp_f32 v31, v27, v31
	v_log_f32_e32 v31, v31
	v_mul_f32_e32 v28, 0x3fb8aa3b, v29
	v_mul_f32_e32 v30, 0x3fb8aa3b, v30
	v_exp_f32_e32 v30, v30
	v_mul_f32_e32 v33, 0x3f317217, v31
	v_fma_f32 v33, v31, s31, -v33
	v_fmac_f32_e32 v33, 0x3377d1cf, v31
	v_fmac_f32_e32 v33, 0x3f317217, v31
	v_cmp_lt_f32_e64 s[4:5], |v31|, s34
	v_sub_f32_e32 v27, 1.0, v27
	v_exp_f32_e32 v28, v28
	v_cndmask_b32_e64 v31, v31, v33, s[4:5]
	v_cndmask_b32_e32 v33, 0, v206, vcc
	v_sub_f32_e32 v31, v31, v33
	v_add_f32_e32 v31, v31, v29
	v_sub_f32_e32 v29, v31, v5
	v_min_f32_e32 v29, 0x42a00000, v29
	v_mul_f32_e32 v29, 0x3fb8aa3b, v29
	v_exp_f32_e32 v33, v29
	v_sub_f32_e32 v29, v5, v31
	v_min_f32_e32 v29, 0x42a00000, v29
	v_mul_f32_e32 v29, 0x3fb8aa3b, v29
	v_exp_f32_e32 v29, v29
	v_mul_f32_e32 v2, 0x3fb8aa3b, v31
	v_cmp_gt_f32_e32 vcc, s35, v26
	s_movk_i32 s6, 0xe000
	v_mul_f32_e32 v27, v27, v29
	v_exp_f32_e32 v29, v2
	v_cvt_pk_bf16_f32 v27, v27, s0
	ds_write_b16 v126, v27 offset:15120
	s_waitcnt vmcnt(1)
	v_lshlrev_b32_e32 v2, 16, v32
	s_waitcnt vmcnt(0)
; #define LAS __attribute__((address_space(3)))
; __device__ __forceinline__ float bf2f(unsigned v) { return __uint_as_float(v << 16); }
; __device__ __forceinline__ unsigned pk2(float lo, float hi) { const f32x2_t v = {lo, hi}; const bf16x2_t b = __builtin_convertvector(v, bf16x2_t); return __builtin_bit_cast(unsigned, b); }
; __device__ __forceinline__ unsigned f2bf(float f) { return pk2(f, 0.f) & 0xffffu; }
; __device__ __forceinline__ void hgrn_out_phase(const Ctx& F, const Args& a, int l) {
;     ...
;             unsigned qh[32]; float cum = 0.f, qh_prev = 0.f;
; #pragma unroll
;             for (int t = 0; t < 64; ++t) {
;                 const float qv = bf2f(PB[(size_t)(rb + (dir ? 63 - t : t)) * INW + colq]) * 0.125f;
;                 cum += __logf(fv[t]);
;                 const float qt = qv * __expf(fminf(cum - ref, 80.f));
;                 const float kt = (1.0f - fv[t]) * __expf(fminf(ref - cum, 80.f));
;                 const float qhv = qv * __expf(cum);
;                 *(LAS bf16_t*)(TQ + t * TP + 2 * lane) = (bf16_t)f2bf(qt);
;                 *(LAS bf16_t*)(TK + t * TP + 2 * lane) = (bf16_t)f2bf(kt);
;                 if (t & 1) qh[t >> 1] = pk2(qh_prev, qhv); else qh_prev = qhv;
;             }
	v_lshlrev_b32_e32 v3, 16, v3
	v_pk_mul_f32 v[2:3], v[2:3], s[8:9] op_sel_hi:[1,0]
	s_nop 0
	v_mul_f32_e32 v27, v30, v2
	v_cvt_pk_bf16_f32 v27, v27, s0
	ds_write_b16 v126, v27 offset:5760
	v_mul_f32_e32 v27, v33, v3
	v_cvt_pk_bf16_f32 v27, v27, s0
	ds_write_b16 v126, v27 offset:5904
	v_cndmask_b32_e64 v27, 0, 32, vcc
	v_ldexp_f32 v27, v26, v27
	v_log_f32_e32 v27, v27
	v_pk_mul_f32 v[2:3], v[28:29], v[2:3]
	v_sub_f32_e32 v26, 1.0, v26
	v_cvt_pk_bf16_f32 v54, v2, v3
	v_mul_f32_e32 v28, 0x3f317217, v27
	v_fma_f32 v28, v27, s31, -v28
	v_mad_i64_i32 v[2:3], s[4:5], s55, v205, v[108:109]
	v_fmac_f32_e32 v28, 0x3377d1cf, v27
	v_fmac_f32_e32 v28, 0x3f317217, v27
	v_cmp_lt_f32_e64 s[4:5], |v27|, s34
	global_load_ushort v30, v[2:3], off offset:1024
	s_nop 0
	v_cndmask_b32_e64 v27, v27, v28, s[4:5]
	v_mad_i64_i32 v[2:3], s[4:5], s54, v205, v[108:109]
	global_load_ushort v3, v[2:3], off offset:1024
	v_cndmask_b32_e32 v28, 0, v206, vcc
	v_sub_f32_e32 v27, v27, v28
	v_add_f32_e32 v27, v27, v31
	v_sub_f32_e32 v29, v5, v27
	v_min_f32_e32 v29, 0x42a00000, v29
	v_mul_f32_e32 v29, 0x3fb8aa3b, v29
	v_exp_f32_e32 v29, v29
	v_cmp_gt_f32_e32 vcc, s35, v25
	v_sub_f32_e32 v28, v27, v5
	v_min_f32_e32 v28, 0x42a00000, v28
	v_mul_f32_e32 v29, v26, v29
	v_cvt_pk_bf16_f32 v29, v29, s0
	ds_write_b16 v126, v29 offset:15264
	v_cndmask_b32_e64 v29, 0, 32, vcc
	v_ldexp_f32 v29, v25, v29
	v_log_f32_e32 v29, v29
	v_mul_f32_e32 v26, 0x3fb8aa3b, v27
	v_mul_f32_e32 v28, 0x3fb8aa3b, v28
	v_exp_f32_e32 v28, v28
	v_mul_f32_e32 v31, 0x3f317217, v29
	v_fma_f32 v31, v29, s31, -v31
	v_fmac_f32_e32 v31, 0x3377d1cf, v29
	v_fmac_f32_e32 v31, 0x3f317217, v29
	v_cmp_lt_f32_e64 s[4:5], |v29|, s34
	v_sub_f32_e32 v25, 1.0, v25
	v_exp_f32_e32 v26, v26
	v_cndmask_b32_e64 v29, v29, v31, s[4:5]
	v_cndmask_b32_e32 v31, 0, v206, vcc
	v_sub_f32_e32 v29, v29, v31
	v_add_f32_e32 v29, v29, v27
	v_sub_f32_e32 v27, v29, v5
	v_min_f32_e32 v27, 0x42a00000, v27
	v_mul_f32_e32 v27, 0x3fb8aa3b, v27
	v_exp_f32_e32 v31, v27
	v_sub_f32_e32 v27, v5, v29
	v_min_f32_e32 v27, 0x42a00000, v27
	v_mul_f32_e32 v27, 0x3fb8aa3b, v27
	v_exp_f32_e32 v27, v27
	v_mul_f32_e32 v2, 0x3fb8aa3b, v29
	v_cmp_gt_f32_e32 vcc, s35, v24
	v_mul_f32_e32 v25, v25, v27
	v_exp_f32_e32 v27, v2
	v_cvt_pk_bf16_f32 v25, v25, s0
	ds_write_b16 v126, v25 offset:15408
	s_waitcnt vmcnt(1)
	v_lshlrev_b32_e32 v2, 16, v30
	s_waitcnt vmcnt(0)
	v_lshlrev_b32_e32 v3, 16, v3
	v_pk_mul_f32 v[2:3], v[2:3], s[8:9] op_sel_hi:[1,0]
	s_nop 0
	v_mul_f32_e32 v25, v28, v2
	v_cvt_pk_bf16_f32 v25, v25, s0
	ds_write_b16 v126, v25 offset:6048
	v_mul_f32_e32 v25, v31, v3
	v_cvt_pk_bf16_f32 v25, v25, s0
	ds_write_b16 v126, v25 offset:6192
	v_cndmask_b32_e64 v25, 0, 32, vcc
	v_ldexp_f32 v25, v24, v25
	v_log_f32_e32 v25, v25
	v_pk_mul_f32 v[2:3], v[26:27], v[2:3]
	v_sub_f32_e32 v24, 1.0, v24
	v_cvt_pk_bf16_f32 v55, v2, v3
	v_mul_f32_e32 v26, 0x3f317217, v25
	v_fma_f32 v26, v25, s31, -v26
	v_mad_i64_i32 v[2:3], s[4:5], s53, v205, v[108:109]
	v_fmac_f32_e32 v26, 0x3377d1cf, v25
	v_fmac_f32_e32 v26, 0x3f317217, v25
	v_cmp_lt_f32_e64 s[4:5], |v25|, s34
	global_load_ushort v28, v[2:3], off offset:1024
	s_nop 0
	v_cndmask_b32_e64 v25, v25, v26, s[4:5]
	v_mad_i64_i32 v[2:3], s[4:5], s52, v205, v[108:109]
	global_load_ushort v3, v[2:3], off offset:1024
	v_cndmask_b32_e32 v26, 0, v206, vcc
	v_sub_f32_e32 v25, v25, v26
	v_add_f32_e32 v25, v25, v29
	v_sub_f32_e32 v27, v5, v25
	v_min_f32_e32 v27, 0x42a00000, v27
	v_mul_f32_e32 v27, 0x3fb8aa3b, v27
	v_exp_f32_e32 v27, v27
	v_cmp_gt_f32_e32 vcc, s35, v23
	v_sub_f32_e32 v26, v25, v5
	v_min_f32_e32 v26, 0x42a00000, v26
	v_mul_f32_e32 v27, v24, v27
	v_cvt_pk_bf16_f32 v27, v27, s0
	ds_write_b16 v126, v27 offset:15552
	v_cndmask_b32_e64 v27, 0, 32, vcc
	v_ldexp_f32 v27, v23, v27
	v_log_f32_e32 v27, v27
	v_mul_f32_e32 v24, 0x3fb8aa3b, v25
	v_mul_f32_e32 v26, 0x3fb8aa3b, v26
	v_exp_f32_e32 v26, v26
	v_mul_f32_e32 v29, 0x3f317217, v27
	v_fma_f32 v29, v27, s31, -v29
	v_fmac_f32_e32 v29, 0x3377d1cf, v27
	v_fmac_f32_e32 v29, 0x3f317217, v27
	v_cmp_lt_f32_e64 s[4:5], |v27|, s34
	v_sub_f32_e32 v23, 1.0, v23
	v_exp_f32_e32 v24, v24
	v_cndmask_b32_e64 v27, v27, v29, s[4:5]
	v_cndmask_b32_e32 v29, 0, v206, vcc
	v_sub_f32_e32 v27, v27, v29
	v_add_f32_e32 v27, v27, v25
	v_sub_f32_e32 v25, v27, v5
	v_min_f32_e32 v25, 0x42a00000, v25
	v_mul_f32_e32 v25, 0x3fb8aa3b, v25
	v_exp_f32_e32 v29, v25
	v_sub_f32_e32 v25, v5, v27
	v_min_f32_e32 v25, 0x42a00000, v25
	v_mul_f32_e32 v25, 0x3fb8aa3b, v25
	v_exp_f32_e32 v25, v25
	v_mul_f32_e32 v2, 0x3fb8aa3b, v27
	v_cmp_gt_f32_e32 vcc, s35, v22
	v_mul_f32_e32 v23, v23, v25
	v_exp_f32_e32 v25, v2
	v_cvt_pk_bf16_f32 v23, v23, s0
	ds_write_b16 v126, v23 offset:15696
	s_waitcnt vmcnt(1)
	v_lshlrev_b32_e32 v2, 16, v28
	s_waitcnt vmcnt(0)
; #define LAS __attribute__((address_space(3)))
; __device__ __forceinline__ float bf2f(unsigned v) { return __uint_as_float(v << 16); }
; __device__ __forceinline__ unsigned pk2(float lo, float hi) { const f32x2_t v = {lo, hi}; const bf16x2_t b = __builtin_convertvector(v, bf16x2_t); return __builtin_bit_cast(unsigned, b); }
; __device__ __forceinline__ unsigned f2bf(float f) { return pk2(f, 0.f) & 0xffffu; }
; __device__ __forceinline__ void hgrn_out_phase(const Ctx& F, const Args& a, int l) {
;     ...
;             unsigned qh[32]; float cum = 0.f, qh_prev = 0.f;
; #pragma unroll
;             for (int t = 0; t < 64; ++t) {
;                 const float qv = bf2f(PB[(size_t)(rb + (dir ? 63 - t : t)) * INW + colq]) * 0.125f;
;                 cum += __logf(fv[t]);
;                 const float qt = qv * __expf(fminf(cum - ref, 80.f));
;                 const float kt = (1.0f - fv[t]) * __expf(fminf(ref - cum, 80.f));
;                 const float qhv = qv * __expf(cum);
;                 *(LAS bf16_t*)(TQ + t * TP + 2 * lane) = (bf16_t)f2bf(qt);
;                 *(LAS bf16_t*)(TK + t * TP + 2 * lane) = (bf16_t)f2bf(kt);
;                 if (t & 1) qh[t >> 1] = pk2(qh_prev, qhv); else qh_prev = qhv;
;             }
	v_lshlrev_b32_e32 v3, 16, v3
	v_pk_mul_f32 v[2:3], v[2:3], s[8:9] op_sel_hi:[1,0]
	s_nop 0
	v_mul_f32_e32 v23, v26, v2
	v_cvt_pk_bf16_f32 v23, v23, s0
	ds_write_b16 v126, v23 offset:6336
	v_mul_f32_e32 v23, v29, v3
	v_cvt_pk_bf16_f32 v23, v23, s0
	ds_write_b16 v126, v23 offset:6480
	v_cndmask_b32_e64 v23, 0, 32, vcc
	v_ldexp_f32 v23, v22, v23
	v_log_f32_e32 v23, v23
	v_pk_mul_f32 v[2:3], v[24:25], v[2:3]
	v_sub_f32_e32 v22, 1.0, v22
	v_cvt_pk_bf16_f32 v56, v2, v3
	v_mul_f32_e32 v24, 0x3f317217, v23
	v_fma_f32 v24, v23, s31, -v24
	v_mad_i64_i32 v[2:3], s[4:5], s51, v205, v[108:109]
	v_fmac_f32_e32 v24, 0x3377d1cf, v23
	v_fmac_f32_e32 v24, 0x3f317217, v23
	v_cmp_lt_f32_e64 s[4:5], |v23|, s34
	global_load_ushort v26, v[2:3], off offset:1024
	s_nop 0
	v_cndmask_b32_e64 v23, v23, v24, s[4:5]
	v_mad_i64_i32 v[2:3], s[4:5], s50, v205, v[108:109]
	global_load_ushort v3, v[2:3], off offset:1024
	v_cndmask_b32_e32 v24, 0, v206, vcc
	v_sub_f32_e32 v23, v23, v24
	v_add_f32_e32 v23, v23, v27
	v_sub_f32_e32 v25, v5, v23
	v_min_f32_e32 v25, 0x42a00000, v25
	v_mul_f32_e32 v25, 0x3fb8aa3b, v25
	v_exp_f32_e32 v25, v25
	v_cmp_gt_f32_e32 vcc, s35, v21
	v_sub_f32_e32 v24, v23, v5
	v_min_f32_e32 v24, 0x42a00000, v24
	v_mul_f32_e32 v25, v22, v25
	v_cvt_pk_bf16_f32 v25, v25, s0
	ds_write_b16 v126, v25 offset:15840
	v_cndmask_b32_e64 v25, 0, 32, vcc
	v_ldexp_f32 v25, v21, v25
	v_log_f32_e32 v25, v25
	v_mul_f32_e32 v22, 0x3fb8aa3b, v23
	v_mul_f32_e32 v24, 0x3fb8aa3b, v24
	v_exp_f32_e32 v24, v24
	v_mul_f32_e32 v27, 0x3f317217, v25
	v_fma_f32 v27, v25, s31, -v27
	v_fmac_f32_e32 v27, 0x3377d1cf, v25
	v_fmac_f32_e32 v27, 0x3f317217, v25
	v_cmp_lt_f32_e64 s[4:5], |v25|, s34
	v_sub_f32_e32 v21, 1.0, v21
	v_exp_f32_e32 v22, v22
	v_cndmask_b32_e64 v25, v25, v27, s[4:5]
	v_cndmask_b32_e32 v27, 0, v206, vcc
	v_sub_f32_e32 v25, v25, v27
	v_add_f32_e32 v25, v25, v23
	v_sub_f32_e32 v23, v25, v5
	v_min_f32_e32 v23, 0x42a00000, v23
	v_mul_f32_e32 v23, 0x3fb8aa3b, v23
	v_exp_f32_e32 v27, v23
	v_sub_f32_e32 v23, v5, v25
	v_min_f32_e32 v23, 0x42a00000, v23
	v_mul_f32_e32 v23, 0x3fb8aa3b, v23
	v_exp_f32_e32 v23, v23
	v_mul_f32_e32 v2, 0x3fb8aa3b, v25
	v_cmp_gt_f32_e32 vcc, s35, v20
	v_mul_f32_e32 v21, v21, v23
	v_exp_f32_e32 v23, v2
	v_cvt_pk_bf16_f32 v21, v21, s0
	ds_write_b16 v126, v21 offset:15984
	s_waitcnt vmcnt(1)
	v_lshlrev_b32_e32 v2, 16, v26
	s_waitcnt vmcnt(0)
	v_lshlrev_b32_e32 v3, 16, v3
	v_pk_mul_f32 v[2:3], v[2:3], s[8:9] op_sel_hi:[1,0]
	s_nop 0
	v_mul_f32_e32 v21, v24, v2
	v_cvt_pk_bf16_f32 v21, v21, s0
	ds_write_b16 v126, v21 offset:6624
	v_mul_f32_e32 v21, v27, v3
	v_cvt_pk_bf16_f32 v21, v21, s0
	ds_write_b16 v126, v21 offset:6768
	v_cndmask_b32_e64 v21, 0, 32, vcc
	v_ldexp_f32 v21, v20, v21
	v_log_f32_e32 v21, v21
	v_pk_mul_f32 v[2:3], v[22:23], v[2:3]
	v_sub_f32_e32 v20, 1.0, v20
	v_cvt_pk_bf16_f32 v57, v2, v3
	v_mul_f32_e32 v22, 0x3f317217, v21
	v_fma_f32 v22, v21, s31, -v22
	v_mad_i64_i32 v[2:3], s[4:5], s49, v205, v[108:109]
	v_fmac_f32_e32 v22, 0x3377d1cf, v21
	v_fmac_f32_e32 v22, 0x3f317217, v21
	v_cmp_lt_f32_e64 s[4:5], |v21|, s34
	global_load_ushort v24, v[2:3], off offset:1024
	s_nop 0
	v_cndmask_b32_e64 v21, v21, v22, s[4:5]
	v_mad_i64_i32 v[2:3], s[4:5], s48, v205, v[108:109]
	global_load_ushort v3, v[2:3], off offset:1024
	v_cndmask_b32_e32 v22, 0, v206, vcc
	v_sub_f32_e32 v21, v21, v22
	v_add_f32_e32 v21, v21, v25
	v_sub_f32_e32 v23, v5, v21
	v_min_f32_e32 v23, 0x42a00000, v23
	v_mul_f32_e32 v23, 0x3fb8aa3b, v23
	v_exp_f32_e32 v23, v23
	v_cmp_gt_f32_e32 vcc, s35, v19
	v_sub_f32_e32 v22, v21, v5
	v_min_f32_e32 v22, 0x42a00000, v22
	v_mul_f32_e32 v23, v20, v23
	v_cvt_pk_bf16_f32 v23, v23, s0
	ds_write_b16 v126, v23 offset:16128
	v_cndmask_b32_e64 v23, 0, 32, vcc
	v_ldexp_f32 v23, v19, v23
	v_log_f32_e32 v23, v23
	v_mul_f32_e32 v20, 0x3fb8aa3b, v21
	v_mul_f32_e32 v22, 0x3fb8aa3b, v22
	v_exp_f32_e32 v22, v22
	v_mul_f32_e32 v25, 0x3f317217, v23
	v_fma_f32 v25, v23, s31, -v25
	v_fmac_f32_e32 v25, 0x3377d1cf, v23
	v_fmac_f32_e32 v25, 0x3f317217, v23
	v_cmp_lt_f32_e64 s[4:5], |v23|, s34
	v_sub_f32_e32 v19, 1.0, v19
	v_exp_f32_e32 v20, v20
	v_cndmask_b32_e64 v23, v23, v25, s[4:5]
	v_cndmask_b32_e32 v25, 0, v206, vcc
	v_sub_f32_e32 v23, v23, v25
	v_add_f32_e32 v23, v23, v21
	v_sub_f32_e32 v21, v23, v5
	v_min_f32_e32 v21, 0x42a00000, v21
	v_mul_f32_e32 v21, 0x3fb8aa3b, v21
	v_exp_f32_e32 v25, v21
	v_sub_f32_e32 v21, v5, v23
	v_min_f32_e32 v21, 0x42a00000, v21
	v_mul_f32_e32 v21, 0x3fb8aa3b, v21
	v_exp_f32_e32 v21, v21
	v_mul_f32_e32 v2, 0x3fb8aa3b, v23
	v_cmp_gt_f32_e32 vcc, s35, v18
	v_mul_f32_e32 v19, v19, v21
	v_exp_f32_e32 v21, v2
	v_cvt_pk_bf16_f32 v19, v19, s0
	ds_write_b16 v126, v19 offset:16272
	s_waitcnt vmcnt(1)
	v_lshlrev_b32_e32 v2, 16, v24
	s_waitcnt vmcnt(0)
; #define LAS __attribute__((address_space(3)))
; __device__ __forceinline__ float bf2f(unsigned v) { return __uint_as_float(v << 16); }
; __device__ __forceinline__ unsigned pk2(float lo, float hi) { const f32x2_t v = {lo, hi}; const bf16x2_t b = __builtin_convertvector(v, bf16x2_t); return __builtin_bit_cast(unsigned, b); }
; __device__ __forceinline__ unsigned f2bf(float f) { return pk2(f, 0.f) & 0xffffu; }
; __device__ __forceinline__ void hgrn_out_phase(const Ctx& F, const Args& a, int l) {
;     ...
;             unsigned qh[32]; float cum = 0.f, qh_prev = 0.f;
; #pragma unroll
;             for (int t = 0; t < 64; ++t) {
;                 const float qv = bf2f(PB[(size_t)(rb + (dir ? 63 - t : t)) * INW + colq]) * 0.125f;
;                 cum += __logf(fv[t]);
;                 const float qt = qv * __expf(fminf(cum - ref, 80.f));
;                 const float kt = (1.0f - fv[t]) * __expf(fminf(ref - cum, 80.f));
;                 const float qhv = qv * __expf(cum);
;                 *(LAS bf16_t*)(TQ + t * TP + 2 * lane) = (bf16_t)f2bf(qt);
;                 *(LAS bf16_t*)(TK + t * TP + 2 * lane) = (bf16_t)f2bf(kt);
;                 if (t & 1) qh[t >> 1] = pk2(qh_prev, qhv); else qh_prev = qhv;
;             }
	v_lshlrev_b32_e32 v3, 16, v3
	v_pk_mul_f32 v[2:3], v[2:3], s[8:9] op_sel_hi:[1,0]
	s_nop 0
	v_mul_f32_e32 v19, v22, v2
	v_cvt_pk_bf16_f32 v19, v19, s0
	ds_write_b16 v126, v19 offset:6912
	v_mul_f32_e32 v19, v25, v3
	v_cvt_pk_bf16_f32 v19, v19, s0
	ds_write_b16 v126, v19 offset:7056
	v_cndmask_b32_e64 v19, 0, 32, vcc
	v_ldexp_f32 v19, v18, v19
	v_log_f32_e32 v19, v19
	v_pk_mul_f32 v[2:3], v[20:21], v[2:3]
	v_sub_f32_e32 v18, 1.0, v18
	v_cvt_pk_bf16_f32 v58, v2, v3
	v_mul_f32_e32 v20, 0x3f317217, v19
	v_fma_f32 v20, v19, s31, -v20
	v_mad_i64_i32 v[2:3], s[4:5], s38, v205, v[108:109]
	v_fmac_f32_e32 v20, 0x3377d1cf, v19
	v_fmac_f32_e32 v20, 0x3f317217, v19
	v_cmp_lt_f32_e64 s[4:5], |v19|, s34
	global_load_ushort v22, v[2:3], off offset:1024
	s_nop 0
	v_cndmask_b32_e64 v19, v19, v20, s[4:5]
	v_mad_i64_i32 v[2:3], s[4:5], s81, v205, v[108:109]
	global_load_ushort v3, v[2:3], off offset:1024
	v_cndmask_b32_e32 v20, 0, v206, vcc
	v_sub_f32_e32 v19, v19, v20
	v_add_f32_e32 v19, v19, v23
	v_sub_f32_e32 v21, v5, v19
	v_min_f32_e32 v21, 0x42a00000, v21
	v_mul_f32_e32 v21, 0x3fb8aa3b, v21
	v_exp_f32_e32 v21, v21
	v_cmp_gt_f32_e32 vcc, s35, v17
	v_sub_f32_e32 v20, v19, v5
	v_min_f32_e32 v20, 0x42a00000, v20
	v_mul_f32_e32 v21, v18, v21
	v_cvt_pk_bf16_f32 v21, v21, s0
	ds_write_b16 v126, v21 offset:16416
	v_cndmask_b32_e64 v21, 0, 32, vcc
	v_ldexp_f32 v21, v17, v21
	v_log_f32_e32 v21, v21
	v_mul_f32_e32 v18, 0x3fb8aa3b, v19
	v_mul_f32_e32 v20, 0x3fb8aa3b, v20
	v_exp_f32_e32 v20, v20
	v_mul_f32_e32 v23, 0x3f317217, v21
	v_fma_f32 v23, v21, s31, -v23
	v_fmac_f32_e32 v23, 0x3377d1cf, v21
	v_fmac_f32_e32 v23, 0x3f317217, v21
	v_cmp_lt_f32_e64 s[4:5], |v21|, s34
	v_sub_f32_e32 v17, 1.0, v17
	v_exp_f32_e32 v18, v18
	v_cndmask_b32_e64 v21, v21, v23, s[4:5]
	v_cndmask_b32_e32 v23, 0, v206, vcc
	v_sub_f32_e32 v21, v21, v23
	v_add_f32_e32 v21, v21, v19
	v_sub_f32_e32 v19, v21, v5
	v_min_f32_e32 v19, 0x42a00000, v19
	v_mul_f32_e32 v19, 0x3fb8aa3b, v19
	v_exp_f32_e32 v23, v19
	v_sub_f32_e32 v19, v5, v21
	v_min_f32_e32 v19, 0x42a00000, v19
	v_mul_f32_e32 v19, 0x3fb8aa3b, v19
	v_exp_f32_e32 v19, v19
	v_mul_f32_e32 v2, 0x3fb8aa3b, v21
	v_cmp_gt_f32_e32 vcc, s35, v16
	v_mul_f32_e32 v17, v17, v19
	v_exp_f32_e32 v19, v2
	v_cvt_pk_bf16_f32 v17, v17, s0
	ds_write_b16 v126, v17 offset:16560
	s_waitcnt vmcnt(1)
	v_lshlrev_b32_e32 v2, 16, v22
	s_waitcnt vmcnt(0)
	v_lshlrev_b32_e32 v3, 16, v3
	v_pk_mul_f32 v[2:3], v[2:3], s[8:9] op_sel_hi:[1,0]
	s_nop 0
	v_mul_f32_e32 v17, v20, v2
	v_cvt_pk_bf16_f32 v17, v17, s0
	ds_write_b16 v126, v17 offset:7200
	v_mul_f32_e32 v17, v23, v3
	v_cvt_pk_bf16_f32 v17, v17, s0
	ds_write_b16 v126, v17 offset:7344
	v_cndmask_b32_e64 v17, 0, 32, vcc
	v_ldexp_f32 v17, v16, v17
	v_log_f32_e32 v17, v17
	v_pk_mul_f32 v[2:3], v[18:19], v[2:3]
	v_sub_f32_e32 v16, 1.0, v16
	v_cvt_pk_bf16_f32 v59, v2, v3
	v_mul_f32_e32 v18, 0x3f317217, v17
	v_fma_f32 v18, v17, s31, -v18
	v_mad_i64_i32 v[2:3], s[4:5], s80, v205, v[108:109]
	v_fmac_f32_e32 v18, 0x3377d1cf, v17
	v_fmac_f32_e32 v18, 0x3f317217, v17
	v_cmp_lt_f32_e64 s[4:5], |v17|, s34
	global_load_ushort v20, v[2:3], off offset:1024
	s_nop 0
	v_cndmask_b32_e64 v17, v17, v18, s[4:5]
	v_mad_i64_i32 v[2:3], s[4:5], s95, v205, v[108:109]
	global_load_ushort v3, v[2:3], off offset:1024
	v_cndmask_b32_e32 v18, 0, v206, vcc
	v_sub_f32_e32 v17, v17, v18
	v_add_f32_e32 v17, v17, v21
	v_sub_f32_e32 v19, v5, v17
	v_min_f32_e32 v19, 0x42a00000, v19
	v_mul_f32_e32 v19, 0x3fb8aa3b, v19
	v_exp_f32_e32 v19, v19
	v_cmp_gt_f32_e32 vcc, s35, v15
	v_sub_f32_e32 v18, v17, v5
	v_min_f32_e32 v18, 0x42a00000, v18
	v_mul_f32_e32 v19, v16, v19
	v_cvt_pk_bf16_f32 v19, v19, s0
	ds_write_b16 v126, v19 offset:16704
	v_cndmask_b32_e64 v19, 0, 32, vcc
	v_ldexp_f32 v19, v15, v19
	v_log_f32_e32 v19, v19
	v_mul_f32_e32 v16, 0x3fb8aa3b, v17
	v_mul_f32_e32 v18, 0x3fb8aa3b, v18
	v_exp_f32_e32 v18, v18
	v_mul_f32_e32 v21, 0x3f317217, v19
	v_fma_f32 v21, v19, s31, -v21
	v_fmac_f32_e32 v21, 0x3377d1cf, v19
	v_fmac_f32_e32 v21, 0x3f317217, v19
	v_cmp_lt_f32_e64 s[4:5], |v19|, s34
	v_sub_f32_e32 v15, 1.0, v15
	v_exp_f32_e32 v16, v16
	v_cndmask_b32_e64 v19, v19, v21, s[4:5]
	v_cndmask_b32_e32 v21, 0, v206, vcc
	v_sub_f32_e32 v19, v19, v21
	v_add_f32_e32 v19, v19, v17
	v_sub_f32_e32 v17, v19, v5
	v_min_f32_e32 v17, 0x42a00000, v17
	v_mul_f32_e32 v17, 0x3fb8aa3b, v17
	v_exp_f32_e32 v21, v17
	v_sub_f32_e32 v17, v5, v19
	v_min_f32_e32 v17, 0x42a00000, v17
	v_mul_f32_e32 v17, 0x3fb8aa3b, v17
	v_exp_f32_e32 v17, v17
	v_mul_f32_e32 v2, 0x3fb8aa3b, v19
	v_cmp_gt_f32_e32 vcc, s35, v14
	v_mul_f32_e32 v15, v15, v17
	v_exp_f32_e32 v17, v2
	v_cvt_pk_bf16_f32 v15, v15, s0
	ds_write_b16 v126, v15 offset:16848
	s_waitcnt vmcnt(1)
	v_lshlrev_b32_e32 v2, 16, v20
	s_waitcnt vmcnt(0)
; #define LAS __attribute__((address_space(3)))
; __device__ __forceinline__ float bf2f(unsigned v) { return __uint_as_float(v << 16); }
; __device__ __forceinline__ unsigned pk2(float lo, float hi) { const f32x2_t v = {lo, hi}; const bf16x2_t b = __builtin_convertvector(v, bf16x2_t); return __builtin_bit_cast(unsigned, b); }
; __device__ __forceinline__ unsigned f2bf(float f) { return pk2(f, 0.f) & 0xffffu; }
; __device__ __forceinline__ void hgrn_out_phase(const Ctx& F, const Args& a, int l) {
;     ...
;             unsigned qh[32]; float cum = 0.f, qh_prev = 0.f;
; #pragma unroll
;             for (int t = 0; t < 64; ++t) {
;                 const float qv = bf2f(PB[(size_t)(rb + (dir ? 63 - t : t)) * INW + colq]) * 0.125f;
;                 cum += __logf(fv[t]);
;                 const float qt = qv * __expf(fminf(cum - ref, 80.f));
;                 const float kt = (1.0f - fv[t]) * __expf(fminf(ref - cum, 80.f));
;                 const float qhv = qv * __expf(cum);
;                 *(LAS bf16_t*)(TQ + t * TP + 2 * lane) = (bf16_t)f2bf(qt);
;                 *(LAS bf16_t*)(TK + t * TP + 2 * lane) = (bf16_t)f2bf(kt);
;                 if (t & 1) qh[t >> 1] = pk2(qh_prev, qhv); else qh_prev = qhv;
;             }
	v_lshlrev_b32_e32 v3, 16, v3
	v_pk_mul_f32 v[2:3], v[2:3], s[8:9] op_sel_hi:[1,0]
	s_nop 0
	v_mul_f32_e32 v15, v18, v2
	v_cvt_pk_bf16_f32 v15, v15, s0
	ds_write_b16 v126, v15 offset:7488
	v_mul_f32_e32 v15, v21, v3
	v_cvt_pk_bf16_f32 v15, v15, s0
	ds_write_b16 v126, v15 offset:7632
	v_cndmask_b32_e64 v15, 0, 32, vcc
	v_ldexp_f32 v15, v14, v15
	v_log_f32_e32 v15, v15
	v_pk_mul_f32 v[2:3], v[16:17], v[2:3]
	v_sub_f32_e32 v14, 1.0, v14
	v_cvt_pk_bf16_f32 v60, v2, v3
	v_mul_f32_e32 v16, 0x3f317217, v15
	v_fma_f32 v16, v15, s31, -v16
	v_mad_i64_i32 v[2:3], s[4:5], s94, v205, v[108:109]
	v_fmac_f32_e32 v16, 0x3377d1cf, v15
	v_fmac_f32_e32 v16, 0x3f317217, v15
	v_cmp_lt_f32_e64 s[4:5], |v15|, s34
	global_load_ushort v18, v[2:3], off offset:1024
	s_nop 0
	v_cndmask_b32_e64 v15, v15, v16, s[4:5]
	v_mad_i64_i32 v[2:3], s[4:5], s93, v205, v[108:109]
	global_load_ushort v3, v[2:3], off offset:1024
	v_cndmask_b32_e32 v16, 0, v206, vcc
	v_sub_f32_e32 v15, v15, v16
	v_add_f32_e32 v15, v15, v19
	v_sub_f32_e32 v17, v5, v15
	v_min_f32_e32 v17, 0x42a00000, v17
	v_mul_f32_e32 v17, 0x3fb8aa3b, v17
	v_exp_f32_e32 v17, v17
	v_cmp_gt_f32_e32 vcc, s35, v13
	v_sub_f32_e32 v16, v15, v5
	v_min_f32_e32 v16, 0x42a00000, v16
	v_mul_f32_e32 v17, v14, v17
	v_cvt_pk_bf16_f32 v17, v17, s0
	ds_write_b16 v126, v17 offset:16992
	v_cndmask_b32_e64 v17, 0, 32, vcc
	v_ldexp_f32 v17, v13, v17
	v_log_f32_e32 v17, v17
	v_mul_f32_e32 v14, 0x3fb8aa3b, v15
	v_mul_f32_e32 v16, 0x3fb8aa3b, v16
	v_exp_f32_e32 v16, v16
	v_mul_f32_e32 v19, 0x3f317217, v17
	v_fma_f32 v19, v17, s31, -v19
	v_fmac_f32_e32 v19, 0x3377d1cf, v17
	v_fmac_f32_e32 v19, 0x3f317217, v17
	v_cmp_lt_f32_e64 s[4:5], |v17|, s34
	v_sub_f32_e32 v13, 1.0, v13
	v_exp_f32_e32 v14, v14
	v_cndmask_b32_e64 v17, v17, v19, s[4:5]
	v_cndmask_b32_e32 v19, 0, v206, vcc
	v_sub_f32_e32 v17, v17, v19
	v_add_f32_e32 v17, v17, v15
	v_sub_f32_e32 v15, v17, v5
	v_min_f32_e32 v15, 0x42a00000, v15
	v_mul_f32_e32 v15, 0x3fb8aa3b, v15
	v_exp_f32_e32 v19, v15
	v_sub_f32_e32 v15, v5, v17
	v_min_f32_e32 v15, 0x42a00000, v15
	v_mul_f32_e32 v15, 0x3fb8aa3b, v15
	v_exp_f32_e32 v15, v15
	v_mul_f32_e32 v2, 0x3fb8aa3b, v17
	v_cmp_gt_f32_e32 vcc, s35, v12
	v_mul_f32_e32 v13, v13, v15
	v_exp_f32_e32 v15, v2
	v_cvt_pk_bf16_f32 v13, v13, s0
	ds_write_b16 v126, v13 offset:17136
	s_waitcnt vmcnt(1)
	v_lshlrev_b32_e32 v2, 16, v18
	s_waitcnt vmcnt(0)
	v_lshlrev_b32_e32 v3, 16, v3
	v_pk_mul_f32 v[2:3], v[2:3], s[8:9] op_sel_hi:[1,0]
	s_nop 0
	v_mul_f32_e32 v13, v16, v2
	v_cvt_pk_bf16_f32 v13, v13, s0
	ds_write_b16 v126, v13 offset:7776
	v_mul_f32_e32 v13, v19, v3
	v_cvt_pk_bf16_f32 v13, v13, s0
	ds_write_b16 v126, v13 offset:7920
	v_cndmask_b32_e64 v13, 0, 32, vcc
	v_ldexp_f32 v13, v12, v13
	v_log_f32_e32 v13, v13
	v_pk_mul_f32 v[2:3], v[14:15], v[2:3]
	v_sub_f32_e32 v12, 1.0, v12
	v_cvt_pk_bf16_f32 v61, v2, v3
	v_mul_f32_e32 v14, 0x3f317217, v13
	v_fma_f32 v14, v13, s31, -v14
	v_mad_i64_i32 v[2:3], s[4:5], s92, v205, v[108:109]
	v_fmac_f32_e32 v14, 0x3377d1cf, v13
	v_fmac_f32_e32 v14, 0x3f317217, v13
	v_cmp_lt_f32_e64 s[4:5], |v13|, s34
	global_load_ushort v16, v[2:3], off offset:1024
	s_nop 0
	v_cndmask_b32_e64 v13, v13, v14, s[4:5]
	v_mad_i64_i32 v[2:3], s[4:5], s91, v205, v[108:109]
	global_load_ushort v3, v[2:3], off offset:1024
	v_cndmask_b32_e32 v14, 0, v206, vcc
	v_sub_f32_e32 v13, v13, v14
	v_add_f32_e32 v13, v13, v17
	v_sub_f32_e32 v15, v5, v13
	v_min_f32_e32 v15, 0x42a00000, v15
	v_mul_f32_e32 v15, 0x3fb8aa3b, v15
	v_exp_f32_e32 v15, v15
	v_cmp_gt_f32_e32 vcc, s35, v11
	v_sub_f32_e32 v14, v13, v5
	v_min_f32_e32 v14, 0x42a00000, v14
	v_mul_f32_e32 v15, v12, v15
	v_cvt_pk_bf16_f32 v15, v15, s0
	ds_write_b16 v126, v15 offset:17280
	v_cndmask_b32_e64 v15, 0, 32, vcc
	v_ldexp_f32 v15, v11, v15
	v_log_f32_e32 v15, v15
	v_mul_f32_e32 v12, 0x3fb8aa3b, v13
	v_mul_f32_e32 v14, 0x3fb8aa3b, v14
	v_exp_f32_e32 v14, v14
	v_mul_f32_e32 v17, 0x3f317217, v15
	v_fma_f32 v17, v15, s31, -v17
	v_fmac_f32_e32 v17, 0x3377d1cf, v15
	v_fmac_f32_e32 v17, 0x3f317217, v15
	v_cmp_lt_f32_e64 s[4:5], |v15|, s34
	v_sub_f32_e32 v11, 1.0, v11
	v_exp_f32_e32 v12, v12
	v_cndmask_b32_e64 v15, v15, v17, s[4:5]
	v_cndmask_b32_e32 v17, 0, v206, vcc
	v_sub_f32_e32 v15, v15, v17
	v_add_f32_e32 v15, v15, v13
	v_sub_f32_e32 v13, v15, v5
	v_min_f32_e32 v13, 0x42a00000, v13
	v_mul_f32_e32 v13, 0x3fb8aa3b, v13
	v_exp_f32_e32 v17, v13
	v_sub_f32_e32 v13, v5, v15
	v_min_f32_e32 v13, 0x42a00000, v13
	v_mul_f32_e32 v13, 0x3fb8aa3b, v13
	v_exp_f32_e32 v13, v13
	v_mul_f32_e32 v2, 0x3fb8aa3b, v15
	v_cmp_gt_f32_e32 vcc, s35, v10
	v_mul_f32_e32 v11, v11, v13
	v_exp_f32_e32 v13, v2
	v_cvt_pk_bf16_f32 v11, v11, s0
	ds_write_b16 v126, v11 offset:17424
	s_waitcnt vmcnt(1)
	v_lshlrev_b32_e32 v2, 16, v16
	s_waitcnt vmcnt(0)
; #define LAS __attribute__((address_space(3)))
; __device__ __forceinline__ float bf2f(unsigned v) { return __uint_as_float(v << 16); }
; __device__ __forceinline__ unsigned pk2(float lo, float hi) { const f32x2_t v = {lo, hi}; const bf16x2_t b = __builtin_convertvector(v, bf16x2_t); return __builtin_bit_cast(unsigned, b); }
; __device__ __forceinline__ unsigned f2bf(float f) { return pk2(f, 0.f) & 0xffffu; }
; __device__ __forceinline__ void hgrn_out_phase(const Ctx& F, const Args& a, int l) {
;     ...
;             unsigned qh[32]; float cum = 0.f, qh_prev = 0.f;
; #pragma unroll
;             for (int t = 0; t < 64; ++t) {
;                 const float qv = bf2f(PB[(size_t)(rb + (dir ? 63 - t : t)) * INW + colq]) * 0.125f;
;                 cum += __logf(fv[t]);
;                 const float qt = qv * __expf(fminf(cum - ref, 80.f));
;                 const float kt = (1.0f - fv[t]) * __expf(fminf(ref - cum, 80.f));
;                 const float qhv = qv * __expf(cum);
;                 *(LAS bf16_t*)(TQ + t * TP + 2 * lane) = (bf16_t)f2bf(qt);
;                 *(LAS bf16_t*)(TK + t * TP + 2 * lane) = (bf16_t)f2bf(kt);
;                 if (t & 1) qh[t >> 1] = pk2(qh_prev, qhv); else qh_prev = qhv;
;             }
	v_lshlrev_b32_e32 v3, 16, v3
	v_pk_mul_f32 v[2:3], v[2:3], s[8:9] op_sel_hi:[1,0]
	s_nop 0
	v_mul_f32_e32 v11, v14, v2
	v_cvt_pk_bf16_f32 v11, v11, s0
	ds_write_b16 v126, v11 offset:8064
	v_mul_f32_e32 v11, v17, v3
	v_cvt_pk_bf16_f32 v11, v11, s0
	ds_write_b16 v126, v11 offset:8208
	v_cndmask_b32_e64 v11, 0, 32, vcc
	v_ldexp_f32 v11, v10, v11
	v_log_f32_e32 v11, v11
	v_pk_mul_f32 v[2:3], v[12:13], v[2:3]
	v_sub_f32_e32 v10, 1.0, v10
	v_cvt_pk_bf16_f32 v62, v2, v3
	v_mul_f32_e32 v12, 0x3f317217, v11
	v_fma_f32 v12, v11, s31, -v12
	v_mad_i64_i32 v[2:3], s[4:5], s90, v205, v[108:109]
	v_fmac_f32_e32 v12, 0x3377d1cf, v11
	v_fmac_f32_e32 v12, 0x3f317217, v11
	v_cmp_lt_f32_e64 s[4:5], |v11|, s34
	global_load_ushort v14, v[2:3], off offset:1024
	s_nop 0
	v_cndmask_b32_e64 v11, v11, v12, s[4:5]
	v_mad_i64_i32 v[2:3], s[4:5], s89, v205, v[108:109]
	global_load_ushort v3, v[2:3], off offset:1024
	v_cndmask_b32_e32 v12, 0, v206, vcc
	v_sub_f32_e32 v11, v11, v12
	v_add_f32_e32 v11, v11, v15
	v_sub_f32_e32 v13, v5, v11
	v_min_f32_e32 v13, 0x42a00000, v13
	v_mul_f32_e32 v13, 0x3fb8aa3b, v13
	v_exp_f32_e32 v13, v13
	v_cmp_gt_f32_e32 vcc, s35, v9
	v_sub_f32_e32 v12, v11, v5
	v_min_f32_e32 v12, 0x42a00000, v12
	v_mul_f32_e32 v13, v10, v13
	v_cvt_pk_bf16_f32 v13, v13, s0
	ds_write_b16 v126, v13 offset:17568
	v_cndmask_b32_e64 v13, 0, 32, vcc
	v_ldexp_f32 v13, v9, v13
	v_log_f32_e32 v13, v13
	v_mul_f32_e32 v10, 0x3fb8aa3b, v11
	v_mul_f32_e32 v12, 0x3fb8aa3b, v12
	v_exp_f32_e32 v12, v12
	v_mul_f32_e32 v15, 0x3f317217, v13
	v_fma_f32 v15, v13, s31, -v15
	v_fmac_f32_e32 v15, 0x3377d1cf, v13
	v_fmac_f32_e32 v15, 0x3f317217, v13
	v_cmp_lt_f32_e64 s[4:5], |v13|, s34
	v_sub_f32_e32 v9, 1.0, v9
	v_exp_f32_e32 v10, v10
	v_cndmask_b32_e64 v13, v13, v15, s[4:5]
	v_cndmask_b32_e32 v15, 0, v206, vcc
	v_sub_f32_e32 v13, v13, v15
	v_add_f32_e32 v13, v13, v11
	v_sub_f32_e32 v11, v13, v5
	v_min_f32_e32 v11, 0x42a00000, v11
	v_mul_f32_e32 v11, 0x3fb8aa3b, v11
	v_exp_f32_e32 v15, v11
	v_sub_f32_e32 v11, v5, v13
	v_min_f32_e32 v11, 0x42a00000, v11
	v_mul_f32_e32 v11, 0x3fb8aa3b, v11
	v_exp_f32_e32 v11, v11
	v_mul_f32_e32 v2, 0x3fb8aa3b, v13
	v_cmp_gt_f32_e32 vcc, s35, v8
	v_mul_f32_e32 v9, v9, v11
	v_exp_f32_e32 v11, v2
	v_cvt_pk_bf16_f32 v9, v9, s0
	ds_write_b16 v126, v9 offset:17712
	s_waitcnt vmcnt(1)
	v_lshlrev_b32_e32 v2, 16, v14
	s_waitcnt vmcnt(0)
	v_lshlrev_b32_e32 v3, 16, v3
	v_pk_mul_f32 v[2:3], v[2:3], s[8:9] op_sel_hi:[1,0]
	s_nop 0
	v_mul_f32_e32 v9, v12, v2
	v_cvt_pk_bf16_f32 v9, v9, s0
	ds_write_b16 v126, v9 offset:8352
	v_mul_f32_e32 v9, v15, v3
	v_cvt_pk_bf16_f32 v9, v9, s0
	ds_write_b16 v126, v9 offset:8496
	v_cndmask_b32_e64 v9, 0, 32, vcc
	v_ldexp_f32 v9, v8, v9
	v_log_f32_e32 v9, v9
	v_pk_mul_f32 v[2:3], v[10:11], v[2:3]
	v_sub_f32_e32 v8, 1.0, v8
	v_cvt_pk_bf16_f32 v63, v2, v3
	v_mul_f32_e32 v10, 0x3f317217, v9
	v_fma_f32 v10, v9, s31, -v10
	v_mad_i64_i32 v[2:3], s[4:5], s88, v205, v[108:109]
	v_fmac_f32_e32 v10, 0x3377d1cf, v9
	v_fmac_f32_e32 v10, 0x3f317217, v9
	v_cmp_lt_f32_e64 s[4:5], |v9|, s34
	global_load_ushort v12, v[2:3], off offset:1024
	s_nop 0
	v_cndmask_b32_e64 v9, v9, v10, s[4:5]
	v_mad_i64_i32 v[2:3], s[4:5], s87, v205, v[108:109]
	global_load_ushort v3, v[2:3], off offset:1024
	v_cndmask_b32_e32 v10, 0, v206, vcc
	v_sub_f32_e32 v9, v9, v10
	v_add_f32_e32 v9, v9, v13
	v_sub_f32_e32 v11, v5, v9
	v_min_f32_e32 v11, 0x42a00000, v11
	v_mul_f32_e32 v11, 0x3fb8aa3b, v11
	v_exp_f32_e32 v11, v11
	v_cmp_gt_f32_e32 vcc, s35, v7
	v_sub_f32_e32 v10, v9, v5
	v_min_f32_e32 v10, 0x42a00000, v10
	v_mul_f32_e32 v11, v8, v11
	v_cvt_pk_bf16_f32 v11, v11, s0
	ds_write_b16 v126, v11 offset:17856
	v_cndmask_b32_e64 v11, 0, 32, vcc
	v_ldexp_f32 v11, v7, v11
	v_log_f32_e32 v11, v11
	v_mul_f32_e32 v8, 0x3fb8aa3b, v9
	v_mul_f32_e32 v10, 0x3fb8aa3b, v10
	v_exp_f32_e32 v10, v10
	v_mul_f32_e32 v13, 0x3f317217, v11
	v_fma_f32 v13, v11, s31, -v13
	v_fmac_f32_e32 v13, 0x3377d1cf, v11
	v_fmac_f32_e32 v13, 0x3f317217, v11
	v_cmp_lt_f32_e64 s[4:5], |v11|, s34
	v_sub_f32_e32 v7, 1.0, v7
	v_exp_f32_e32 v8, v8
	v_cndmask_b32_e64 v11, v11, v13, s[4:5]
	v_cndmask_b32_e32 v13, 0, v206, vcc
	v_sub_f32_e32 v11, v11, v13
	v_add_f32_e32 v11, v11, v9
	v_sub_f32_e32 v9, v11, v5
	v_min_f32_e32 v9, 0x42a00000, v9
	v_mul_f32_e32 v9, 0x3fb8aa3b, v9
	v_exp_f32_e32 v13, v9
	v_sub_f32_e32 v9, v5, v11
	v_min_f32_e32 v9, 0x42a00000, v9
	v_mul_f32_e32 v9, 0x3fb8aa3b, v9
	v_exp_f32_e32 v9, v9
	v_mul_f32_e32 v2, 0x3fb8aa3b, v11
	v_cmp_gt_f32_e32 vcc, s35, v6
	v_mul_f32_e32 v7, v7, v9
	v_exp_f32_e32 v9, v2
	v_cvt_pk_bf16_f32 v7, v7, s0
	ds_write_b16 v126, v7 offset:18000
	s_waitcnt vmcnt(1)
	v_lshlrev_b32_e32 v2, 16, v12
	s_waitcnt vmcnt(0)
; #define LAS __attribute__((address_space(3)))
; __device__ __forceinline__ unsigned f2bf(float f) { return pk2(f, 0.f) & 0xffffu; }
; __device__ __forceinline__ void hgrn_out_phase(const Ctx& F, const Args& a, int l) {
;     ...
;             unsigned qh[32]; float cum = 0.f, qh_prev = 0.f;
; #pragma unroll
;             for (int t = 0; t < 64; ++t) {
;                 const float qv = bf2f(PB[(size_t)(rb + (dir ? 63 - t : t)) * INW + colq]) * 0.125f;
;                 cum += __logf(fv[t]);
;                 const float qt = qv * __expf(fminf(cum - ref, 80.f));
;                 const float kt = (1.0f - fv[t]) * __expf(fminf(ref - cum, 80.f));
;                 const float qhv = qv * __expf(cum);
;                 *(LAS bf16_t*)(TQ + t * TP + 2 * lane) = (bf16_t)f2bf(qt);
;                 *(LAS bf16_t*)(TK + t * TP + 2 * lane) = (bf16_t)f2bf(kt);
;                 if (t & 1) qh[t >> 1] = pk2(qh_prev, qhv); else qh_prev = qhv;
;             }
;             asm volatile("s_waitcnt lgkmcnt(0)" ::: "memory");
;             __builtin_amdgcn_wave_barrier();
;             f32x16 a00, a01, a11;
; #pragma unroll
;             for (int r = 0; r < 16; ++r) { a00[r] = 0.f; a01[r] = 0.f; a11[r] = 0.f; }
; #pragma unroll
;             for (int k = 0; k < 4; ++k) {
;                 const bf16x8 ka0 = *(const LAS bf16x8*)(TK + q_ * TP + (16 * k + 8 * h) * 2), ka1 = *(const LAS bf16x8*)(TK + (32 + q_) * TP + (16 * k + 8 * h) * 2);
;                 const bf16x8 qb0 = *(const LAS bf16x8*)(TQ + q_ * TP + (16 * k + 8 * h) * 2), qb1 = *(const LAS bf16x8*)(TQ + (32 + q_) * TP + (16 * k + 8 * h) * 2);
;                 a00 = __builtin_amdgcn_mfma_f32_32x32x16_bf16(ka0, qb0, a00, 0, 0, 0);
;                 a01 = __builtin_amdgcn_mfma_f32_32x32x16_bf16(ka0, qb1, a01, 0, 0, 0);
;                 a11 = __builtin_amdgcn_mfma_f32_32x32x16_bf16(ka1, qb1, a11, 0, 0, 0);
;             }
; #pragma unroll
;             for (int r = 0; r < 16; ++r) { const bool ok = (8 * (r >> 2) + 4 * h + (r & 3)) <= q_; a00[r] = ok ? a00[r] : 0.f; a11[r] = ok ? a11[r] : 0.f; }
;             bf16x8 p00[2], p01[2], p11[2];
; #pragma unroll
;             for (int k = 0; k < 2; ++k) { u32x4 w;
;                 w.x = pk2(a00[8 * k], a00[8 * k + 1]); w.y = pk2(a00[8 * k + 2], a00[8 * k + 3]); w.z = pk2(a00[8 * k + 4], a00[8 * k + 5]); w.w = pk2(a00[8 * k + 6], a00[8 * k + 7]); p00[k] = __builtin_bit_cast(bf16x8, w);
	v_lshlrev_b32_e32 v3, 16, v3
	v_pk_mul_f32 v[2:3], v[2:3], s[8:9] op_sel_hi:[1,0]
	s_nop 0
	v_mul_f32_e32 v7, v10, v2
	v_cvt_pk_bf16_f32 v7, v7, s0
	ds_write_b16 v126, v7 offset:8640
	v_mul_f32_e32 v7, v13, v3
	v_cvt_pk_bf16_f32 v7, v7, s0
	ds_write_b16 v126, v7 offset:8784
	v_cndmask_b32_e64 v7, 0, 32, vcc
	v_ldexp_f32 v7, v6, v7
	v_log_f32_e32 v7, v7
	v_pk_mul_f32 v[2:3], v[8:9], v[2:3]
	v_sub_f32_e32 v6, 1.0, v6
	v_cvt_pk_bf16_f32 v64, v2, v3
	v_mul_f32_e32 v8, 0x3f317217, v7
	v_fma_f32 v8, v7, s31, -v8
	v_mad_i64_i32 v[2:3], s[4:5], s86, v205, v[108:109]
	v_fmac_f32_e32 v8, 0x3377d1cf, v7
	v_fmac_f32_e32 v8, 0x3f317217, v7
	v_cmp_lt_f32_e64 s[4:5], |v7|, s34
	global_load_ushort v10, v[2:3], off offset:1024
	s_nop 0
	v_cndmask_b32_e64 v7, v7, v8, s[4:5]
	v_mad_i64_i32 v[2:3], s[4:5], s83, v205, v[108:109]
	global_load_ushort v3, v[2:3], off offset:1024
	v_cndmask_b32_e32 v8, 0, v206, vcc
	v_sub_f32_e32 v7, v7, v8
	v_add_f32_e32 v7, v7, v11
	v_sub_f32_e32 v9, v5, v7
	v_min_f32_e32 v9, 0x42a00000, v9
	v_mul_f32_e32 v9, 0x3fb8aa3b, v9
	v_exp_f32_e32 v9, v9
	v_cmp_gt_f32_e32 vcc, s35, v4
	v_sub_f32_e32 v8, v7, v5
	v_min_f32_e32 v8, 0x42a00000, v8
	v_mul_f32_e32 v9, v6, v9
	v_cvt_pk_bf16_f32 v9, v9, s0
	ds_write_b16 v126, v9 offset:18144
	v_cndmask_b32_e64 v9, 0, 32, vcc
	v_ldexp_f32 v9, v4, v9
	v_log_f32_e32 v9, v9
	v_mul_f32_e32 v6, 0x3fb8aa3b, v7
	v_mul_f32_e32 v8, 0x3fb8aa3b, v8
	v_exp_f32_e32 v8, v8
	v_mul_f32_e32 v11, 0x3f317217, v9
	v_fma_f32 v11, v9, s31, -v11
	v_fmac_f32_e32 v11, 0x3377d1cf, v9
	v_fmac_f32_e32 v11, 0x3f317217, v9
	v_cmp_lt_f32_e64 s[4:5], |v9|, s34
	v_sub_f32_e32 v4, 1.0, v4
	v_exp_f32_e32 v6, v6
	v_cndmask_b32_e64 v9, v9, v11, s[4:5]
	v_cndmask_b32_e32 v11, 0, v206, vcc
	v_sub_f32_e32 v9, v9, v11
	v_add_f32_e32 v7, v9, v7
	v_sub_f32_e32 v9, v7, v5
	v_sub_f32_e32 v5, v5, v7
	v_min_f32_e32 v5, 0x42a00000, v5
	v_mul_f32_e32 v5, 0x3fb8aa3b, v5
	v_exp_f32_e32 v5, v5
	v_min_f32_e32 v9, 0x42a00000, v9
	v_mul_f32_e32 v9, 0x3fb8aa3b, v9
	v_mul_f32_e32 v2, 0x3fb8aa3b, v7
	v_exp_f32_e32 v9, v9
	v_mul_f32_e32 v4, v4, v5
	v_exp_f32_e32 v7, v2
	v_cvt_pk_bf16_f32 v4, v4, s0
	ds_write_b16 v126, v4 offset:18288
	v_readlane_b32 s4, v254, 45
	v_readlane_b32 s5, v254, 46
	s_waitcnt vmcnt(1)
	v_lshlrev_b32_e32 v2, 16, v10
	s_waitcnt vmcnt(0)
	v_lshlrev_b32_e32 v3, 16, v3
	v_pk_mul_f32 v[2:3], v[2:3], s[8:9] op_sel_hi:[1,0]
	s_nop 0
	v_mul_f32_e32 v4, v8, v2
	v_cvt_pk_bf16_f32 v4, v4, s0
	ds_write_b16 v126, v4 offset:8928
	v_mul_f32_e32 v4, v9, v3
	v_cvt_pk_bf16_f32 v4, v4, s0
	ds_write_b16 v126, v4 offset:9072
	v_pk_mul_f32 v[2:3], v[6:7], v[2:3]
	s_waitcnt lgkmcnt(0)
	s_nop 0
	v_cvt_pk_bf16_f32 v65, v2, v3
	ds_read_b128 v[66:69], v170 offset:9216
	ds_read_b128 v[2:5], v170 offset:13824
	ds_read_b128 v[70:73], v170 offset:4608
	ds_read_b128 v[6:9], v170
	ds_read_b128 v[74:77], v170 offset:32
	s_waitcnt lgkmcnt(1)
	v_mfma_f32_32x32x16_bf16 v[18:33], v[66:69], v[6:9], 0
	ds_read_b128 v[78:81], v170 offset:9248
	ds_read_b128 v[82:85], v170 offset:13856
	ds_read_b128 v[86:89], v170 offset:4640
	v_mfma_f32_32x32x16_bf16 v[2:17], v[2:5], v[70:73], 0
	s_waitcnt lgkmcnt(2)
	v_mfma_f32_32x32x16_bf16 v[18:33], v[78:81], v[74:77], v[18:33]
	s_waitcnt lgkmcnt(0)
	v_mfma_f32_32x32x16_bf16 v[2:17], v[82:85], v[86:89], v[2:17]
	ds_read_b128 v[74:77], v170 offset:9280
	ds_read_b128 v[82:85], v170 offset:13888
	ds_read_b128 v[90:93], v170 offset:64
	ds_read_b128 v[94:97], v170 offset:4672
	s_waitcnt lgkmcnt(1)
	v_mfma_f32_32x32x16_bf16 v[18:33], v[74:77], v[90:93], v[18:33]
	s_waitcnt lgkmcnt(0)
	v_mfma_f32_32x32x16_bf16 v[2:17], v[82:85], v[94:97], v[2:17]
	ds_read_b128 v[82:85], v170 offset:9312
	ds_read_b128 v[90:93], v170 offset:13920
	ds_read_b128 v[118:121], v170 offset:96
	ds_read_b128 v[122:125], v170 offset:4704
	s_waitcnt lgkmcnt(0)
	ds_write_b16 v126, v34
	ds_write_b16_d16_hi v126, v34 offset:144
	ds_write_b16 v126, v35 offset:288
	ds_write_b16_d16_hi v126, v35 offset:432
	ds_write_b16 v126, v36 offset:576
	ds_write_b16_d16_hi v126, v36 offset:720
	ds_write_b16 v126, v37 offset:864
	ds_write_b16_d16_hi v126, v37 offset:1008
	ds_write_b16 v126, v38 offset:1152
	ds_write_b16_d16_hi v126, v38 offset:1296
	ds_write_b16 v126, v39 offset:1440
	ds_write_b16_d16_hi v126, v39 offset:1584
	ds_write_b16 v126, v40 offset:1728
	ds_write_b16_d16_hi v126, v40 offset:1872
	ds_write_b16 v126, v41 offset:2016
	ds_write_b16_d16_hi v126, v41 offset:2160
	ds_write_b16 v126, v42 offset:2304
	ds_write_b16_d16_hi v126, v42 offset:2448
	ds_write_b16 v126, v43 offset:2592
	ds_write_b16_d16_hi v126, v43 offset:2736
	ds_write_b16 v126, v44 offset:2880
	ds_write_b16_d16_hi v126, v44 offset:3024
	ds_write_b16 v126, v45 offset:3168
	ds_write_b16_d16_hi v126, v45 offset:3312
	ds_write_b16 v126, v46 offset:3456
	ds_write_b16_d16_hi v126, v46 offset:3600
	ds_write_b16 v126, v47 offset:3744
	ds_write_b16_d16_hi v126, v47 offset:3888
	ds_write_b16 v126, v48 offset:4032
	ds_write_b16_d16_hi v126, v48 offset:4176
	ds_write_b16 v126, v49 offset:4320
	ds_write_b16_d16_hi v126, v49 offset:4464
	ds_write_b16 v126, v51 offset:4608
	ds_write_b16_d16_hi v126, v51 offset:4752
	ds_write_b16 v126, v50 offset:4896
	ds_write_b16_d16_hi v126, v50 offset:5040
	ds_write_b16 v126, v52 offset:5184
	ds_write_b16_d16_hi v126, v52 offset:5328
	ds_write_b16 v126, v53 offset:5472
	ds_write_b16_d16_hi v126, v53 offset:5616
	ds_write_b16 v126, v54 offset:5760
	ds_write_b16_d16_hi v126, v54 offset:5904
	ds_write_b16 v126, v55 offset:6048
	ds_write_b16_d16_hi v126, v55 offset:6192
	ds_write_b16 v126, v56 offset:6336
	ds_write_b16_d16_hi v126, v56 offset:6480
	ds_write_b16 v126, v57 offset:6624
	ds_write_b16_d16_hi v126, v57 offset:6768
	ds_write_b16 v126, v58 offset:6912
	ds_write_b16_d16_hi v126, v58 offset:7056
	ds_write_b16 v126, v59 offset:7200
	ds_write_b16_d16_hi v126, v59 offset:7344
	ds_write_b16 v126, v60 offset:7488
	ds_write_b16_d16_hi v126, v60 offset:7632
	ds_write_b16 v126, v61 offset:7776
	ds_write_b16_d16_hi v126, v61 offset:7920
	ds_write_b16 v126, v62 offset:8064
	ds_write_b16_d16_hi v126, v62 offset:8208
	ds_write_b16 v126, v63 offset:8352
	ds_write_b16_d16_hi v126, v63 offset:8496
	ds_write_b16 v126, v64 offset:8640
	ds_write_b16_d16_hi v126, v64 offset:8784
	ds_write_b16 v126, v65 offset:8928
	ds_write_b16_d16_hi v126, v65 offset:9072
	v_or_b32_e32 v36, s45, v137
	v_or_b32_e32 v34, s45, v135
	v_or_b32_e32 v35, s45, v136
	v_or_b32_e32 v56, s45, v141
	s_waitcnt lgkmcnt(14)
; #define LAS __attribute__((address_space(3)))
; __device__ __forceinline__ void hgrn_out_phase(const Ctx& F, const Args& a, int l) {
;     ...
; #pragma unroll
;             for (int r = 0; r < 16; ++r) { const bool ok = (8 * (r >> 2) + 4 * h + (r & 3)) <= q_; a00[r] = ok ? a00[r] : 0.f; a11[r] = ok ? a11[r] : 0.f; }
;             bf16x8 p00[2], p01[2], p11[2];
; #pragma unroll
;             for (int k = 0; k < 2; ++k) { u32x4 w;
;                 w.x = pk2(a00[8 * k], a00[8 * k + 1]); w.y = pk2(a00[8 * k + 2], a00[8 * k + 3]); w.z = pk2(a00[8 * k + 4], a00[8 * k + 5]); w.w = pk2(a00[8 * k + 6], a00[8 * k + 7]); p00[k] = __builtin_bit_cast(bf16x8, w);
;                 w.x = pk2(a01[8 * k], a01[8 * k + 1]); w.y = pk2(a01[8 * k + 2], a01[8 * k + 3]); w.z = pk2(a01[8 * k + 4], a01[8 * k + 5]); w.w = pk2(a01[8 * k + 6], a01[8 * k + 7]); p01[k] = __builtin_bit_cast(bf16x8, w);
;                 w.x = pk2(a11[8 * k], a11[8 * k + 1]); w.y = pk2(a11[8 * k + 2], a11[8 * k + 3]); w.z = pk2(a11[8 * k + 4], a11[8 * k + 5]); w.w = pk2(a11[8 * k + 6], a11[8 * k + 7]); p11[k] = __builtin_bit_cast(bf16x8, w); }
;             asm volatile("s_waitcnt lgkmcnt(0)" ::: "memory");
;             __builtin_amdgcn_wave_barrier();
; #pragma unroll
;             for (int t2 = 0; t2 < 32; ++t2) { *(LAS bf16_t*)(TQ + (2 * t2) * TP + 2 * lane) = (bf16_t)(qh[t2] & 0xffffu); *(LAS bf16_t*)(TQ + (2 * t2 + 1) * TP + 2 * lane) = (bf16_t)(qh[t2] >> 16); }
;             f32x16 o[2][2];
; #pragma unroll
;             for (int r = 0; r < 16; ++r) { o[0][0][r] = 0.f; o[0][1][r] = 0.f; o[1][0][r] = 0.f; o[1][1][r] = 0.f; }
;             const bf16_t* vbase = PB + C_BI + head * 64 + q_;
; #pragma unroll
;             for (int cv = 0; cv < 2; ++cv)
; #pragma unroll
;                 for (int sa = 0; sa < 2; ++sa)
; #pragma unroll
;                     for (int k = 0; k < 2; ++k) {
;                         unsigned e[8];
; #pragma unroll
;                         for (int j = 0; j < 8; ++j) { const int s = 32 * sa + 16 * k + 8 * (j >> 2) + 4 * h + (j & 3); e[j] = vbase[(size_t)(rb + (dir ? 63 - s : s)) * INW + 32 * cv]; }
;                         const u32x4 w = {e[0] | (e[1] << 16), e[2] | (e[3] << 16), e[4] | (e[5] << 16), e[6] | (e[7] << 16)};
;                         const bf16x8 vf = __builtin_bit_cast(bf16x8, w);
	v_mfma_f32_32x32x16_bf16 v[18:33], v[82:85], v[118:121], v[18:33]
	v_or_b32_e32 v54, s45, v139
	v_or_b32_e32 v37, s45, v138
	v_or_b32_e32 v55, s45, v140
	v_or_b32_e32 v57, s45, v142
	v_mfma_f32_32x32x16_bf16 v[2:17], v[90:93], v[122:125], v[2:17]
	s_nop 6
	v_cndmask_b32_e64 v18, v18, 0, s[4:5]
	s_nop 3
	v_cndmask_b32_e64 v90, v2, 0, s[4:5]
	v_readlane_b32 s4, v254, 47
	v_readlane_b32 s5, v254, 48
	s_nop 1
	v_cndmask_b32_e64 v19, 0, v19, s[4:5]
	v_cndmask_b32_e64 v91, 0, v3, s[4:5]
	v_readlane_b32 s4, v254, 49
	v_readlane_b32 s5, v254, 50
	s_nop 1
	v_cndmask_b32_e64 v20, v20, 0, s[4:5]
	v_cndmask_b32_e64 v92, v4, 0, s[4:5]
	v_readlane_b32 s4, v254, 51
	v_readlane_b32 s5, v254, 52
	s_nop 1
	v_cndmask_b32_e64 v21, v21, 0, s[4:5]
	v_cndmask_b32_e64 v93, v5, 0, s[4:5]
	v_readlane_b32 s4, v254, 53
	v_readlane_b32 s5, v254, 54
	s_nop 1
	v_cndmask_b32_e64 v22, v22, 0, s[4:5]
	v_cndmask_b32_e64 v99, v6, 0, s[4:5]
	v_readlane_b32 s4, v254, 55
	v_readlane_b32 s5, v254, 56
	s_nop 1
	v_cndmask_b32_e64 v23, 0, v23, s[4:5]
	v_cndmask_b32_e64 v118, 0, v7, s[4:5]
	v_readlane_b32 s4, v254, 57
	v_readlane_b32 s5, v254, 58
	s_nop 1
	v_cndmask_b32_e64 v24, v24, 0, s[4:5]
	v_cndmask_b32_e64 v119, v8, 0, s[4:5]
	v_readlane_b32 s4, v254, 59
	v_readlane_b32 s5, v254, 60
	s_nop 1
	v_cndmask_b32_e64 v25, v25, 0, s[4:5]
	v_cndmask_b32_e64 v120, v9, 0, s[4:5]
	v_readlane_b32 s4, v254, 61
	v_readlane_b32 s5, v254, 62
	s_nop 1
	v_cndmask_b32_e64 v26, v26, 0, s[4:5]
	v_cndmask_b32_e64 v121, v10, 0, s[4:5]
	v_readlane_b32 s4, v254, 63
	v_readlane_b32 s5, v255, 0
	s_nop 1
	v_cndmask_b32_e64 v27, 0, v27, s[4:5]
	v_cndmask_b32_e64 v173, 0, v11, s[4:5]
	v_readlane_b32 s4, v255, 1
	v_readlane_b32 s5, v255, 2
	s_nop 1
	v_cndmask_b32_e64 v28, v28, 0, s[4:5]
	v_cndmask_b32_e64 v174, v12, 0, s[4:5]
	v_readlane_b32 s4, v255, 3
	v_readlane_b32 s5, v255, 4
	s_nop 1
	v_cndmask_b32_e64 v29, v29, 0, s[4:5]
	v_cndmask_b32_e64 v175, v13, 0, s[4:5]
	v_readlane_b32 s4, v255, 5
	v_readlane_b32 s5, v255, 6
	s_nop 1
	v_cndmask_b32_e64 v30, v30, 0, s[4:5]
	v_cndmask_b32_e64 v176, v14, 0, s[4:5]
	v_readlane_b32 s4, v255, 7
	v_readlane_b32 s5, v255, 8
	s_nop 1
	v_cndmask_b32_e64 v31, 0, v31, s[4:5]
	v_cndmask_b32_e64 v177, 0, v15, s[4:5]
	v_readlane_b32 s4, v255, 9
	v_readlane_b32 s5, v255, 10
	s_nop 1
	v_cndmask_b32_e64 v32, v32, 0, s[4:5]
	v_cndmask_b32_e64 v178, v16, 0, s[4:5]
	v_readlane_b32 s4, v255, 11
	v_readlane_b32 s5, v255, 12
	s_nop 1
	v_cndmask_b32_e64 v179, v17, 0, s[4:5]
	v_mfma_f32_32x32x16_bf16 v[2:17], v[66:69], v[70:73], 0
	v_cndmask_b32_e64 v33, v33, 0, s[4:5]
	v_cvt_pk_bf16_f32 v66, v18, v19
	v_cvt_pk_bf16_f32 v67, v20, v21
	v_cvt_pk_bf16_f32 v68, v22, v23
	v_cvt_pk_bf16_f32 v69, v24, v25
	v_mfma_f32_32x32x16_bf16 v[2:17], v[78:81], v[86:89], v[2:17]
	v_cvt_pk_bf16_f32 v86, v121, v173
	v_cvt_pk_bf16_f32 v78, v26, v27
	v_cvt_pk_bf16_f32 v79, v28, v29
	v_cvt_pk_bf16_f32 v80, v30, v31
	v_cvt_pk_bf16_f32 v81, v32, v33
	v_cvt_pk_bf16_f32 v87, v174, v175
	v_cvt_pk_bf16_f32 v88, v176, v177
	v_mfma_f32_32x32x16_bf16 v[2:17], v[74:77], v[94:97], v[2:17]
	v_mad_i64_i32 v[96:97], s[4:5], v36, s21, v[110:111]
	global_load_ushort v36, v[96:97], off
	v_cvt_pk_bf16_f32 v74, v90, v91
	v_cvt_pk_bf16_f32 v75, v92, v93
	v_mad_i64_i32 v[90:91], s[4:5], v35, s21, v[110:111]
	v_mfma_f32_32x32x16_bf16 v[2:17], v[82:85], v[122:125], v[2:17]
	v_mad_i64_i32 v[92:93], s[4:5], v34, s21, v[110:111]
	v_mad_i64_i32 v[124:125], s[4:5], v56, s21, v[110:111]
	v_cvt_pk_bf16_f32 v77, v119, v120
	global_load_ushort v35, v[90:91], off
	global_load_ushort v34, v[92:93], off
	s_nop 6
	v_cvt_pk_bf16_f32 v70, v2, v3
	v_or_b32_e32 v2, s45, v127
	v_or_b32_e32 v3, s45, v128
	v_mad_i64_i32 v[38:39], s[4:5], v3, s21, v[110:111]
	v_mad_i64_i32 v[40:41], s[4:5], v2, s21, v[110:111]
	global_load_ushort v3, v[38:39], off
	global_load_ushort v2, v[40:41], off
	v_cvt_pk_bf16_f32 v71, v4, v5
	v_cvt_pk_bf16_f32 v73, v8, v9
	v_or_b32_e32 v4, s45, v129
	v_or_b32_e32 v5, s45, v130
	v_or_b32_e32 v8, s45, v133
	v_cvt_pk_bf16_f32 v72, v6, v7
	v_or_b32_e32 v6, s45, v131
	v_mad_i64_i32 v[42:43], s[4:5], v5, s21, v[110:111]
	v_mad_i64_i32 v[44:45], s[4:5], v4, s21, v[110:111]
	v_mad_i64_i32 v[52:53], s[4:5], v8, s21, v[110:111]
	global_load_ushort v4, v[44:45], off
	v_mad_i64_i32 v[48:49], s[4:5], v6, s21, v[110:111]
	global_load_ushort v6, v[52:53], off
	v_or_b32_e32 v7, s45, v132
	v_mad_i64_i32 v[46:47], s[4:5], v7, s21, v[110:111]
	global_load_ushort v5, v[48:49], off
	v_mad_i64_i32 v[120:121], s[4:5], v54, s21, v[110:111]
	global_load_ushort v54, v[124:125], off
	v_or_b32_e32 v9, s45, v134
	v_mad_i64_i32 v[50:51], s[4:5], v9, s21, v[110:111]
	v_mad_i64_i32 v[94:95], s[4:5], v37, s21, v[110:111]
	global_load_ushort v37, v[120:121], off
	v_cvt_pk_bf16_f32 v76, v99, v118
	v_mad_i64_i32 v[118:119], s[4:5], v55, s21, v[110:111]
	v_mad_i64_i32 v[122:123], s[4:5], v57, s21, v[110:111]
	v_cvt_pk_bf16_f32 v82, v10, v11
	v_cvt_pk_bf16_f32 v83, v12, v13
	v_cvt_pk_bf16_f32 v84, v14, v15
	v_cvt_pk_bf16_f32 v85, v16, v17
	v_or_b32_e32 v56, s45, v149
	v_cvt_pk_bf16_f32 v89, v178, v179
	v_mad_i64_i32 v[188:189], s[4:5], v56, s21, v[110:111]
	v_or_b32_e32 v55, s45, v148
	v_mad_i64_i32 v[182:183], s[4:5], v55, s21, v[110:111]
	v_or_b32_e32 v57, s45, v150
	v_mad_i64_i32 v[186:187], s[4:5], v57, s21, v[110:111]
	v_or_b32_e32 v56, s45, v168
	v_mad_i64_i32 v[220:221], s[4:5], v56, s21, v[110:111]
	v_or_b32_e32 v55, s45, v167
	v_mad_i64_i32 v[200:201], s[4:5], v55, s21, v[110:111]
	v_or_b32_e32 v57, s45, v169
	v_mad_i64_i32 v[218:219], s[4:5], v57, s21, v[110:111]
	s_waitcnt vmcnt(7)
	v_lshl_or_b32 v34, v35, 16, v34
	global_load_ushort v35, v[94:95], off
	s_waitcnt vmcnt(6)
; __device__ __forceinline__ void hgrn_out_phase(const Ctx& F, const Args& a, int l) {
;     ...
;             const bf16_t* vbase = PB + C_BI + head * 64 + q_;
; #pragma unroll
;             for (int cv = 0; cv < 2; ++cv)
; #pragma unroll
;                 for (int sa = 0; sa < 2; ++sa)
; #pragma unroll
;                     for (int k = 0; k < 2; ++k) {
;                         unsigned e[8];
; #pragma unroll
;                         for (int j = 0; j < 8; ++j) { const int s = 32 * sa + 16 * k + 8 * (j >> 2) + 4 * h + (j & 3); e[j] = vbase[(size_t)(rb + (dir ? 63 - s : s)) * INW + 32 * cv]; }
;                         const u32x4 w = {e[0] | (e[1] << 16), e[2] | (e[3] << 16), e[4] | (e[5] << 16), e[6] | (e[7] << 16)};
;                         const bf16x8 vf = __builtin_bit_cast(bf16x8, w);
;                         if (sa == 0) { o[cv][0] = __builtin_amdgcn_mfma_f32_32x32x16_bf16(vf, p00[k], o[cv][0], 0, 0, 0); o[cv][1] = __builtin_amdgcn_mfma_f32_32x32x16_bf16(vf, p01[k], o[cv][1], 0, 0, 0); }
;                         else o[cv][1] = __builtin_amdgcn_mfma_f32_32x32x16_bf16(vf, p11[k], o[cv][1], 0, 0, 0);
;                     }
;             asm volatile("s_waitcnt lgkmcnt(0)" ::: "memory");
;             __builtin_amdgcn_wave_barrier();
;             const float* sbase = GS + ((size_t)((dir * NCHUNK + c) * 4 + head)) * 4096 + q_;
	v_lshl_or_b32 v2, v3, 16, v2
	global_load_ushort v3, v[42:43], off
	s_waitcnt vmcnt(1)
	v_lshl_or_b32 v35, v35, 16, v36
	global_load_ushort v36, v[118:119], off
	s_waitcnt vmcnt(1)
	v_lshl_or_b32 v3, v3, 16, v4
	global_load_ushort v4, v[46:47], off
	s_waitcnt vmcnt(1)
	v_lshl_or_b32 v36, v36, 16, v37
	global_load_ushort v37, v[122:123], off
	s_waitcnt vmcnt(1)
	v_lshl_or_b32 v4, v4, 16, v5
	global_load_ushort v5, v[50:51], off
	s_waitcnt vmcnt(1)
	v_lshl_or_b32 v37, v37, 16, v54
	v_or_b32_e32 v54, s45, v147
	v_mad_i64_i32 v[184:185], s[4:5], v54, s21, v[110:111]
	global_load_ushort v54, v[188:189], off
	s_waitcnt vmcnt(1)
	v_lshl_or_b32 v5, v5, 16, v6
	s_nop 1
	v_mfma_f32_32x32x16_bf16 v[18:33], v[2:5], v[66:69], 0
	v_mfma_f32_32x32x16_bf16 v[2:17], v[2:5], v[70:73], 0
	v_mfma_f32_32x32x16_bf16 v[18:33], v[34:37], v[78:81], v[18:33]
	v_mfma_f32_32x32x16_bf16 v[2:17], v[34:37], v[82:85], v[2:17]
	v_or_b32_e32 v34, s45, v143
	v_or_b32_e32 v35, s45, v144
	v_mad_i64_i32 v[174:175], s[4:5], v35, s21, v[110:111]
	v_mad_i64_i32 v[176:177], s[4:5], v34, s21, v[110:111]
	global_load_ushort v35, v[174:175], off
	global_load_ushort v34, v[176:177], off
	v_or_b32_e32 v36, s45, v145
	v_or_b32_e32 v37, s45, v146
	v_mad_i64_i32 v[178:179], s[4:5], v37, s21, v[110:111]
	v_mad_i64_i32 v[180:181], s[4:5], v36, s21, v[110:111]
	global_load_ushort v36, v[180:181], off
	global_load_ushort v37, v[184:185], off
	s_waitcnt vmcnt(2)
	v_lshl_or_b32 v34, v35, 16, v34
	global_load_ushort v35, v[178:179], off
	s_waitcnt vmcnt(0)
	v_lshl_or_b32 v35, v35, 16, v36
	global_load_ushort v36, v[182:183], off
	s_waitcnt vmcnt(0)
	v_lshl_or_b32 v36, v36, 16, v37
	global_load_ushort v37, v[186:187], off
	s_waitcnt vmcnt(0)
	v_lshl_or_b32 v37, v37, 16, v54
	s_nop 1
	v_mfma_f32_32x32x16_bf16 v[2:17], v[34:37], v[74:77], v[2:17]
	v_or_b32_e32 v34, s45, v151
	v_or_b32_e32 v35, s45, v152
	v_mad_i64_i32 v[190:191], s[4:5], v35, s21, v[110:111]
	v_mad_i64_i32 v[194:195], s[4:5], v34, s21, v[110:111]
	global_load_ushort v35, v[190:191], off
	global_load_ushort v34, v[194:195], off
	v_or_b32_e32 v36, s45, v153
	v_or_b32_e32 v37, s45, v154
	v_or_b32_e32 v54, s45, v155
	v_mad_i64_i32 v[196:197], s[4:5], v37, s21, v[110:111]
	v_mad_i64_i32 v[198:199], s[4:5], v36, s21, v[110:111]
	global_load_ushort v36, v[198:199], off
	v_mad_i64_i32 v[214:215], s[4:5], v54, s21, v[110:111]
	global_load_ushort v54, v[220:221], off
	global_load_ushort v37, v[214:215], off
	v_readlane_b32 s4, v253, 22
	v_readlane_b32 s5, v253, 23
	s_and_b64 s[4:5], s[4:5], exec
	s_cselect_b32 s2, s82, s44
	v_readlane_b32 s4, v253, 29
	s_add_i32 s2, s2, s4
	s_lshl_b32 s2, s2, 2
	s_or_b32 s4, s2, s9
	s_ashr_i32 s5, s4, 31
	s_lshl_b64 s[4:5], s[4:5], 14
	s_movk_i32 s2, 0x1000
	s_mov_b32 s44, s85
	s_waitcnt vmcnt(3)
	v_lshl_or_b32 v34, v35, 16, v34
	global_load_ushort v35, v[196:197], off
	s_waitcnt vmcnt(0)
	v_lshl_or_b32 v35, v35, 16, v36
	global_load_ushort v36, v[200:201], off
	s_waitcnt vmcnt(0)
	v_lshl_or_b32 v36, v36, 16, v37
	global_load_ushort v37, v[218:219], off
	s_waitcnt vmcnt(0)
	v_lshl_or_b32 v37, v37, 16, v54
	s_nop 1
	v_mfma_f32_32x32x16_bf16 v[2:17], v[34:37], v[86:89], v[2:17]
	global_load_ushort v34, v[38:39], off offset:64
	global_load_ushort v35, v[40:41], off offset:64
	s_waitcnt vmcnt(0)
	v_lshl_or_b32 v34, v34, 16, v35
	global_load_ushort v35, v[42:43], off offset:64
	global_load_ushort v36, v[44:45], off offset:64
	s_waitcnt vmcnt(0)
	v_lshl_or_b32 v35, v35, 16, v36
	global_load_ushort v36, v[46:47], off offset:64
	global_load_ushort v37, v[48:49], off offset:64
	s_waitcnt vmcnt(0)
	v_lshl_or_b32 v36, v36, 16, v37
	global_load_ushort v37, v[50:51], off offset:64
	global_load_ushort v38, v[52:53], off offset:64
	s_waitcnt vmcnt(0)
	v_lshl_or_b32 v37, v37, 16, v38
	s_nop 1
	v_mfma_f32_32x32x16_bf16 v[50:65], v[34:37], v[66:69], 0
	global_load_ushort v66, v[90:91], off offset:64
	global_load_ushort v67, v[92:93], off offset:64
	s_waitcnt vmcnt(0)
	v_lshl_or_b32 v66, v66, 16, v67
	global_load_ushort v67, v[94:95], off offset:64
	global_load_ushort v68, v[96:97], off offset:64
	v_mfma_f32_32x32x16_bf16 v[34:49], v[34:37], v[70:73], 0
	s_waitcnt vmcnt(0)
	v_lshl_or_b32 v67, v67, 16, v68
	global_load_ushort v68, v[118:119], off offset:64
	global_load_ushort v69, v[120:121], off offset:64
	s_waitcnt vmcnt(0)
	v_lshl_or_b32 v68, v68, 16, v69
	global_load_ushort v69, v[122:123], off offset:64
	global_load_ushort v70, v[124:125], off offset:64
	v_lshl_add_u64 v[122:123], v[114:115], 0, s[4:5]
	v_add_co_u32_e32 v120, vcc, s2, v122
	s_movk_i32 s2, 0x3000
	s_nop 0
	v_addc_co_u32_e32 v121, vcc, 0, v123, vcc
	v_add_co_u32_e32 v118, vcc, s30, v122
	s_waitcnt vmcnt(0)
	v_lshl_or_b32 v69, v69, 16, v70
	s_nop 1
	v_mfma_f32_32x32x16_bf16 v[50:65], v[66:69], v[78:81], v[50:65]
	v_addc_co_u32_e32 v119, vcc, 0, v123, vcc
	v_add_co_u32_e32 v124, vcc, s2, v122
	s_nop 1
	v_addc_co_u32_e32 v125, vcc, 0, v123, vcc
	v_mfma_f32_32x32x16_bf16 v[34:49], v[66:69], v[82:85], v[34:49]
	global_load_ushort v66, v[174:175], off offset:64
	global_load_ushort v67, v[176:177], off offset:64
	s_waitcnt vmcnt(0)
	v_lshl_or_b32 v66, v66, 16, v67
	global_load_ushort v67, v[178:179], off offset:64
	global_load_ushort v68, v[180:181], off offset:64
	s_waitcnt vmcnt(0)
	v_lshl_or_b32 v67, v67, 16, v68
	global_load_ushort v68, v[182:183], off offset:64
	global_load_ushort v69, v[184:185], off offset:64
	s_waitcnt vmcnt(0)
	v_lshl_or_b32 v68, v68, 16, v69
	global_load_ushort v69, v[186:187], off offset:64
	global_load_ushort v70, v[188:189], off offset:64
	s_waitcnt vmcnt(0)
; #define LAS __attribute__((address_space(3)))
; __device__ __forceinline__ unsigned pk2(float lo, float hi) { const f32x2_t v = {lo, hi}; const bf16x2_t b = __builtin_convertvector(v, bf16x2_t); return __builtin_bit_cast(unsigned, b); }
; __device__ __forceinline__ void hgrn_out_phase(const Ctx& F, const Args& a, int l) {
;     ...
;             const float* sbase = GS + ((size_t)((dir * NCHUNK + c) * 4 + head)) * 4096 + q_;
; #pragma unroll
;             for (int cv = 0; cv < 2; ++cv)
; #pragma unroll
;                 for (int k = 0; k < 4; ++k) {
;                     float sv[8];
; #pragma unroll
;                     for (int j = 0; j < 8; ++j) sv[j] = sbase[(16 * k + 8 * h + j) * 64 + 32 * cv];
;                     const u32x4 w = {pk2(sv[0], sv[1]), pk2(sv[2], sv[3]), pk2(sv[4], sv[5]), pk2(sv[6], sv[7])};
;                     const bf16x8 sf = __builtin_bit_cast(bf16x8, w);
;                     const bf16x8 qb0 = *(const LAS bf16x8*)(TQ + q_ * TP + (16 * k + 8 * h) * 2), qb1 = *(const LAS bf16x8*)(TQ + (32 + q_) * TP + (16 * k + 8 * h) * 2);
;                     o[cv][0] = __builtin_amdgcn_mfma_f32_32x32x16_bf16(sf, qb0, o[cv][0], 0, 0, 0);
;                     o[cv][1] = __builtin_amdgcn_mfma_f32_32x32x16_bf16(sf, qb1, o[cv][1], 0, 0, 0);
;                 }
	v_lshl_or_b32 v69, v69, 16, v70
	s_nop 1
	v_mfma_f32_32x32x16_bf16 v[34:49], v[66:69], v[74:77], v[34:49]
	global_load_ushort v66, v[190:191], off offset:64
	global_load_ushort v67, v[194:195], off offset:64
	s_waitcnt vmcnt(0)
	v_lshl_or_b32 v66, v66, 16, v67
	global_load_ushort v67, v[196:197], off offset:64
	global_load_ushort v68, v[198:199], off offset:64
	s_waitcnt vmcnt(0)
	v_lshl_or_b32 v67, v67, 16, v68
	global_load_ushort v68, v[200:201], off offset:64
	global_load_ushort v69, v[214:215], off offset:64
	s_waitcnt vmcnt(0)
	v_lshl_or_b32 v68, v68, 16, v69
	global_load_ushort v69, v[218:219], off offset:64
	global_load_ushort v70, v[220:221], off offset:64
	s_waitcnt lgkmcnt(0)
	s_waitcnt vmcnt(0)
	v_lshl_or_b32 v69, v69, 16, v70
	s_nop 1
	v_mfma_f32_32x32x16_bf16 v[34:49], v[66:69], v[86:89], v[34:49]
	global_load_dword v222, v[122:123], off
	global_load_dword v223, v[122:123], off offset:256
	global_load_dword v224, v[122:123], off offset:512
	global_load_dword v225, v[122:123], off offset:768
	global_load_dword v226, v[122:123], off offset:1024
	global_load_dword v227, v[122:123], off offset:1280
	global_load_dword v228, v[122:123], off offset:1536
	global_load_dword v229, v[122:123], off offset:1792
	global_load_dword v230, v[118:119], off offset:-4096
	global_load_dword v231, v[120:121], off offset:256
	global_load_dword v232, v[120:121], off offset:512
	global_load_dword v233, v[120:121], off offset:768
	global_load_dword v234, v[120:121], off offset:1024
	global_load_dword v235, v[120:121], off offset:1280
	global_load_dword v236, v[120:121], off offset:1536
	global_load_dword v237, v[120:121], off offset:1792
	ds_read_b128 v[90:93], v170 offset:4608
	ds_read_b128 v[94:97], v170
	ds_read_b128 v[74:77], v170 offset:32
	s_waitcnt vmcnt(14)
	v_cvt_pk_bf16_f32 v66, v222, v223
	s_waitcnt vmcnt(12)
	v_cvt_pk_bf16_f32 v67, v224, v225
	s_waitcnt vmcnt(10)
	v_cvt_pk_bf16_f32 v68, v226, v227
	s_waitcnt vmcnt(8)
	v_cvt_pk_bf16_f32 v69, v228, v229
	s_waitcnt lgkmcnt(1)
	s_nop 0
	v_mfma_f32_32x32x16_bf16 v[18:33], v[66:69], v[94:97], v[18:33]
	v_mfma_f32_32x32x16_bf16 v[2:17], v[66:69], v[90:93], v[2:17]
	global_load_dword v222, v[118:119], off
	global_load_dword v223, v[118:119], off offset:256
	global_load_dword v224, v[118:119], off offset:512
	global_load_dword v225, v[118:119], off offset:768
	global_load_dword v226, v[118:119], off offset:1024
	global_load_dword v227, v[118:119], off offset:1280
	global_load_dword v228, v[118:119], off offset:1536
	global_load_dword v229, v[118:119], off offset:1792
	ds_read_b128 v[78:81], v170 offset:4640
	s_waitcnt vmcnt(14)
	v_cvt_pk_bf16_f32 v66, v230, v231
	s_waitcnt vmcnt(12)
	v_cvt_pk_bf16_f32 v67, v232, v233
	s_waitcnt vmcnt(10)
	v_cvt_pk_bf16_f32 v68, v234, v235
	s_waitcnt vmcnt(8)
	v_cvt_pk_bf16_f32 v69, v236, v237
	s_waitcnt lgkmcnt(1)
	s_nop 0
	v_mfma_f32_32x32x16_bf16 v[18:33], v[66:69], v[74:77], v[18:33]
	s_waitcnt lgkmcnt(0)
	v_mfma_f32_32x32x16_bf16 v[2:17], v[66:69], v[78:81], v[2:17]
	global_load_dword v230, v[124:125], off
	global_load_dword v231, v[124:125], off offset:256
	global_load_dword v232, v[124:125], off offset:512
	global_load_dword v233, v[124:125], off offset:768
	global_load_dword v234, v[124:125], off offset:1024
	global_load_dword v235, v[124:125], off offset:1280
	global_load_dword v236, v[124:125], off offset:1536
	global_load_dword v237, v[124:125], off offset:1792
	ds_read_b128 v[82:85], v170 offset:64
	ds_read_b128 v[86:89], v170 offset:4672
	s_waitcnt vmcnt(14)
	v_cvt_pk_bf16_f32 v66, v222, v223
	s_waitcnt vmcnt(12)
	v_cvt_pk_bf16_f32 v67, v224, v225
	s_waitcnt vmcnt(10)
	v_cvt_pk_bf16_f32 v68, v226, v227
	s_waitcnt vmcnt(8)
	v_cvt_pk_bf16_f32 v69, v228, v229
	s_waitcnt lgkmcnt(1)
	s_nop 0
	v_mfma_f32_32x32x16_bf16 v[18:33], v[66:69], v[82:85], v[18:33]
	s_waitcnt lgkmcnt(0)
	v_mfma_f32_32x32x16_bf16 v[2:17], v[66:69], v[86:89], v[2:17]
	global_load_dword v222, v[122:123], off offset:128
	global_load_dword v223, v[122:123], off offset:384
	global_load_dword v224, v[122:123], off offset:640
	global_load_dword v225, v[122:123], off offset:896
	global_load_dword v226, v[122:123], off offset:1152
	global_load_dword v227, v[122:123], off offset:1408
	global_load_dword v228, v[122:123], off offset:1664
	global_load_dword v229, v[122:123], off offset:1920
	s_waitcnt vmcnt(14)
	v_cvt_pk_bf16_f32 v174, v230, v231
	s_waitcnt vmcnt(12)
	v_cvt_pk_bf16_f32 v175, v232, v233
	s_waitcnt vmcnt(10)
	v_cvt_pk_bf16_f32 v176, v234, v235
	s_waitcnt vmcnt(8)
	v_cvt_pk_bf16_f32 v177, v236, v237
	ds_read_b128 v[70:73], v170 offset:96
	ds_read_b128 v[66:69], v170 offset:4704
	s_waitcnt lgkmcnt(1)
	v_mfma_f32_32x32x16_bf16 v[18:33], v[174:177], v[70:73], v[18:33]
	s_waitcnt lgkmcnt(0)
	v_mfma_f32_32x32x16_bf16 v[2:17], v[174:177], v[66:69], v[2:17]
	global_load_dword v230, v[120:121], off offset:128
	global_load_dword v231, v[120:121], off offset:384
	global_load_dword v232, v[120:121], off offset:640
	global_load_dword v233, v[120:121], off offset:896
	global_load_dword v234, v[120:121], off offset:1152
	global_load_dword v235, v[120:121], off offset:1408
	global_load_dword v236, v[120:121], off offset:1664
	global_load_dword v237, v[120:121], off offset:1920
	s_nop 0
	s_waitcnt vmcnt(14)
	v_cvt_pk_bf16_f32 v176, v222, v223
	s_waitcnt vmcnt(12)
	v_cvt_pk_bf16_f32 v177, v224, v225
	s_waitcnt vmcnt(10)
	v_cvt_pk_bf16_f32 v178, v226, v227
	s_waitcnt vmcnt(8)
; #define LAS __attribute__((address_space(3)))
; __device__ __forceinline__ float bf2f(unsigned v) { return __uint_as_float(v << 16); }
; __device__ __forceinline__ void hgrn_out_phase(const Ctx& F, const Args& a, int l) {
;     ...
;             const float* sbase = GS + ((size_t)((dir * NCHUNK + c) * 4 + head)) * 4096 + q_;
; #pragma unroll
;             for (int cv = 0; cv < 2; ++cv)
; #pragma unroll
;                 for (int k = 0; k < 4; ++k) {
;                     float sv[8];
; #pragma unroll
;                     for (int j = 0; j < 8; ++j) sv[j] = sbase[(16 * k + 8 * h + j) * 64 + 32 * cv];
;                     const u32x4 w = {pk2(sv[0], sv[1]), pk2(sv[2], sv[3]), pk2(sv[4], sv[5]), pk2(sv[6], sv[7])};
;                     const bf16x8 sf = __builtin_bit_cast(bf16x8, w);
;                     const bf16x8 qb0 = *(const LAS bf16x8*)(TQ + q_ * TP + (16 * k + 8 * h) * 2), qb1 = *(const LAS bf16x8*)(TQ + (32 + q_) * TP + (16 * k + 8 * h) * 2);
;                     o[cv][0] = __builtin_amdgcn_mfma_f32_32x32x16_bf16(sf, qb0, o[cv][0], 0, 0, 0);
;                     o[cv][1] = __builtin_amdgcn_mfma_f32_32x32x16_bf16(sf, qb1, o[cv][1], 0, 0, 0);
;                 }
;             asm volatile("s_waitcnt lgkmcnt(0)" ::: "memory");
;             __builtin_amdgcn_wave_barrier();
; #pragma unroll
;             for (int cv = 0; cv < 2; ++cv)
; #pragma unroll
;                 for (int tb = 0; tb < 2; ++tb) {
;                     const int t = 32 * tb + q_, tt = dir ? 63 - t : t;
; #pragma unroll
;                     for (int g4 = 0; g4 < 4; ++g4)
;                         *(LAS f32x4*)(ob + tt * 64 + 32 * cv + 8 * g4 + 4 * h) = (f32x4){o[cv][tb][4 * g4], o[cv][tb][4 * g4 + 1], o[cv][tb][4 * g4 + 2], o[cv][tb][4 * g4 + 3]};
;                 }
;         }
;         __syncthreads();
;         {
; #pragma unroll 4
;             for (int k = 0; k < 32; ++k) {
;                 const int tt = 32 * dir + k;
;                 const float ot = ob_f[tt * 64 + lane] + ob_b[tt * 64 + lane];
;                 const float ss = wave_sum(ot * ot);
;                 const float gg = bf2f(PB[(size_t)(rb + tt) * INW + C_BG + head * 64 + lane]);
;                 const float y = ot * (1.0f / sqrtf(ss * (1.f / 64.f) + EPSN)) * og * siluf_(gg);
;                 Y[(size_t)(rb + tt) * D + 256 + head * 64 + lane] = (bf16_t)f2bf(y);
;             }
	v_cvt_pk_bf16_f32 v179, v228, v229
	s_nop 1
	v_mfma_f32_32x32x16_bf16 v[50:65], v[176:179], v[94:97], v[50:65]
	v_mfma_f32_32x32x16_bf16 v[34:49], v[176:179], v[90:93], v[34:49]
	global_load_dword v222, v[118:119], off offset:128
	global_load_dword v223, v[118:119], off offset:384
	global_load_dword v224, v[118:119], off offset:640
	global_load_dword v225, v[118:119], off offset:896
	global_load_dword v226, v[118:119], off offset:1152
	global_load_dword v227, v[118:119], off offset:1408
	global_load_dword v228, v[118:119], off offset:1664
	global_load_dword v229, v[118:119], off offset:1920
	s_waitcnt vmcnt(14)
	v_cvt_pk_bf16_f32 v90, v230, v231
	s_waitcnt vmcnt(12)
	v_cvt_pk_bf16_f32 v91, v232, v233
	s_waitcnt vmcnt(10)
	v_cvt_pk_bf16_f32 v92, v234, v235
	s_waitcnt vmcnt(8)
	v_cvt_pk_bf16_f32 v93, v236, v237
	s_nop 1
	v_mfma_f32_32x32x16_bf16 v[50:65], v[90:93], v[74:77], v[50:65]
	v_mfma_f32_32x32x16_bf16 v[34:49], v[90:93], v[78:81], v[34:49]
	global_load_dword v230, v[124:125], off offset:128
	global_load_dword v231, v[124:125], off offset:384
	global_load_dword v232, v[124:125], off offset:640
	global_load_dword v233, v[124:125], off offset:896
	global_load_dword v234, v[124:125], off offset:1152
	global_load_dword v235, v[124:125], off offset:1408
	global_load_dword v236, v[124:125], off offset:1664
	global_load_dword v237, v[124:125], off offset:1920
	s_waitcnt vmcnt(14)
	v_cvt_pk_bf16_f32 v74, v222, v223
	s_waitcnt vmcnt(12)
	v_cvt_pk_bf16_f32 v75, v224, v225
	s_waitcnt vmcnt(10)
	v_cvt_pk_bf16_f32 v76, v226, v227
	s_waitcnt vmcnt(8)
	v_cvt_pk_bf16_f32 v77, v228, v229
	s_nop 1
	v_mfma_f32_32x32x16_bf16 v[50:65], v[74:77], v[82:85], v[50:65]
	v_mfma_f32_32x32x16_bf16 v[34:49], v[74:77], v[86:89], v[34:49]
	s_waitcnt lgkmcnt(0)
	s_waitcnt vmcnt(6)
	v_cvt_pk_bf16_f32 v74, v230, v231
	s_waitcnt vmcnt(4)
	v_cvt_pk_bf16_f32 v75, v232, v233
	s_waitcnt vmcnt(2)
	v_cvt_pk_bf16_f32 v76, v234, v235
	s_waitcnt vmcnt(0)
	v_cvt_pk_bf16_f32 v77, v236, v237
	s_nop 1
	v_mfma_f32_32x32x16_bf16 v[50:65], v[74:77], v[70:73], v[50:65]
	v_mfma_f32_32x32x16_bf16 v[34:49], v[74:77], v[66:69], v[34:49]
	ds_write_b128 v171, v[18:21]
	ds_write_b128 v171, v[22:25] offset:32
	ds_write_b128 v171, v[26:29] offset:64
	ds_write_b128 v171, v[30:33] offset:96
	ds_write_b128 v172, v[2:5]
	ds_write_b128 v172, v[6:9] offset:32
	ds_write_b128 v172, v[10:13] offset:64
	ds_write_b128 v172, v[14:17] offset:96
	s_nop 2
	ds_write_b128 v171, v[50:53] offset:128
	ds_write_b128 v171, v[54:57] offset:160
	ds_write_b128 v171, v[58:61] offset:192
	ds_write_b128 v171, v[62:65] offset:224
	ds_write_b128 v172, v[34:37] offset:128
	ds_write_b128 v172, v[38:41] offset:160
	ds_write_b128 v172, v[42:45] offset:192
	ds_write_b128 v172, v[46:49] offset:224
	s_waitcnt lgkmcnt(0)
	s_barrier
.LBB0_314:
	v_add_u32_e32 v4, s6, v0
	v_add_u32_e32 v5, 0x14000, v4
	ds_read2st64_b32 v[2:3], v4 offset0:32 offset1:33
	ds_read_b32 v5, v5
	s_add_i32 s22, s44, -3
	s_ashr_i32 s23, s22, 31
	s_add_i32 s82, s44, -1
	s_ashr_i32 s83, s82, 31
	s_waitcnt lgkmcnt(0)
	v_add_f32_e32 v2, v2, v5
	v_mul_f32_e32 v5, v2, v2
	s_nop 1
	v_mov_b32_dpp v5, v5 quad_perm:[1,0,3,2] row_mask:0xf bank_mask:0xf
	s_ashr_i32 s45, s44, 31
	s_addk_i32 s6, 0x400
	s_waitcnt lgkmcnt(0)
	v_fmac_f32_e32 v5, v2, v2
	s_nop 1
	v_mov_b32_dpp v6, v5 quad_perm:[2,3,0,1] row_mask:0xf bank_mask:0xf
	s_waitcnt lgkmcnt(0)
	v_add_f32_e32 v5, v5, v6
	s_nop 1
	v_mov_b32_dpp v6, v5 row_half_mirror row_mask:0xf bank_mask:0xf
	s_waitcnt lgkmcnt(0)
	v_add_f32_e32 v5, v5, v6
	s_nop 1
	v_mov_b32_dpp v6, v5 row_ror:8 row_mask:0xf bank_mask:0xf
	s_waitcnt lgkmcnt(0)
	v_add_f32_e32 v5, v5, v6
	v_mov_b32_e32 v6, v5
	s_nop 1
	v_permlane16_swap_b32_e32 v5, v6
	s_waitcnt lgkmcnt(0)
	v_add_f32_e32 v5, v5, v6
	v_mov_b32_e32 v6, v5
	s_nop 1
	v_permlane32_swap_b32_e32 v5, v6
	v_add_f32_e32 v5, v5, v6
	v_mad_i64_i32 v[6:7], s[4:5], s22, v205, v[116:117]
	global_load_ushort v6, v[6:7], off offset:3072
	v_fmamk_f32 v5, v5, 0x3c800000, v193
	v_cmp_gt_f32_e32 vcc, s41, v5
	s_waitcnt vmcnt(0)
	v_lshlrev_b32_e32 v7, 16, v6
	v_mul_f32_e32 v6, 0x4f800000, v5
	v_cndmask_b32_e32 v5, v5, v6, vcc
	v_sqrt_f32_e32 v6, v5
	s_nop 0
	v_add_u32_e32 v8, -1, v6
	v_fma_f32 v9, -v8, v6, v5
	v_cmp_ge_f32_e64 s[4:5], 0, v9
	v_add_u32_e32 v9, 1, v6
	s_nop 0
	v_cndmask_b32_e64 v8, v6, v8, s[4:5]
	v_fma_f32 v6, -v9, v6, v5
	v_cmp_lt_f32_e64 s[4:5], 0, v6
	s_nop 1
	v_cndmask_b32_e64 v6, v8, v9, s[4:5]
	v_mul_f32_e32 v8, 0x37800000, v6
	v_cndmask_b32_e32 v6, v6, v8, vcc
	v_cmp_class_f32_e32 vcc, v5, v202
	s_nop 1
	v_cndmask_b32_e32 v5, v6, v5, vcc
	v_div_scale_f32 v6, s[4:5], v5, v5, 1.0
	v_rcp_f32_e32 v8, v6
	s_lshl_b64 s[4:5], s[22:23], 11
	s_add_i32 s22, s44, -2
	s_ashr_i32 s23, s22, 31
	v_fma_f32 v9, -v6, v8, 1.0
	v_fmac_f32_e32 v8, v9, v8
	v_div_scale_f32 v9, vcc, 1.0, v5, 1.0
	v_mul_f32_e32 v10, v9, v8
	v_fma_f32 v11, -v6, v10, v9
	v_fmac_f32_e32 v10, v11, v8
	v_fma_f32 v6, -v6, v10, v9
	v_div_fmas_f32 v6, v6, v8, v10
	v_div_fixup_f32 v5, v6, v5, 1.0
	v_mul_f32_e32 v6, v2, v5
	v_mul_f32_e32 v2, 0xbfb8aa3b, v7
	v_exp_f32_e32 v2, v2
	s_nop 0
	v_add_f32_e32 v2, 1.0, v2
	v_rcp_f32_e32 v99, v2
	s_nop 0
	v_pk_mul_f32 v[6:7], v[98:99], v[6:7]
	s_nop 0
	v_mul_f32_e32 v2, v6, v7
	v_cvt_pk_bf16_f32 v2, v2, s0
	v_lshl_add_u64 v[6:7], v[112:113], 0, s[4:5]
	global_store_short v[6:7], v2, off
	v_add_u32_e32 v2, 0x14100, v4
	ds_read_b32 v2, v2
	s_waitcnt lgkmcnt(0)
	v_add_f32_e32 v5, v3, v2
	v_mul_f32_e32 v2, v5, v5
	s_nop 1
	v_mov_b32_dpp v2, v2 quad_perm:[1,0,3,2] row_mask:0xf bank_mask:0xf
	s_waitcnt lgkmcnt(0)
	v_fmac_f32_e32 v2, v5, v5
	s_nop 1
	v_mov_b32_dpp v3, v2 quad_perm:[2,3,0,1] row_mask:0xf bank_mask:0xf
	s_waitcnt lgkmcnt(0)
; __device__ __forceinline__ float bf2f(unsigned v) { return __uint_as_float(v << 16); }
; __device__ __forceinline__ unsigned f2bf(float f) { return pk2(f, 0.f) & 0xffffu; }
; __device__ __forceinline__ float siluf_(float x) { return x * __builtin_amdgcn_rcpf(1.0f + __builtin_amdgcn_exp2f(-1.4426950408889634f * x)); }
; __device__ __forceinline__ void hgrn_out_phase(const Ctx& F, const Args& a, int l) {
;     ...
; #pragma unroll 4
;             for (int k = 0; k < 32; ++k) {
;                 const int tt = 32 * dir + k;
;                 const float ot = ob_f[tt * 64 + lane] + ob_b[tt * 64 + lane];
;                 const float ss = wave_sum(ot * ot);
;                 const float gg = bf2f(PB[(size_t)(rb + tt) * INW + C_BG + head * 64 + lane]);
;                 const float y = ot * (1.0f / sqrtf(ss * (1.f / 64.f) + EPSN)) * og * siluf_(gg);
;                 Y[(size_t)(rb + tt) * D + 256 + head * 64 + lane] = (bf16_t)f2bf(y);
;             }
;         }
;         __syncthreads();
	v_add_f32_e32 v2, v2, v3
	s_nop 1
	v_mov_b32_dpp v3, v2 row_half_mirror row_mask:0xf bank_mask:0xf
	s_waitcnt lgkmcnt(0)
	v_add_f32_e32 v2, v2, v3
	s_nop 1
	v_mov_b32_dpp v3, v2 row_ror:8 row_mask:0xf bank_mask:0xf
	s_waitcnt lgkmcnt(0)
	v_add_f32_e32 v2, v2, v3
	v_mov_b32_e32 v3, v2
	s_nop 1
	v_permlane16_swap_b32_e32 v2, v3
	s_waitcnt lgkmcnt(0)
	v_add_f32_e32 v2, v2, v3
	v_mov_b32_e32 v3, v2
	s_nop 1
	v_permlane32_swap_b32_e32 v2, v3
	v_add_f32_e32 v6, v2, v3
	v_mad_i64_i32 v[2:3], s[4:5], s22, v205, v[116:117]
	global_load_ushort v2, v[2:3], off offset:3072
	s_waitcnt vmcnt(0)
	v_lshlrev_b32_e32 v3, 16, v2
	v_fmamk_f32 v2, v6, 0x3c800000, v193
	v_cmp_gt_f32_e32 vcc, s41, v2
	v_mul_f32_e32 v6, 0x4f800000, v2
	s_nop 0
	v_cndmask_b32_e32 v2, v2, v6, vcc
	v_sqrt_f32_e32 v6, v2
	s_nop 0
	v_add_u32_e32 v7, -1, v6
	v_fma_f32 v8, -v7, v6, v2
	v_cmp_ge_f32_e64 s[4:5], 0, v8
	v_add_u32_e32 v8, 1, v6
	s_nop 0
	v_cndmask_b32_e64 v7, v6, v7, s[4:5]
	v_fma_f32 v6, -v8, v6, v2
	v_cmp_lt_f32_e64 s[4:5], 0, v6
	s_nop 1
	v_cndmask_b32_e64 v6, v7, v8, s[4:5]
	v_mul_f32_e32 v7, 0x37800000, v6
	v_cndmask_b32_e32 v6, v6, v7, vcc
	v_cmp_class_f32_e32 vcc, v2, v202
	s_nop 1
	v_cndmask_b32_e32 v2, v6, v2, vcc
	v_div_scale_f32 v6, s[4:5], v2, v2, 1.0
	v_rcp_f32_e32 v7, v6
	s_lshl_b64 s[4:5], s[22:23], 11
	v_fma_f32 v8, -v6, v7, 1.0
	v_fmac_f32_e32 v7, v8, v7
	v_div_scale_f32 v8, vcc, 1.0, v2, 1.0
	v_mul_f32_e32 v9, v8, v7
	v_fma_f32 v10, -v6, v9, v8
	v_fmac_f32_e32 v9, v10, v7
	v_fma_f32 v6, -v6, v9, v8
	v_div_fmas_f32 v6, v6, v7, v9
	v_div_fixup_f32 v2, v6, v2, 1.0
	v_mul_f32_e32 v2, v5, v2
	v_mul_f32_e32 v5, 0xbfb8aa3b, v3
	v_exp_f32_e32 v5, v5
	s_nop 0
	v_add_f32_e32 v5, 1.0, v5
	v_rcp_f32_e32 v99, v5
	s_nop 0
	v_pk_mul_f32 v[2:3], v[98:99], v[2:3]
	s_nop 0
	v_mul_f32_e32 v2, v2, v3
	v_cvt_pk_bf16_f32 v5, v2, s0
	v_lshl_add_u64 v[2:3], v[112:113], 0, s[4:5]
	global_store_short v[2:3], v5, off
	v_add_u32_e32 v5, 0x14200, v4
	ds_read2st64_b32 v[2:3], v4 offset0:34 offset1:35
	ds_read_b32 v5, v5
	s_waitcnt lgkmcnt(0)
	v_add_f32_e32 v2, v2, v5
	v_mul_f32_e32 v5, v2, v2
	s_nop 1
	v_mov_b32_dpp v5, v5 quad_perm:[1,0,3,2] row_mask:0xf bank_mask:0xf
	s_waitcnt lgkmcnt(0)
	v_fmac_f32_e32 v5, v2, v2
	s_nop 1
	v_mov_b32_dpp v6, v5 quad_perm:[2,3,0,1] row_mask:0xf bank_mask:0xf
	s_waitcnt lgkmcnt(0)
	v_add_f32_e32 v5, v5, v6
	s_nop 1
	v_mov_b32_dpp v6, v5 row_half_mirror row_mask:0xf bank_mask:0xf
	s_waitcnt lgkmcnt(0)
	v_add_f32_e32 v5, v5, v6
	s_nop 1
	v_mov_b32_dpp v6, v5 row_ror:8 row_mask:0xf bank_mask:0xf
	s_waitcnt lgkmcnt(0)
	v_add_f32_e32 v5, v5, v6
	v_mov_b32_e32 v6, v5
	s_nop 1
	v_permlane16_swap_b32_e32 v5, v6
	s_waitcnt lgkmcnt(0)
	v_add_f32_e32 v5, v5, v6
	v_mov_b32_e32 v6, v5
	s_nop 1
	v_permlane32_swap_b32_e32 v5, v6
	v_add_f32_e32 v5, v5, v6
	v_mad_i64_i32 v[6:7], s[4:5], s82, v205, v[116:117]
	global_load_ushort v6, v[6:7], off offset:3072
	v_fmamk_f32 v5, v5, 0x3c800000, v193
	v_cmp_gt_f32_e32 vcc, s41, v5
	s_waitcnt vmcnt(0)
	v_lshlrev_b32_e32 v7, 16, v6
	v_mul_f32_e32 v6, 0x4f800000, v5
	v_cndmask_b32_e32 v5, v5, v6, vcc
	v_sqrt_f32_e32 v6, v5
	s_nop 0
	v_add_u32_e32 v8, -1, v6
	v_fma_f32 v9, -v8, v6, v5
	v_cmp_ge_f32_e64 s[4:5], 0, v9
	v_add_u32_e32 v9, 1, v6
	s_nop 0
	v_cndmask_b32_e64 v8, v6, v8, s[4:5]
	v_fma_f32 v6, -v9, v6, v5
	v_cmp_lt_f32_e64 s[4:5], 0, v6
	s_nop 1
	v_cndmask_b32_e64 v6, v8, v9, s[4:5]
	v_mul_f32_e32 v8, 0x37800000, v6
	v_cndmask_b32_e32 v6, v6, v8, vcc
	v_cmp_class_f32_e32 vcc, v5, v202
	s_nop 1
	v_cndmask_b32_e32 v5, v6, v5, vcc
	v_div_scale_f32 v6, s[4:5], v5, v5, 1.0
	v_rcp_f32_e32 v8, v6
	s_lshl_b64 s[4:5], s[82:83], 11
	v_fma_f32 v9, -v6, v8, 1.0
	v_fmac_f32_e32 v8, v9, v8
	v_div_scale_f32 v9, vcc, 1.0, v5, 1.0
	v_mul_f32_e32 v10, v9, v8
	v_fma_f32 v11, -v6, v10, v9
	v_fmac_f32_e32 v10, v11, v8
	v_fma_f32 v6, -v6, v10, v9
	v_div_fmas_f32 v6, v6, v8, v10
	v_div_fixup_f32 v5, v6, v5, 1.0
	v_mul_f32_e32 v6, v2, v5
	v_mul_f32_e32 v2, 0xbfb8aa3b, v7
	v_exp_f32_e32 v2, v2
	s_nop 0
	v_add_f32_e32 v2, 1.0, v2
	v_rcp_f32_e32 v99, v2
	s_nop 0
	v_pk_mul_f32 v[6:7], v[98:99], v[6:7]
	s_nop 0
	v_mul_f32_e32 v2, v6, v7
	v_cvt_pk_bf16_f32 v2, v2, s0
	v_lshl_add_u64 v[6:7], v[112:113], 0, s[4:5]
	global_store_short v[6:7], v2, off
	v_add_u32_e32 v2, 0x14300, v4
	ds_read_b32 v2, v2
	s_waitcnt lgkmcnt(0)
	v_add_f32_e32 v2, v3, v2
	v_mul_f32_e32 v3, v2, v2
	s_nop 1
	v_mov_b32_dpp v3, v3 quad_perm:[1,0,3,2] row_mask:0xf bank_mask:0xf
	s_waitcnt lgkmcnt(0)
	v_fmac_f32_e32 v3, v2, v2
	s_nop 1
	v_mov_b32_dpp v4, v3 quad_perm:[2,3,0,1] row_mask:0xf bank_mask:0xf
	s_waitcnt lgkmcnt(0)
	v_add_f32_e32 v3, v3, v4
	s_nop 1
	v_mov_b32_dpp v4, v3 row_half_mirror row_mask:0xf bank_mask:0xf
	s_waitcnt lgkmcnt(0)
	v_add_f32_e32 v3, v3, v4
	s_nop 1
	v_mov_b32_dpp v4, v3 row_ror:8 row_mask:0xf bank_mask:0xf
	s_waitcnt lgkmcnt(0)
	v_add_f32_e32 v3, v3, v4
	v_mov_b32_e32 v4, v3
	s_nop 1
	v_permlane16_swap_b32_e32 v3, v4
	s_waitcnt lgkmcnt(0)
	v_add_f32_e32 v3, v3, v4
	v_mov_b32_e32 v4, v3
	s_nop 1
	v_permlane32_swap_b32_e32 v3, v4
	v_add_f32_e32 v6, v3, v4
	v_mad_i64_i32 v[4:5], s[4:5], s44, v205, v[116:117]
	global_load_ushort v3, v[4:5], off offset:3072
	v_fmamk_f32 v4, v6, 0x3c800000, v193
	v_cmp_gt_f32_e32 vcc, s41, v4
	v_mul_f32_e32 v5, 0x4f800000, v4
	s_waitcnt vmcnt(0)
	v_lshlrev_b32_e32 v3, 16, v3
	v_cndmask_b32_e32 v4, v4, v5, vcc
	v_sqrt_f32_e32 v5, v4
	s_nop 0
	v_add_u32_e32 v6, -1, v5
	v_fma_f32 v7, -v6, v5, v4
	v_cmp_ge_f32_e64 s[4:5], 0, v7
	v_add_u32_e32 v7, 1, v5
	s_nop 0
	v_cndmask_b32_e64 v6, v5, v6, s[4:5]
	v_fma_f32 v5, -v7, v5, v4
	v_cmp_lt_f32_e64 s[4:5], 0, v5
	s_nop 1
	v_cndmask_b32_e64 v5, v6, v7, s[4:5]
	v_mul_f32_e32 v6, 0x37800000, v5
	v_cndmask_b32_e32 v5, v5, v6, vcc
	v_cmp_class_f32_e32 vcc, v4, v202
	s_nop 1
	v_cndmask_b32_e32 v4, v5, v4, vcc
	v_div_scale_f32 v5, s[4:5], v4, v4, 1.0
	v_rcp_f32_e32 v6, v5
	s_lshl_b64 s[4:5], s[44:45], 11
	s_add_i32 s44, s44, 4
	s_cmp_eq_u32 s6, 0
	v_fma_f32 v7, -v5, v6, 1.0
	v_fmac_f32_e32 v6, v7, v6
	v_div_scale_f32 v7, vcc, 1.0, v4, 1.0
	v_mul_f32_e32 v8, v7, v6
	v_fma_f32 v9, -v5, v8, v7
	v_fmac_f32_e32 v8, v9, v6
	v_fma_f32 v5, -v5, v8, v7
	v_div_fmas_f32 v5, v5, v6, v8
	v_div_fixup_f32 v4, v5, v4, 1.0
	v_mul_f32_e32 v2, v2, v4
	v_mul_f32_e32 v4, 0xbfb8aa3b, v3
	v_exp_f32_e32 v4, v4
	s_nop 0
	v_add_f32_e32 v4, 1.0, v4
	v_rcp_f32_e32 v99, v4
	s_nop 0
	v_pk_mul_f32 v[2:3], v[98:99], v[2:3]
	s_nop 0
	v_mul_f32_e32 v2, v2, v3
	v_cvt_pk_bf16_f32 v4, v2, s0
	v_lshl_add_u64 v[2:3], v[112:113], 0, s[4:5]
	global_store_short v[2:3], v4, off
	s_cbranch_scc0 .LBB0_314
	v_readlane_b32 s2, v251, 24
	s_add_i32 s84, s84, s2
	v_readlane_b32 s2, v252, 13
	s_add_i32 s85, s85, s2
	v_readlane_b32 s66, v253, 19
	v_readlane_b32 s46, v253, 24
	v_readlane_b32 s52, v253, 26
	s_cmpk_gt_i32 s84, 0x40f
	s_mov_b32 s93, 0xff61b1e6
	s_mov_b32 s94, 0xc2ce8ed0
	s_mov_b32 s95, 0x42b17218
	s_mov_b32 s36, 0x3fb8aa3b
	v_readlane_b32 s67, v253, 20
	v_readlane_b32 s47, v253, 25
	v_readlane_b32 s53, v253, 27
	s_barrier
	s_cbranch_scc0 .LBB0_313
